# retention and sample code of P7 (workgroups 128-255) 8-byte aligned: VOP1/VOP2/VOPC re-encoded as VOP3, s_nop partners for single 4-byte instructions, aligned labels
# baseline (speedup 1.0000x reference)
; #define LAS __attribute__((address_space(3)))
; template <bool WITH_K>
; __device__ __forceinline__ void ret_load_qk(PR P, LAS bf16_t* QP, LAS bf16_t* KB, unsigned (&kth)[4][4], const int tidv, const int row0, const int n, const int h, const float kd0, const float g32) {
;     const bf16_t* PS = (const bf16_t*)(P.ws + WS_BIG); const float* rc = (const float*)(P.ws + WS_ROPE); const float* rs = rc + 2052 * 64;
;     float kd = kd0;
; #pragma unroll
;     for (int it = 0; it < 4; ++it) { const int idx = it * 512 + tidv, i = idx >> 4, f = (idx & 15) * 4;
;         const bf16_t* src = PS + (size_t)(row0 + i) * NCOLS + 1792 + h * 128;
;         const u32x2 q1 = *(const u32x2*)(src + f), q2 = *(const u32x2*)(src + 64 + f);
;         u32x2 k1 = (u32x2){0u, 0u}, k2 = k1; if (WITH_K) { k1 = *(const u32x2*)(src + 512 + f); k2 = *(const u32x2*)(src + 576 + f); }
;         const float4 cs = *(const float4*)(rc + (size_t)(n * 128 + i) * 64 + f), sn = *(const float4*)(rs + (size_t)(n * 128 + i) * 64 + f);
;         const float c4[4] = {cs.x, cs.y, cs.z, cs.w}, s4[4] = {sn.x, sn.y, sn.z, sn.w};
;         const float qa[4] = {lo_bf(q1.x), hi_bf(q1.x), lo_bf(q1.y), hi_bf(q1.y)}, qb[4] = {lo_bf(q2.x), hi_bf(q2.x), lo_bf(q2.y), hi_bf(q2.y)};
;         float qo1[4], qo2[4];
; #pragma unroll
;         for (int x = 0; x < 4; ++x) { qo1[x] = qa[x] * c4[x] - qb[x] * s4[x]; qo2[x] = qa[x] * s4[x] + qb[x] * c4[x]; }
;         u32x2 w; w.x = pg8::cvt_pk_bf16(qo1[0], qo1[1]); w.y = pg8::cvt_pk_bf16(qo1[2], qo1[3]); *(LAS u32x2*)(QP + i * RS + f) = w;
;         w.x = pg8::cvt_pk_bf16(qo2[0], qo2[1]); w.y = pg8::cvt_pk_bf16(qo2[2], qo2[3]); *(LAS u32x2*)(QP + i * RS + 64 + f) = w;
;         if (WITH_K) {
;             const float ka[4] = {lo_bf(k1.x), hi_bf(k1.x), lo_bf(k1.y), hi_bf(k1.y)}, kb[4] = {lo_bf(k2.x), hi_bf(k2.x), lo_bf(k2.y), hi_bf(k2.y)};
;             float ko1[4], ko2[4];
; #pragma unroll
;             for (int x = 0; x < 4; ++x) { ko1[x] = (ka[x] * c4[x] - kb[x] * s4[x]) * 0.08838834764831845f; ko2[x] = (ka[x] * s4[x] + kb[x] * c4[x]) * 0.08838834764831845f; }
;             w.x = pg8::cvt_pk_bf16(ko1[0], ko1[1]); w.y = pg8::cvt_pk_bf16(ko1[2], ko1[3]); *(LAS u32x2*)(KB + i * RS + f) = w;
;             w.x = pg8::cvt_pk_bf16(ko2[0], ko2[1]); w.y = pg8::cvt_pk_bf16(ko2[2], ko2[3]); *(LAS u32x2*)(KB + i * RS + 64 + f) = w;
.LBB0_617:
	.p2alignl 3, 3212836864
	s_mov_b64 s[38:39], s[0:1]
	s_nop 0
	s_load_dwordx2 s[10:11], s[38:39], 0xd8
	s_and_b32 s4, s2, 15
	s_lshl_b32 s6, s4, 7
	s_mov_b32 s13, 0
	s_nop 0
	s_mov_b32 s21, 0xc2fc0000
	s_waitcnt lgkmcnt(0)
	s_nop 0
	s_add_u32 s14, s10, 0x4000
	s_addc_u32 s15, s11, 0
	s_nop 0
	s_add_u32 s16, s10, 0x84400
	s_addc_u32 s17, s11, 0
	s_lshl_b32 s7, s4, 14
	s_add_u32 s4, s10, 0x1bc4c00
	s_addc_u32 s5, s11, 0
	s_nop 0
	s_add_i32 s26, 0, 0x11000
	v_mov_b32_e32 v56, 0x42800000
	s_mov_b32 s22, 0x800000
	v_mov_b32_e32 v57, 0x42000000
	v_mov_b32_e64 v29, 0
	s_movk_i32 s23, 0x1e00
	s_nop 0
	v_mov_b64_e64 v[30:31], s[10:11]
	s_mov_b64 s[18:19], 0x3d45600
	s_mov_b32 s24, 0x3d45000
	s_movk_i32 s25, 0x110
	s_nop 0
	s_mov_b32 s20, 0x3db504f3
	v_mov_b32_e64 v58, s26
	v_not_b32_e64 v59, 63
	s_movk_i32 s27, 0x7fff
	s_nop 0
	s_mov_b32 s28, 0xcb64800
	s_lshl_b32 s7, s7, 1
	.p2alignl 3, 3212836864
.LBB0_618:
	s_add_i32 s8, s2, s55
	s_ashr_i32 s30, s8, 4
	s_and_b32 s12, s30, 3
	s_nop 0
	v_cvt_f32_ubyte0_e64 v0, s12
	v_sub_f32_e32 v0, 0xc0a00000, v0
	v_cmp_gt_f32_e64 vcc, s21, v0
	s_and_b64 s[8:9], vcc, exec
	s_nop 0
	s_cselect_b32 s8, 0xffffffc0, 0
	v_cndmask_b32_e64 v1, 0, v56, vcc
	v_add_f32_e64 v0, v0, v1
	v_exp_f32_e64 v0, v0
	v_mbcnt_lo_u32_b32 v11, -1, 0
	v_mbcnt_hi_u32_b32 v11, -1, v11
	s_nop 0
	s_nop 0
	v_add_u32_e64 v10, s33, v11
	v_ldexp_f32 v0, v0, s8
	v_sub_f32_e64 v52, 1.0, v0
	v_cmp_gt_f32_e64 vcc, s22, v52
	s_and_b64 s[8:9], vcc, exec
	s_cselect_b32 s31, 32, 0
	s_lshl_b32 s8, s30, 9
	s_nop 0
	s_and_b32 s8, s8, 0xfffff800
	v_ashrrev_i32_e64 v61, 4, v10
	s_or_b32 s29, s8, s6
	s_nop 0
	v_lshlrev_b32_e64 v0, 2, v11
	v_and_b32_e64 v60, 60, v0
	v_add_u32_e64 v0, s29, v61
	v_lshlrev_b32_e64 v28, 2, v60
	v_mad_i64_i32 v[0:1], s[8:9], v0, s23, v[30:31]
	s_lshl_b32 s12, s12, 8
	s_nop 0
	v_lshl_add_u64 v[6:7], s[14:15], 0, v[28:29]
	v_lshl_add_u64 v[4:5], s[16:17], 0, v[28:29]
	v_lshlrev_b32_e64 v28, 1, v60
	v_lshl_add_u64 v[0:1], v[0:1], 0, s[12:13]
	v_lshl_add_u64 v[2:3], v[0:1], 0, v[28:29]
	v_cndmask_b32_e64 v53, 0, v57, vcc
	v_add_co_u32_e64 v8, vcc, s24, v2
	s_nop 1
	s_nop 0
	v_addc_co_u32_e64 v9, vcc, 0, v3, vcc
	v_lshl_add_u64 v[2:3], v[2:3], 0, s[18:19]
	global_load_dwordx2 v[8:9], v[8:9], off offset:1536
	s_nop 0
	s_nop 0
	global_load_dwordx2 v[20:21], v[2:3], off offset:128
	global_load_dwordx2 v[24:25], v[2:3], off offset:1024
	global_load_dwordx2 v[26:27], v[2:3], off offset:1152
	v_add_u32_e64 v2, s6, v61
	v_ashrrev_i32_e64 v3, 31, v2
	v_lshlrev_b64 v[2:3], 8, v[2:3]
	v_lshl_add_u64 v[12:13], v[4:5], 0, v[2:3]
	v_lshl_add_u64 v[2:3], v[6:7], 0, v[2:3]
	global_load_dwordx4 v[12:15], v[12:13], off
	s_nop 0
	s_nop 0
	global_load_dwordx4 v[16:19], v[2:3], off
	v_add_u32_e32 v2, 0x200, v10
	v_ashrrev_i32_e64 v63, 4, v2
	v_add_u32_e64 v2, s6, v63
	v_ashrrev_i32_e64 v3, 31, v2
	v_lshlrev_b64 v[22:23], 8, v[2:3]
	v_add_u32_e64 v2, s29, v63
	v_mad_i64_i32 v[2:3], s[8:9], v2, s23, v[30:31]
	v_lshl_add_u64 v[2:3], v[2:3], 0, s[12:13]
	v_lshl_add_u64 v[34:35], v[2:3], 0, v[28:29]
	v_add_co_u32_e64 v36, vcc, s24, v34
	v_lshl_add_u64 v[32:33], v[6:7], 0, v[22:23]
	s_nop 0
	s_nop 0
	v_addc_co_u32_e64 v37, vcc, 0, v35, vcc
	v_lshl_add_u64 v[34:35], v[34:35], 0, s[18:19]
	global_load_dwordx2 v[44:45], v[36:37], off offset:1536
	global_load_dwordx2 v[46:47], v[34:35], off offset:128
	v_lshl_add_u64 v[22:23], v[4:5], 0, v[22:23]
	global_load_dwordx4 v[36:39], v[22:23], off
	global_load_dwordx4 v[40:43], v[32:33], off
	global_load_dwordx2 v[48:49], v[34:35], off offset:1024
	global_load_dwordx2 v[50:51], v[34:35], off offset:1152
	v_ldexp_f32 v22, v52, s31
	v_log_f32_e64 v22, v22
	v_mul_lo_u32 v23, v61, s25
	v_add3_u32 v72, 0, v23, v28
	v_sub_f32_e64 v62, v22, v53
	s_waitcnt vmcnt(0)
	s_nop 0
	v_lshlrev_b32_e64 v32, 16, v20
	v_lshlrev_b32_e64 v22, 16, v8
	v_and_b32_e32 v23, 0xffff0000, v8
	v_and_b32_e32 v33, 0xffff0000, v20
	v_lshlrev_b32_e64 v8, 16, v9
	v_and_b32_e32 v9, 0xffff0000, v9
	v_lshlrev_b32_e64 v20, 16, v21
	v_and_b32_e32 v21, 0xffff0000, v21
	v_pk_mul_f32 v[54:55], v[12:13], v[32:33]
	v_pk_mul_f32 v[64:65], v[12:13], v[22:23]
	v_pk_mul_f32 v[66:67], v[14:15], v[20:21]
	v_pk_mul_f32 v[68:69], v[14:15], v[8:9]
	v_lshlrev_b32_e64 v34, 16, v24
	v_and_b32_e32 v35, 0xffff0000, v24
	v_lshlrev_b32_e64 v52, 16, v26
	v_and_b32_e32 v53, 0xffff0000, v26
	v_pk_fma_f32 v[22:23], v[16:17], v[22:23], v[54:55] neg_lo:[0,0,1] neg_hi:[0,0,1]
	v_pk_fma_f32 v[32:33], v[16:17], v[32:33], v[64:65]
	v_pk_fma_f32 v[8:9], v[18:19], v[8:9], v[66:67] neg_lo:[0,0,1] neg_hi:[0,0,1]
	v_pk_fma_f32 v[20:21], v[18:19], v[20:21], v[68:69]
	v_pk_mul_f32 v[70:71], v[12:13], v[34:35]
	v_pk_mul_f32 v[12:13], v[12:13], v[52:53]
	v_cvt_pk_bf16_f32 v22, v22, v23
	v_cvt_pk_bf16_f32 v23, v8, v9
	v_cvt_pk_bf16_f32 v8, v32, v33
	v_cvt_pk_bf16_f32 v9, v20, v21
	ds_write2_b64 v72, v[22:23], v[8:9] offset1:16
	v_pk_fma_f32 v[8:9], v[16:17], v[34:35], v[12:13] neg_lo:[0,0,1] neg_hi:[0,0,1]
	v_pk_fma_f32 v[52:53], v[16:17], v[52:53], v[70:71]
	v_pk_mul_f32 v[22:23], v[8:9], s[20:21] op_sel_hi:[1,0]
	v_lshlrev_b32_e64 v8, 16, v25
	v_and_b32_e32 v9, 0xffff0000, v25
	v_lshlrev_b32_e64 v12, 16, v27
	v_and_b32_e32 v13, 0xffff0000, v27
	v_pk_mul_f32 v[16:17], v[14:15], v[8:9]
	v_pk_mul_f32 v[20:21], v[52:53], s[20:21] op_sel_hi:[1,0]
	v_pk_fma_f32 v[16:17], v[18:19], v[12:13], v[16:17]
	v_pk_mul_f32 v[12:13], v[14:15], v[12:13]
	v_pk_mul_f32 v[24:25], v[16:17], s[20:21] op_sel_hi:[1,0]
	v_pk_fma_f32 v[8:9], v[18:19], v[8:9], v[12:13] neg_lo:[0,0,1] neg_hi:[0,0,1]
	v_cvt_pk_bf16_f32 v12, v20, v21
	v_pk_mul_f32 v[26:27], v[8:9], s[20:21] op_sel_hi:[1,0]
	v_cvt_pk_bf16_f32 v8, v22, v23
; template <bool WITH_K>
; __device__ __forceinline__ void ret_load_qk(PR P, LAS bf16_t* QP, LAS bf16_t* KB, unsigned (&kth)[4][4], const int tidv, const int row0, const int n, const int h, const float kd0, const float g32) {
;     ...
;     for (int it = 0; it < 4; ++it) { const int idx = it * 512 + tidv, i = idx >> 4, f = (idx & 15) * 4;
;         const bf16_t* src = PS + (size_t)(row0 + i) * NCOLS + 1792 + h * 128;
;         const u32x2 q1 = *(const u32x2*)(src + f), q2 = *(const u32x2*)(src + 64 + f);
;         u32x2 k1 = (u32x2){0u, 0u}, k2 = k1; if (WITH_K) { k1 = *(const u32x2*)(src + 512 + f); k2 = *(const u32x2*)(src + 576 + f); }
;         const float4 cs = *(const float4*)(rc + (size_t)(n * 128 + i) * 64 + f), sn = *(const float4*)(rs + (size_t)(n * 128 + i) * 64 + f);
;         const float c4[4] = {cs.x, cs.y, cs.z, cs.w}, s4[4] = {sn.x, sn.y, sn.z, sn.w};
;         const float qa[4] = {lo_bf(q1.x), hi_bf(q1.x), lo_bf(q1.y), hi_bf(q1.y)}, qb[4] = {lo_bf(q2.x), hi_bf(q2.x), lo_bf(q2.y), hi_bf(q2.y)};
;         float qo1[4], qo2[4];
; #pragma unroll
;         for (int x = 0; x < 4; ++x) { qo1[x] = qa[x] * c4[x] - qb[x] * s4[x]; qo2[x] = qa[x] * s4[x] + qb[x] * c4[x]; }
;         u32x2 w; w.x = pg8::cvt_pk_bf16(qo1[0], qo1[1]); w.y = pg8::cvt_pk_bf16(qo1[2], qo1[3]); *(LAS u32x2*)(QP + i * RS + f) = w;
;         w.x = pg8::cvt_pk_bf16(qo2[0], qo2[1]); w.y = pg8::cvt_pk_bf16(qo2[2], qo2[3]); *(LAS u32x2*)(QP + i * RS + 64 + f) = w;
;         if (WITH_K) {
;             const float ka[4] = {lo_bf(k1.x), hi_bf(k1.x), lo_bf(k1.y), hi_bf(k1.y)}, kb[4] = {lo_bf(k2.x), hi_bf(k2.x), lo_bf(k2.y), hi_bf(k2.y)};
;             float ko1[4], ko2[4];
; #pragma unroll
;             for (int x = 0; x < 4; ++x) { ko1[x] = (ka[x] * c4[x] - kb[x] * s4[x]) * 0.08838834764831845f; ko2[x] = (ka[x] * s4[x] + kb[x] * c4[x]) * 0.08838834764831845f; }
;             w.x = pg8::cvt_pk_bf16(ko1[0], ko1[1]); w.y = pg8::cvt_pk_bf16(ko1[2], ko1[3]); *(LAS u32x2*)(KB + i * RS + f) = w;
;             w.x = pg8::cvt_pk_bf16(ko2[0], ko2[1]); w.y = pg8::cvt_pk_bf16(ko2[2], ko2[3]); *(LAS u32x2*)(KB + i * RS + 64 + f) = w;
;             kth[it][0] = pg8::cvt_pk_bf16(ko1[0] * kd, ko1[1] * kd); kth[it][1] = pg8::cvt_pk_bf16(ko1[2] * kd, ko1[3] * kd);
;             kth[it][2] = pg8::cvt_pk_bf16(ko2[0] * kd, ko2[1] * kd); kth[it][3] = pg8::cvt_pk_bf16(ko2[2] * kd, ko2[3] * kd); kd *= g32; }
	v_cvt_pk_bf16_f32 v9, v26, v27
	v_cvt_pk_bf16_f32 v13, v24, v25
	v_add_u32_e32 v14, 0x8800, v72
	ds_write2_b64 v14, v[8:9], v[12:13] offset1:16
	v_lshlrev_b32_e64 v12, 16, v46
	v_and_b32_e32 v13, 0xffff0000, v46
	v_lshlrev_b32_e64 v8, 16, v44
	v_and_b32_e32 v9, 0xffff0000, v44
	v_pk_mul_f32 v[14:15], v[36:37], v[12:13]
	v_lshlrev_b32_e64 v16, 16, v47
	v_pk_fma_f32 v[14:15], v[40:41], v[8:9], v[14:15] neg_lo:[0,0,1] neg_hi:[0,0,1]
	v_pk_mul_f32 v[8:9], v[36:37], v[8:9]
	v_and_b32_e32 v17, 0xffff0000, v47
	v_pk_fma_f32 v[8:9], v[40:41], v[12:13], v[8:9]
	v_lshlrev_b32_e64 v12, 16, v45
	v_and_b32_e32 v13, 0xffff0000, v45
	v_pk_mul_f32 v[18:19], v[38:39], v[16:17]
	v_cvt_pk_bf16_f32 v14, v14, v15
	v_pk_fma_f32 v[18:19], v[42:43], v[12:13], v[18:19] neg_lo:[0,0,1] neg_hi:[0,0,1]
	v_pk_mul_f32 v[12:13], v[38:39], v[12:13]
	v_cvt_pk_bf16_f32 v15, v18, v19
	v_pk_fma_f32 v[12:13], v[42:43], v[16:17], v[12:13]
	v_mul_lo_u32 v16, v63, s25
	v_add3_u32 v16, 0, v16, v28
	v_cvt_pk_bf16_f32 v8, v8, v9
	v_cvt_pk_bf16_f32 v9, v12, v13
	ds_write2_b64 v16, v[14:15], v[8:9] offset1:16
	v_lshlrev_b32_e64 v8, 16, v48
	v_and_b32_e32 v9, 0xffff0000, v48
	v_lshlrev_b32_e64 v12, 16, v50
	v_and_b32_e32 v13, 0xffff0000, v50
	v_pk_mul_f32 v[14:15], v[36:37], v[8:9]
	s_nop 0
	s_nop 0
	v_pk_fma_f32 v[14:15], v[40:41], v[12:13], v[14:15]
	v_pk_mul_f32 v[12:13], v[36:37], v[12:13]
	v_pk_mul_f32 v[32:33], v[14:15], s[20:21] op_sel_hi:[1,0]
	v_pk_fma_f32 v[8:9], v[40:41], v[8:9], v[12:13] neg_lo:[0,0,1] neg_hi:[0,0,1]
	v_lshlrev_b32_e64 v12, 16, v51
	v_pk_mul_f32 v[34:35], v[8:9], s[20:21] op_sel_hi:[1,0]
	v_lshlrev_b32_e64 v8, 16, v49
	v_and_b32_e32 v9, 0xffff0000, v49
	v_and_b32_e32 v13, 0xffff0000, v51
	v_pk_mul_f32 v[14:15], v[38:39], v[8:9]
	s_nop 0
	s_nop 0
	v_pk_fma_f32 v[14:15], v[42:43], v[12:13], v[14:15]
	v_pk_mul_f32 v[12:13], v[38:39], v[12:13]
	v_pk_mul_f32 v[36:37], v[14:15], s[20:21] op_sel_hi:[1,0]
	v_pk_fma_f32 v[8:9], v[42:43], v[8:9], v[12:13] neg_lo:[0,0,1] neg_hi:[0,0,1]
	v_cvt_pk_bf16_f32 v12, v32, v33
	v_pk_mul_f32 v[38:39], v[8:9], s[20:21] op_sel_hi:[1,0]
	v_cvt_pk_bf16_f32 v8, v34, v35
	v_cvt_pk_bf16_f32 v9, v38, v39
	v_cvt_pk_bf16_f32 v13, v36, v37
	v_add_u32_e32 v14, 0x8800, v16
	ds_write2_b64 v14, v[8:9], v[12:13] offset1:16
	v_add_u32_e32 v8, 0x400, v10
	v_ashrrev_i32_e64 v90, 4, v8
	v_add_u32_e64 v8, s29, v90
	v_mad_i64_i32 v[8:9], s[8:9], v8, s23, v[30:31]
	v_lshl_add_u64 v[8:9], v[8:9], 0, s[12:13]
	v_lshl_add_u64 v[12:13], v[8:9], 0, v[28:29]
	v_add_co_u32_e64 v14, vcc, s24, v12
	v_add_u32_e32 v48, 0x600, v10
	s_nop 0
	s_nop 0
	v_addc_co_u32_e64 v15, vcc, 0, v13, vcc
	v_lshl_add_u64 v[12:13], v[12:13], 0, s[18:19]
	global_load_dwordx2 v[40:41], v[14:15], off offset:1536
	global_load_dwordx2 v[42:43], v[12:13], off offset:128
	global_load_dwordx2 v[44:45], v[12:13], off offset:1024
	global_load_dwordx2 v[46:47], v[12:13], off offset:1152
	v_add_u32_e64 v12, s6, v90
	v_ashrrev_i32_e64 v13, 31, v12
	v_ashrrev_i32_e64 v91, 4, v48
	v_lshlrev_b64 v[16:17], 8, v[12:13]
	v_add_u32_e64 v49, s29, v91
	v_lshl_add_u64 v[12:13], v[4:5], 0, v[16:17]
	v_add_u32_e64 v48, s6, v91
	v_mad_i64_i32 v[50:51], s[8:9], v49, s23, v[30:31]
	global_load_dwordx4 v[12:15], v[12:13], off
	v_lshl_add_u64 v[16:17], v[6:7], 0, v[16:17]
	v_ashrrev_i32_e64 v49, 31, v48
	v_lshl_add_u64 v[64:65], v[50:51], 0, s[12:13]
	global_load_dwordx4 v[16:19], v[16:17], off
	v_lshlrev_b64 v[48:49], 8, v[48:49]
	v_lshl_add_u64 v[50:51], v[64:65], 0, v[28:29]
	v_lshl_add_u64 v[52:53], v[6:7], 0, v[48:49]
	v_add_co_u32_e64 v6, vcc, s24, v50
	v_lshl_add_u64 v[4:5], v[4:5], 0, v[48:49]
	s_nop 0
	s_nop 0
	v_addc_co_u32_e64 v7, vcc, 0, v51, vcc
	v_lshl_add_u64 v[50:51], v[50:51], 0, s[18:19]
	global_load_dwordx2 v[68:69], v[50:51], off offset:128
	global_load_dwordx2 v[66:67], v[6:7], off offset:1536
	s_nop 0
	s_nop 0
	global_load_dwordx4 v[4:7], v[4:5], off
	s_nop 0
	s_nop 0
	global_load_dwordx4 v[52:55], v[52:53], off
	s_nop 0
	s_nop 0
	global_load_dwordx2 v[70:71], v[50:51], off offset:1024
	global_load_dwordx2 v[72:73], v[50:51], off offset:1152
	v_lshlrev_b32_e64 v216, 3, v11
	v_and_b32_e32 v216, 0x78, v216
	v_lshlrev_b32_e64 v216, 1, v216
	v_add_u32_e64 v216, s24, v216
	v_mov_b32_e64 v217, 0
	v_lshl_add_u64 v[218:219], v[0:1], 0, v[216:217]
	v_lshl_add_u64 v[220:221], v[2:3], 0, v[216:217]
	v_lshl_add_u64 v[222:223], v[8:9], 0, v[216:217]
	v_lshl_add_u64 v[224:225], v[64:65], 0, v[216:217]
	global_load_dwordx4 v[200:203], v[218:219], off offset:3584
	global_load_dwordx4 v[204:207], v[220:221], off offset:3584
	global_load_dwordx4 v[208:211], v[222:223], off offset:3584
	global_load_dwordx4 v[212:215], v[224:225], off offset:3584
	v_mul_lo_u32 v48, v90, s25
	v_add3_u32 v92, 0, v48, v28
	s_waitcnt vmcnt(14)
	s_nop 0
	v_lshlrev_b32_e64 v50, 16, v42
	v_lshlrev_b32_e64 v48, 16, v40
	v_and_b32_e32 v49, 0xffff0000, v40
	v_and_b32_e32 v51, 0xffff0000, v42
	v_lshlrev_b32_e64 v40, 16, v41
	v_and_b32_e32 v41, 0xffff0000, v41
	v_lshlrev_b32_e64 v42, 16, v43
	v_and_b32_e32 v43, 0xffff0000, v43
	s_waitcnt vmcnt(13)
	s_nop 0
	v_lshlrev_b32_e64 v74, 16, v44
	v_and_b32_e32 v75, 0xffff0000, v44
	s_waitcnt vmcnt(12)
	s_nop 0
	v_lshlrev_b32_e64 v76, 16, v46
	v_and_b32_e32 v77, 0xffff0000, v46
	v_lshlrev_b32_e64 v44, 16, v45
	v_and_b32_e32 v45, 0xffff0000, v45
	v_lshlrev_b32_e64 v46, 16, v47
	v_and_b32_e32 v47, 0xffff0000, v47
	s_waitcnt vmcnt(11)
	s_nop 0
	v_pk_mul_f32 v[78:79], v[12:13], v[50:51]
	v_pk_mul_f32 v[80:81], v[12:13], v[48:49]
	v_pk_mul_f32 v[82:83], v[14:15], v[42:43]
	v_pk_mul_f32 v[84:85], v[14:15], v[40:41]
	v_pk_mul_f32 v[86:87], v[12:13], v[74:75]
	v_pk_mul_f32 v[12:13], v[12:13], v[76:77]
	v_pk_mul_f32 v[88:89], v[14:15], v[44:45]
	v_pk_mul_f32 v[14:15], v[14:15], v[46:47]
	s_waitcnt vmcnt(10)
; template <bool WITH_K>
; __device__ __forceinline__ void ret_load_qk(PR P, LAS bf16_t* QP, LAS bf16_t* KB, unsigned (&kth)[4][4], const int tidv, const int row0, const int n, const int h, const float kd0, const float g32) {
;     ...
;     for (int it = 0; it < 4; ++it) { const int idx = it * 512 + tidv, i = idx >> 4, f = (idx & 15) * 4;
;         const bf16_t* src = PS + (size_t)(row0 + i) * NCOLS + 1792 + h * 128;
;         const u32x2 q1 = *(const u32x2*)(src + f), q2 = *(const u32x2*)(src + 64 + f);
;         u32x2 k1 = (u32x2){0u, 0u}, k2 = k1; if (WITH_K) { k1 = *(const u32x2*)(src + 512 + f); k2 = *(const u32x2*)(src + 576 + f); }
;         const float4 cs = *(const float4*)(rc + (size_t)(n * 128 + i) * 64 + f), sn = *(const float4*)(rs + (size_t)(n * 128 + i) * 64 + f);
;         const float c4[4] = {cs.x, cs.y, cs.z, cs.w}, s4[4] = {sn.x, sn.y, sn.z, sn.w};
;         const float qa[4] = {lo_bf(q1.x), hi_bf(q1.x), lo_bf(q1.y), hi_bf(q1.y)}, qb[4] = {lo_bf(q2.x), hi_bf(q2.x), lo_bf(q2.y), hi_bf(q2.y)};
;         float qo1[4], qo2[4];
; #pragma unroll
;         for (int x = 0; x < 4; ++x) { qo1[x] = qa[x] * c4[x] - qb[x] * s4[x]; qo2[x] = qa[x] * s4[x] + qb[x] * c4[x]; }
;         u32x2 w; w.x = pg8::cvt_pk_bf16(qo1[0], qo1[1]); w.y = pg8::cvt_pk_bf16(qo1[2], qo1[3]); *(LAS u32x2*)(QP + i * RS + f) = w;
;         w.x = pg8::cvt_pk_bf16(qo2[0], qo2[1]); w.y = pg8::cvt_pk_bf16(qo2[2], qo2[3]); *(LAS u32x2*)(QP + i * RS + 64 + f) = w;
;         if (WITH_K) {
;             const float ka[4] = {lo_bf(k1.x), hi_bf(k1.x), lo_bf(k1.y), hi_bf(k1.y)}, kb[4] = {lo_bf(k2.x), hi_bf(k2.x), lo_bf(k2.y), hi_bf(k2.y)};
;             float ko1[4], ko2[4];
; #pragma unroll
;             for (int x = 0; x < 4; ++x) { ko1[x] = (ka[x] * c4[x] - kb[x] * s4[x]) * 0.08838834764831845f; ko2[x] = (ka[x] * s4[x] + kb[x] * c4[x]) * 0.08838834764831845f; }
;             w.x = pg8::cvt_pk_bf16(ko1[0], ko1[1]); w.y = pg8::cvt_pk_bf16(ko1[2], ko1[3]); *(LAS u32x2*)(KB + i * RS + f) = w;
;             w.x = pg8::cvt_pk_bf16(ko2[0], ko2[1]); w.y = pg8::cvt_pk_bf16(ko2[2], ko2[3]); *(LAS u32x2*)(KB + i * RS + 64 + f) = w;
;             kth[it][0] = pg8::cvt_pk_bf16(ko1[0] * kd, ko1[1] * kd); kth[it][1] = pg8::cvt_pk_bf16(ko1[2] * kd, ko1[3] * kd);
;             kth[it][2] = pg8::cvt_pk_bf16(ko2[0] * kd, ko2[1] * kd); kth[it][3] = pg8::cvt_pk_bf16(ko2[2] * kd, ko2[3] * kd); kd *= g32; }
	s_nop 0
	v_pk_fma_f32 v[48:49], v[16:17], v[48:49], v[78:79] neg_lo:[0,0,1] neg_hi:[0,0,1]
	v_pk_fma_f32 v[50:51], v[16:17], v[50:51], v[80:81]
	v_pk_fma_f32 v[40:41], v[18:19], v[40:41], v[82:83] neg_lo:[0,0,1] neg_hi:[0,0,1]
	v_pk_fma_f32 v[42:43], v[18:19], v[42:43], v[84:85]
	v_pk_fma_f32 v[76:77], v[16:17], v[76:77], v[86:87]
	v_pk_fma_f32 v[12:13], v[16:17], v[74:75], v[12:13] neg_lo:[0,0,1] neg_hi:[0,0,1]
	v_pk_fma_f32 v[16:17], v[18:19], v[46:47], v[88:89]
	v_pk_fma_f32 v[14:15], v[18:19], v[44:45], v[14:15] neg_lo:[0,0,1] neg_hi:[0,0,1]
	v_cvt_pk_bf16_f32 v18, v48, v49
	v_cvt_pk_bf16_f32 v19, v40, v41
	v_cvt_pk_bf16_f32 v49, v42, v43
	v_pk_mul_f32 v[40:41], v[76:77], s[20:21] op_sel_hi:[1,0]
	v_pk_mul_f32 v[44:45], v[12:13], s[20:21] op_sel_hi:[1,0]
	v_pk_mul_f32 v[42:43], v[16:17], s[20:21] op_sel_hi:[1,0]
	v_pk_mul_f32 v[46:47], v[14:15], s[20:21] op_sel_hi:[1,0]
	v_cvt_pk_bf16_f32 v12, v44, v45
	v_cvt_pk_bf16_f32 v13, v46, v47
	v_cvt_pk_bf16_f32 v14, v40, v41
	v_cvt_pk_bf16_f32 v15, v42, v43
	v_add_u32_e32 v16, 0x8800, v92
	ds_write2_b64 v16, v[12:13], v[14:15] offset1:16
	s_waitcnt vmcnt(9)
	s_nop 0
	v_lshlrev_b32_e64 v14, 16, v68
	v_and_b32_e32 v15, 0xffff0000, v68
	v_cvt_pk_bf16_f32 v48, v50, v51
	s_waitcnt vmcnt(8)
	s_nop 0
	v_lshlrev_b32_e64 v12, 16, v66
	v_and_b32_e32 v13, 0xffff0000, v66
	s_waitcnt vmcnt(7)
	s_nop 0
	v_pk_mul_f32 v[16:17], v[4:5], v[14:15]
	ds_write2_b64 v92, v[18:19], v[48:49] offset1:16
	s_waitcnt vmcnt(6)
	s_nop 0
	v_pk_fma_f32 v[16:17], v[52:53], v[12:13], v[16:17] neg_lo:[0,0,1] neg_hi:[0,0,1]
	v_pk_mul_f32 v[12:13], v[4:5], v[12:13]
	v_lshlrev_b32_e64 v18, 16, v69
	v_and_b32_e32 v19, 0xffff0000, v69
	v_pk_fma_f32 v[12:13], v[52:53], v[14:15], v[12:13]
	v_lshlrev_b32_e64 v14, 16, v67
	v_and_b32_e32 v15, 0xffff0000, v67
	v_pk_mul_f32 v[48:49], v[6:7], v[18:19]
	v_cvt_pk_bf16_f32 v16, v16, v17
	v_pk_fma_f32 v[48:49], v[54:55], v[14:15], v[48:49] neg_lo:[0,0,1] neg_hi:[0,0,1]
	v_pk_mul_f32 v[14:15], v[6:7], v[14:15]
	v_cvt_pk_bf16_f32 v17, v48, v49
	v_pk_fma_f32 v[14:15], v[54:55], v[18:19], v[14:15]
	v_mul_lo_u32 v18, v91, s25
	v_add3_u32 v18, 0, v18, v28
	v_cvt_pk_bf16_f32 v12, v12, v13
	v_cvt_pk_bf16_f32 v13, v14, v15
	ds_write2_b64 v18, v[16:17], v[12:13] offset1:16
	s_waitcnt vmcnt(5)
	s_nop 0
	v_lshlrev_b32_e64 v12, 16, v70
	v_and_b32_e32 v13, 0xffff0000, v70
	s_waitcnt vmcnt(4)
	s_nop 0
	v_lshlrev_b32_e64 v14, 16, v72
	v_and_b32_e32 v15, 0xffff0000, v72
	v_pk_mul_f32 v[16:17], v[4:5], v[12:13]
	v_pk_mul_f32 v[4:5], v[4:5], v[14:15]
	v_pk_fma_f32 v[16:17], v[52:53], v[14:15], v[16:17]
	v_pk_fma_f32 v[4:5], v[52:53], v[12:13], v[4:5] neg_lo:[0,0,1] neg_hi:[0,0,1]
	v_lshlrev_b32_e64 v12, 16, v73
	v_pk_mul_f32 v[50:51], v[4:5], s[20:21] op_sel_hi:[1,0]
	v_lshlrev_b32_e64 v4, 16, v71
	v_and_b32_e32 v5, 0xffff0000, v71
	v_and_b32_e32 v13, 0xffff0000, v73
	v_pk_mul_f32 v[14:15], v[6:7], v[4:5]
	v_pk_mul_f32 v[6:7], v[6:7], v[12:13]
	v_pk_fma_f32 v[14:15], v[54:55], v[12:13], v[14:15]
	v_pk_fma_f32 v[4:5], v[54:55], v[4:5], v[6:7] neg_lo:[0,0,1] neg_hi:[0,0,1]
	v_pk_mul_f32 v[48:49], v[16:17], s[20:21] op_sel_hi:[1,0]
	v_pk_mul_f32 v[52:53], v[14:15], s[20:21] op_sel_hi:[1,0]
	v_pk_mul_f32 v[54:55], v[4:5], s[20:21] op_sel_hi:[1,0]
	v_cvt_pk_bf16_f32 v4, v50, v51
	v_cvt_pk_bf16_f32 v5, v54, v55
	v_cvt_pk_bf16_f32 v6, v48, v49
	v_cvt_pk_bf16_f32 v7, v52, v53
	v_add_u32_e32 v12, 0x8800, v18
	ds_write2_b64 v12, v[4:5], v[6:7] offset1:16
	v_lshlrev_b32_e64 v4, 3, v11
	v_and_b32_e32 v66, 0x78, v4
	v_lshlrev_b32_e64 v28, 1, v66
	v_lshlrev_b32_e64 v79, 1, v61
	v_lshlrev_b32_e64 v78, 1, v63
	v_bfe_u32 v28, v11, 4, 2
	v_ashrrev_i32_e64 v9, 2, v10
	v_and_b32_e64 v8, 15, v11
	v_and_b32_e32 v69, 0xffffffe0, v9
	v_lshlrev_b32_e64 v75, 4, v28
	v_or_b32_e64 v11, v69, v8
	v_mad_u32_u24 v9, v66, s25, v58
	v_add_u32_e64 v73, 0, v75
	v_mul_lo_u32 v77, v11, s25
	v_lshlrev_b32_e64 v76, 1, v90
	v_lshlrev_b32_e64 v74, 1, v91
	v_add_u32_e64 v63, v9, v79
	v_add_u32_e64 v68, v73, v77
	v_add_u32_e64 v64, v9, v78
	v_add_u32_e64 v65, v9, v76
	v_add_u32_e64 v9, v9, v74
	s_waitcnt vmcnt(3)
	s_nop 0
	ds_write_b16 v63, v200
	ds_write_b16_d16_hi v63, v200 offset:272
	ds_write_b16 v63, v201 offset:544
	ds_write_b16_d16_hi v63, v201 offset:816
	ds_write_b16 v63, v202 offset:1088
	ds_write_b16_d16_hi v63, v202 offset:1360
	ds_write_b16 v63, v203 offset:1632
	ds_write_b16_d16_hi v63, v203 offset:1904
	s_waitcnt vmcnt(2)
	s_nop 0
	ds_write_b16 v64, v204
	ds_write_b16_d16_hi v64, v204 offset:272
	ds_write_b16 v64, v205 offset:544
	ds_write_b16_d16_hi v64, v205 offset:816
	ds_write_b16 v64, v206 offset:1088
	ds_write_b16_d16_hi v64, v206 offset:1360
	ds_write_b16 v64, v207 offset:1632
	ds_write_b16_d16_hi v64, v207 offset:1904
	s_waitcnt vmcnt(1)
	s_nop 0
	ds_write_b16 v65, v208
	ds_write_b16_d16_hi v65, v208 offset:272
	ds_write_b16 v65, v209 offset:544
	ds_write_b16_d16_hi v65, v209 offset:816
	ds_write_b16 v65, v210 offset:1088
	ds_write_b16_d16_hi v65, v210 offset:1360
	ds_write_b16 v65, v211 offset:1632
	ds_write_b16_d16_hi v65, v211 offset:1904
	s_waitcnt vmcnt(0)
	s_nop 0
	ds_write_b16 v9, v212
	ds_write_b16_d16_hi v9, v212 offset:272
	ds_write_b16 v9, v213 offset:544
	ds_write_b16_d16_hi v9, v213 offset:816
	ds_write_b16 v9, v214 offset:1088
	ds_write_b16_d16_hi v9, v214 offset:1360
	ds_write_b16 v9, v215 offset:1632
	ds_write_b16_d16_hi v9, v215 offset:1904
	s_waitcnt lgkmcnt(0)
	s_barrier
; #define LAS __attribute__((address_space(3)))
; __device__ __forceinline__ void ret_unit_a(PR P, LAS unsigned char* lds, const int bh, const int n, const int wv) {
;     ...
;     f32x4 accP[2][4];
; #pragma unroll
;     for (int mt = 0; mt < 2; ++mt)
; #pragma unroll
;         for (int nt = 0; nt < 4; ++nt) accP[mt][nt] = (f32x4){0.f, 0.f, 0.f, 0.f};
; #pragma unroll
;     for (int ks = 0; ks < 4; ++ks) { bf16x8 aq[2];
; #pragma unroll
;         for (int mt = 0; mt < 2; ++mt) aq[mt] = *(const LAS bf16x8*)(QP + (wr * 32 + mt * 16 + fr) * RS + ks * 32 + fq * 8);
; #pragma unroll
;         for (int nt = 0; nt < 4; ++nt) { const bf16x8 bk = *(const LAS bf16x8*)(KB + (wc * 64 + nt * 16 + fr) * RS + ks * 32 + fq * 8);
; #pragma unroll
;             for (int mt = 0; mt < 2; ++mt) accP[mt][nt] = __builtin_amdgcn_mfma_f32_16x16x32_bf16(aq[mt], bk, accP[mt][nt], 0, 0, 0); }
;         __builtin_amdgcn_sched_barrier(0); }
;     __syncthreads();
;     { float ri[2][4], cj[4];
; #pragma unroll
;       for (int mt = 0; mt < 2; ++mt)
; #pragma unroll
;           for (int j = 0; j < 4; ++j) ri[mt][j] = exp2f(lg2 * (float)(wr * 32 + mt * 16 + fq * 4 + j));
	ds_read_b128 v[0:3], v68
	v_and_or_b32 v63, v10, 64, v8
	v_mad_u32_u24 v70, v63, s25, v73
	ds_read_b128 v[4:7], v68 offset:4352
	ds_read_b128 v[8:11], v70 offset:34816
	ds_read_b128 v[12:15], v70 offset:39168
	ds_read_b128 v[80:83], v70 offset:43520
	ds_read_b128 v[84:87], v70 offset:47872
	s_waitcnt lgkmcnt(3)
	s_nop 0
	v_mfma_f32_16x16x32_bf16 v[16:19], v[0:3], v[8:11], 0
	v_or_b32_e64 v116, 16, v63
	v_or_b32_e64 v117, 32, v63
	v_or_b32_e64 v118, 48, v63
	v_mfma_f32_16x16x32_bf16 v[8:11], v[4:7], v[8:11], 0
	s_waitcnt lgkmcnt(2)
	s_nop 0
	v_mfma_f32_16x16x32_bf16 v[64:67], v[0:3], v[12:15], 0
	v_mfma_f32_16x16x32_bf16 v[12:15], v[4:7], v[12:15], 0
	s_waitcnt lgkmcnt(1)
	s_nop 0
	v_mfma_f32_16x16x32_bf16 v[88:91], v[0:3], v[80:83], 0
	v_mfma_f32_16x16x32_bf16 v[80:83], v[4:7], v[80:83], 0
	s_waitcnt lgkmcnt(0)
	s_nop 0
	v_mfma_f32_16x16x32_bf16 v[0:3], v[0:3], v[84:87], 0
	v_mfma_f32_16x16x32_bf16 v[4:7], v[4:7], v[84:87], 0
	ds_read_b128 v[84:87], v68 offset:64
	ds_read_b128 v[92:95], v68 offset:4416
	ds_read_b128 v[96:99], v70 offset:34880
	ds_read_b128 v[100:103], v70 offset:39232
	s_waitcnt lgkmcnt(1)
	s_nop 0
	v_mfma_f32_16x16x32_bf16 v[16:19], v[84:87], v[96:99], v[16:19]
	v_mfma_f32_16x16x32_bf16 v[8:11], v[92:95], v[96:99], v[8:11]
	s_waitcnt lgkmcnt(0)
	s_nop 0
	v_mfma_f32_16x16x32_bf16 v[64:67], v[84:87], v[100:103], v[64:67]
	v_mfma_f32_16x16x32_bf16 v[12:15], v[92:95], v[100:103], v[12:15]
	ds_read_b128 v[96:99], v70 offset:43584
	ds_read_b128 v[100:103], v70 offset:47936
	s_waitcnt lgkmcnt(1)
	s_nop 0
	v_mfma_f32_16x16x32_bf16 v[88:91], v[84:87], v[96:99], v[88:91]
	v_mfma_f32_16x16x32_bf16 v[80:83], v[92:95], v[96:99], v[80:83]
	s_waitcnt lgkmcnt(0)
	s_nop 0
	v_mfma_f32_16x16x32_bf16 v[0:3], v[84:87], v[100:103], v[0:3]
	v_mfma_f32_16x16x32_bf16 v[4:7], v[92:95], v[100:103], v[4:7]
	ds_read_b128 v[84:87], v68 offset:128
	ds_read_b128 v[92:95], v68 offset:4480
	ds_read_b128 v[96:99], v70 offset:34944
	ds_read_b128 v[100:103], v70 offset:39296
	s_waitcnt lgkmcnt(1)
	s_nop 0
	v_mfma_f32_16x16x32_bf16 v[16:19], v[84:87], v[96:99], v[16:19]
	v_mfma_f32_16x16x32_bf16 v[8:11], v[92:95], v[96:99], v[8:11]
	s_waitcnt lgkmcnt(0)
	s_nop 0
	v_mfma_f32_16x16x32_bf16 v[64:67], v[84:87], v[100:103], v[64:67]
	v_mfma_f32_16x16x32_bf16 v[96:99], v[92:95], v[100:103], v[12:15]
	s_nop 2
	s_nop 0
	ds_read_b128 v[12:15], v70 offset:43648
	ds_read_b128 v[100:103], v70 offset:48000
	s_waitcnt lgkmcnt(1)
	s_nop 0
	v_mfma_f32_16x16x32_bf16 v[88:91], v[84:87], v[12:15], v[88:91]
	v_mfma_f32_16x16x32_bf16 v[80:83], v[92:95], v[12:15], v[80:83]
	s_waitcnt lgkmcnt(0)
	s_nop 0
	v_mfma_f32_16x16x32_bf16 v[0:3], v[84:87], v[100:103], v[0:3]
	v_mfma_f32_16x16x32_bf16 v[84:87], v[92:95], v[100:103], v[4:7]
	ds_read_b128 v[92:95], v68 offset:192
	ds_read_b128 v[100:103], v68 offset:4544
	s_nop 0
	s_nop 0
	ds_read_b128 v[4:7], v70 offset:35008
	ds_read_b128 v[104:107], v70 offset:39360
	s_waitcnt lgkmcnt(1)
	s_nop 0
	v_mfma_f32_16x16x32_bf16 v[108:111], v[92:95], v[4:7], v[16:19]
	v_mfma_f32_16x16x32_bf16 v[12:15], v[100:103], v[4:7], v[8:11]
	s_waitcnt lgkmcnt(0)
	s_nop 0
	v_mfma_f32_16x16x32_bf16 v[112:115], v[92:95], v[104:107], v[64:67]
	ds_read_b128 v[4:7], v70 offset:43712
	s_nop 1
	s_nop 0
	ds_read_b128 v[64:67], v70 offset:48064
	v_mfma_f32_16x16x32_bf16 v[8:11], v[100:103], v[104:107], v[96:99]
	s_waitcnt lgkmcnt(1)
	s_nop 0
	v_mfma_f32_16x16x32_bf16 v[88:91], v[92:95], v[4:7], v[88:91]
	v_mfma_f32_16x16x32_bf16 v[4:7], v[100:103], v[4:7], v[80:83]
	s_waitcnt lgkmcnt(0)
	s_nop 0
	v_mfma_f32_16x16x32_bf16 v[16:19], v[92:95], v[64:67], v[0:3]
	v_mfma_f32_16x16x32_bf16 v[0:3], v[100:103], v[64:67], v[84:87]
	v_lshl_or_b32 v72, v28, 2, v69
	v_cvt_f32_i32_e64 v28, v72
	v_or_b32_e64 v71, 1, v72
	v_cvt_f32_i32_e64 v65, v71
	v_or_b32_e64 v70, 2, v72
	v_mul_f32_e64 v64, v62, v28
	v_cmp_gt_f32_e64 vcc, s21, v64
	v_mul_f32_e64 v66, v62, v65
	v_or_b32_e64 v69, 3, v72
	v_cndmask_b32_e64 v64, 0, v56, vcc
	v_fmac_f32_e64 v64, v62, v28
	v_exp_f32_e64 v28, v64
	v_cndmask_b32_e64 v64, 0, v59, vcc
	v_cmp_gt_f32_e64 vcc, s21, v66
	v_or_b32_e64 v67, 16, v72
	v_ldexp_f32 v81, v28, v64
	v_cndmask_b32_e64 v66, 0, v56, vcc
	v_fmac_f32_e64 v66, v62, v65
	v_exp_f32_e64 v65, v66
	v_cvt_f32_i32_e64 v66, v70
	v_cndmask_b32_e64 v28, 0, v59, vcc
	v_cvt_f32_i32_e64 v64, v69
	v_ldexp_f32 v84, v65, v28
	v_mul_f32_e64 v28, v62, v66
	v_cmp_gt_f32_e64 vcc, s21, v28
	v_cvt_f32_i32_e64 v80, v67
	s_nop 0
	s_nop 0
	v_cndmask_b32_e64 v28, 0, v56, vcc
	v_fmac_f32_e64 v28, v62, v66
	v_mul_f32_e64 v66, v62, v64
	v_cndmask_b32_e64 v65, 0, v59, vcc
	v_cmp_gt_f32_e64 vcc, s21, v66
	v_exp_f32_e64 v28, v28
	s_barrier
; __device__ __forceinline__ bf16_t f2bf(float f) { unsigned u = __float_as_uint(f); u += 0x7FFFu + ((u >> 16) & 1u); return (bf16_t)(u >> 16); }
; __device__ __forceinline__ void ret_unit_a(PR P, LAS unsigned char* lds, const int bh, const int n, const int wv) {
;     ...
;     { float ri[2][4], cj[4];
; #pragma unroll
;       for (int mt = 0; mt < 2; ++mt)
; #pragma unroll
;           for (int j = 0; j < 4; ++j) ri[mt][j] = exp2f(lg2 * (float)(wr * 32 + mt * 16 + fq * 4 + j));
; #pragma unroll
;       for (int nt = 0; nt < 4; ++nt) cj[nt] = exp2f(-lg2 * (float)(wc * 64 + nt * 16 + fr));
; #pragma unroll
;       for (int mt = 0; mt < 2; ++mt)
; #pragma unroll
;           for (int nt = 0; nt < 4; ++nt)
; #pragma unroll
;               for (int j = 0; j < 4; ++j) { const int i = wr * 32 + mt * 16 + fq * 4 + j, jj = wc * 64 + nt * 16 + fr;
;                   const float val = i >= jj ? accP[mt][nt][j] * ri[mt][j] * cj[nt] : 0.f; QP[i * RS + jj] = f2bf(val); } }
	s_nop 0
	v_cndmask_b32_e64 v66, 0, v56, vcc
	v_fmac_f32_e64 v66, v62, v64
	v_exp_f32_e64 v64, v66
	v_ldexp_f32 v85, v28, v65
	v_cndmask_b32_e64 v28, 0, v59, vcc
	v_or_b32_e64 v66, 17, v72
	v_ldexp_f32 v86, v64, v28
	v_cvt_f32_i32_e64 v64, v66
	v_mul_f32_e64 v28, v62, v80
	v_cmp_gt_f32_e64 vcc, s21, v28
	v_mul_f32_e64 v65, v62, v64
	s_nop 0
	s_nop 0
	v_cndmask_b32_e64 v28, 0, v56, vcc
	v_fmac_f32_e64 v28, v62, v80
	v_cndmask_b32_e64 v80, 0, v59, vcc
	v_cmp_gt_f32_e64 vcc, s21, v65
	v_exp_f32_e64 v28, v28
	v_mul_f32_e64 v16, v81, v16
	v_cndmask_b32_e64 v65, 0, v56, vcc
	v_fmac_f32_e64 v65, v62, v64
	v_exp_f32_e64 v64, v65
	v_or_b32_e64 v65, 18, v72
	v_cvt_f32_i32_e64 v82, v65
	v_ldexp_f32 v87, v28, v80
	v_cndmask_b32_e64 v28, 0, v59, vcc
	v_ldexp_f32 v92, v64, v28
	v_or_b32_e64 v64, 19, v72
	v_cvt_f32_i32_e64 v80, v64
	v_mul_f32_e64 v28, v62, v82
	v_cmp_gt_f32_e64 vcc, s21, v28
	v_mul_f32_e64 v12, v87, v12
	v_mul_f32_e64 v8, v87, v8
	v_cndmask_b32_e64 v28, 0, v56, vcc
	v_fmac_f32_e64 v28, v62, v82
	v_mul_f32_e64 v82, v62, v80
	v_cmp_gt_f32_e64 s[8:9], s21, v82
	v_exp_f32_e64 v28, v28
	v_mul_f32_e64 v4, v87, v4
	v_cndmask_b32_e64 v82, 0, v56, s[8:9]
	v_fmac_f32_e64 v82, v62, v80
	v_exp_f32_e64 v80, v82
	v_cndmask_b32_e64 v82, 0, v59, vcc
	v_ldexp_f32 v93, v28, v82
	v_cndmask_b32_e64 v28, 0, v59, s[8:9]
	v_ldexp_f32 v94, v80, v28
	v_cvt_f32_ubyte0_e64 v28, v63
	v_mul_f32_e64 v80, -v62, v28
	v_cmp_gt_f32_e64 vcc, s21, v80
	v_mul_f32_e64 v0, v87, v0
	s_nop 0
	s_nop 0
	v_cndmask_b32_e64 v80, 0, v56, vcc
	v_fma_f32 v28, -v62, v28, v80
	v_cvt_f32_ubyte0_e64 v80, v116
	v_mul_f32_e64 v82, -v62, v80
	v_cmp_gt_f32_e64 s[8:9], s21, v82
	v_exp_f32_e64 v28, v28
	s_nop 0
	s_nop 0
	v_cndmask_b32_e64 v82, 0, v56, s[8:9]
	v_fma_f32 v80, -v62, v80, v82
	v_exp_f32_e64 v80, v80
	v_cndmask_b32_e64 v82, 0, v59, vcc
	v_ldexp_f32 v95, v28, v82
	v_cndmask_b32_e64 v28, 0, v59, s[8:9]
	v_ldexp_f32 v96, v80, v28
	v_cvt_f32_ubyte0_e64 v28, v117
	v_mul_f32_e64 v80, -v62, v28
	v_cmp_gt_f32_e64 vcc, s21, v80
	v_mul_f32_e64 v12, v95, v12
	v_mul_f32_e64 v8, v96, v8
	v_cndmask_b32_e64 v80, 0, v56, vcc
	v_fma_f32 v28, -v62, v28, v80
	v_cvt_f32_ubyte0_e64 v80, v118
	v_mul_f32_e64 v82, -v62, v80
	v_cmp_gt_f32_e64 s[8:9], s21, v82
	v_exp_f32_e64 v28, v28
	s_nop 0
	s_nop 0
	v_cndmask_b32_e64 v82, 0, v56, s[8:9]
	v_fma_f32 v80, -v62, v80, v82
	v_exp_f32_e64 v80, v80
	v_cndmask_b32_e64 v82, 0, v59, vcc
	v_ldexp_f32 v97, v28, v82
	v_mul_f32_e64 v82, v81, v108
	v_cndmask_b32_e64 v28, 0, v59, s[8:9]
	v_mul_f32_e64 v82, v95, v82
	v_cmp_lt_i32_e64 vcc, v72, v63
	v_ldexp_f32 v98, v80, v28
	v_lshlrev_b32_e64 v28, 1, v63
	v_cndmask_b32_e64 v82, v82, 0, vcc
	v_add_u32_e64 v80, 0, v28
	v_bfe_u32 v83, v82, 16, 1
	v_add3_u32 v99, v82, v83, s27
	v_mad_u64_u32 v[82:83], s[8:9], v72, s25, v[80:81]
	v_mul_f32_e64 v83, v84, v109
	v_mul_f32_e64 v83, v95, v83
	v_cmp_ge_i32_e64 s[8:9], v71, v63
	ds_write_b16_d16_hi v82, v99
	v_mul_f32_e64 v16, v98, v16
	v_cndmask_b32_e64 v83, 0, v83, s[8:9]
	v_bfe_u32 v99, v83, 16, 1
	v_add3_u32 v83, v83, v99, s27
	ds_write_b16_d16_hi v82, v83 offset:272
	v_mul_f32_e64 v83, v85, v110
	v_mul_f32_e64 v83, v95, v83
	v_cmp_ge_i32_e64 s[8:9], v70, v63
	v_cndmask_b32_e64 v8, v8, 0, vcc
	v_cmp_ge_i32_e64 vcc, v66, v116
	v_cndmask_b32_e64 v83, 0, v83, s[8:9]
	v_bfe_u32 v99, v83, 16, 1
	v_add3_u32 v83, v83, v99, s27
	ds_write_b16_d16_hi v82, v83 offset:544
	v_mul_f32_e64 v83, v86, v111
	v_mul_f32_e64 v83, v95, v83
	v_cmp_ge_i32_e64 s[8:9], v69, v63
	v_mul_f32_e64 v4, v97, v4
	v_mul_f32_e64 v0, v98, v0
	v_cndmask_b32_e64 v83, 0, v83, s[8:9]
	v_bfe_u32 v99, v83, 16, 1
	v_add3_u32 v83, v83, v99, s27
	ds_write_b16_d16_hi v82, v83 offset:816
	v_mul_f32_e64 v83, v81, v112
	v_mul_f32_e64 v83, v96, v83
	v_cmp_ge_i32_e64 s[8:9], v72, v116
	s_nop 1
	s_nop 0
	v_cndmask_b32_e64 v83, 0, v83, s[8:9]
	v_bfe_u32 v99, v83, 16, 1
	v_add3_u32 v83, v83, v99, s27
	ds_write_b16_d16_hi v82, v83 offset:32
	v_mul_f32_e64 v83, v84, v113
	v_mul_f32_e64 v83, v96, v83
	v_cmp_ge_i32_e64 s[8:9], v71, v116
	s_nop 1
	s_nop 0
	v_cndmask_b32_e64 v83, 0, v83, s[8:9]
	v_bfe_u32 v99, v83, 16, 1
	v_add3_u32 v83, v83, v99, s27
	ds_write_b16_d16_hi v82, v83 offset:304
	v_mul_f32_e64 v83, v85, v114
	v_mul_f32_e64 v83, v96, v83
	v_cmp_ge_i32_e64 s[8:9], v70, v116
	s_nop 1
	s_nop 0
	v_cndmask_b32_e64 v83, 0, v83, s[8:9]
	v_bfe_u32 v99, v83, 16, 1
	v_add3_u32 v83, v83, v99, s27
	ds_write_b16_d16_hi v82, v83 offset:576
	v_mul_f32_e64 v83, v86, v115
	v_mul_f32_e64 v83, v96, v83
	v_cmp_ge_i32_e64 s[8:9], v69, v116
	s_nop 1
	s_nop 0
	v_cndmask_b32_e64 v83, 0, v83, s[8:9]
	v_bfe_u32 v99, v83, 16, 1
	v_add3_u32 v83, v83, v99, s27
	ds_write_b16_d16_hi v82, v83 offset:848
	v_mul_f32_e64 v83, v81, v88
	v_mul_f32_e64 v83, v97, v83
	v_cmp_ge_i32_e64 s[8:9], v72, v117
	s_nop 1
	s_nop 0
	v_cndmask_b32_e64 v83, 0, v83, s[8:9]
	v_bfe_u32 v88, v83, 16, 1
	v_add3_u32 v83, v83, v88, s27
	ds_write_b16_d16_hi v82, v83 offset:64
	v_mul_f32_e64 v83, v84, v89
	v_mul_f32_e64 v83, v97, v83
	v_cmp_ge_i32_e64 s[8:9], v71, v117
	s_nop 1
	s_nop 0
	v_cndmask_b32_e64 v83, 0, v83, s[8:9]
	v_bfe_u32 v88, v83, 16, 1
	v_add3_u32 v83, v83, v88, s27
	ds_write_b16_d16_hi v82, v83 offset:336
	v_mul_f32_e64 v83, v85, v90
	v_mul_f32_e64 v83, v97, v83
	v_cmp_ge_i32_e64 s[8:9], v70, v117
	s_nop 1
	s_nop 0
	v_cndmask_b32_e64 v83, 0, v83, s[8:9]
	v_bfe_u32 v88, v83, 16, 1
	v_add3_u32 v83, v83, v88, s27
	ds_write_b16_d16_hi v82, v83 offset:608
	v_mul_f32_e64 v83, v86, v91
	v_mul_f32_e64 v83, v97, v83
	v_cmp_ge_i32_e64 s[8:9], v69, v117
	s_nop 1
	s_nop 0
	v_cndmask_b32_e64 v83, 0, v83, s[8:9]
	v_cmp_ge_i32_e64 s[8:9], v72, v118
	v_bfe_u32 v88, v83, 16, 1
; __device__ __forceinline__ int fresh_tid(int wv) { int l; asm volatile("v_mbcnt_lo_u32_b32 %0, -1, 0\n\tv_mbcnt_hi_u32_b32 %0, -1, %0" : "=v"(l)); return wv * 64 + l; }
; #define LAS __attribute__((address_space(3)))
; template <bool WITH_K>
; __device__ __forceinline__ void ret_load_qk(PR P, LAS bf16_t* QP, LAS bf16_t* KB, unsigned (&kth)[4][4], const int tidv, const int row0, const int n, const int h, const float kd0, const float g32) {
;     ...
;             kth[it][0] = pg8::cvt_pk_bf16(ko1[0] * kd, ko1[1] * kd); kth[it][1] = pg8::cvt_pk_bf16(ko1[2] * kd, ko1[3] * kd);
;             kth[it][2] = pg8::cvt_pk_bf16(ko2[0] * kd, ko2[1] * kd); kth[it][3] = pg8::cvt_pk_bf16(ko2[2] * kd, ko2[3] * kd); kd *= g32; }
;         if (it & 1) __builtin_amdgcn_sched_barrier(0); }
; }
; __device__ __forceinline__ void ret_unit_a(PR P, LAS unsigned char* lds, const int bh, const int n, const int wv) {
;     LAS bf16_t* QP = (LAS bf16_t*)lds; LAS bf16_t* KB = QP + BUFE; LAS bf16_t* VT = KB + BUFE;
;     const int tid = fresh_tid(wv), lane = tid & 63, wid = tid >> 6, wr = wid >> 1, wc = wid & 1, fr = lane & 15, fq = lane >> 4;
;     const int b = bh >> 2, h = bh & 3;
;     const bf16_t* PS = (const bf16_t*)(P.ws + WS_BIG); bf16_t* Y = (bf16_t*)(P.ws + WS_XN); bf16_t* KVB = kvb_ptr(P.ws, bh) + (size_t)n * 16384;
;     const float lg2 = log2f(1.0f - exp2f(-5.0f - (float)h));
;     const float kd0 = exp2f(lg2 * (float)(127 - (tid >> 4))), g32 = exp2f(-32.0f * lg2);
;     ...
;       for (int mt = 0; mt < 2; ++mt)
; #pragma unroll
;           for (int nt = 0; nt < 4; ++nt)
; #pragma unroll
;               for (int j = 0; j < 4; ++j) { const int i = wr * 32 + mt * 16 + fq * 4 + j, jj = wc * 64 + nt * 16 + fr;
;                   const float val = i >= jj ? accP[mt][nt][j] * ri[mt][j] * cj[nt] : 0.f; QP[i * RS + jj] = f2bf(val); } }
; #pragma unroll
;     for (int it = 0; it < 4; ++it) { const int idx = it * 512 + tid, j = idx >> 4, f = (idx & 15) * 4; LAS bf16_t* d = KB + f * RS + j;
;         d[0] = (bf16_t)(kth[it][0] & 0xffffu); d[RS] = (bf16_t)(kth[it][0] >> 16); d[2 * RS] = (bf16_t)(kth[it][1] & 0xffffu); d[3 * RS] = (bf16_t)(kth[it][1] >> 16);
;         LAS bf16_t* d2 = d + 64 * RS;
;         d2[0] = (bf16_t)(kth[it][2] & 0xffffu); d2[RS] = (bf16_t)(kth[it][2] >> 16); d2[2 * RS] = (bf16_t)(kth[it][3] & 0xffffu); d2[3 * RS] = (bf16_t)(kth[it][3] >> 16); }
	v_add3_u32 v83, v83, v88, s27
	v_cndmask_b32_e64 v16, 0, v16, s[8:9]
	v_bfe_u32 v81, v16, 16, 1
	v_add3_u32 v16, v16, v81, s27
	ds_write_b16_d16_hi v82, v16 offset:96
	v_mul_f32_e64 v16, v84, v17
	v_mul_f32_e64 v16, v98, v16
	v_cmp_ge_i32_e64 s[8:9], v71, v118
	ds_write_b16_d16_hi v82, v83 offset:880
	s_nop 0
	s_nop 0
	v_cndmask_b32_e64 v16, 0, v16, s[8:9]
	v_bfe_u32 v17, v16, 16, 1
	v_add3_u32 v16, v16, v17, s27
	ds_write_b16_d16_hi v82, v16 offset:368
	v_mul_f32_e64 v16, v85, v18
	v_mul_f32_e64 v16, v98, v16
	v_cmp_ge_i32_e64 s[8:9], v70, v118
	s_nop 1
	s_nop 0
	v_cndmask_b32_e64 v16, 0, v16, s[8:9]
	v_bfe_u32 v17, v16, 16, 1
	v_add3_u32 v16, v16, v17, s27
	ds_write_b16_d16_hi v82, v16 offset:640
	v_mul_f32_e64 v16, v86, v19
	v_mul_f32_e64 v16, v98, v16
	v_cmp_ge_i32_e64 s[8:9], v69, v118
	s_nop 1
	s_nop 0
	v_cndmask_b32_e64 v16, 0, v16, s[8:9]
	v_bfe_u32 v17, v16, 16, 1
	v_cmp_ge_i32_e64 s[8:9], v67, v63
	v_add3_u32 v16, v16, v17, s27
	ds_write_b16_d16_hi v82, v16 offset:912
	v_cndmask_b32_e64 v12, 0, v12, s[8:9]
	v_bfe_u32 v16, v12, 16, 1
	v_add3_u32 v12, v12, v16, s27
	v_mad_u64_u32 v[16:17], s[8:9], v67, s25, v[80:81]
	ds_write_b16_d16_hi v16, v12
	v_mul_f32_e64 v12, v92, v13
	v_mul_f32_e64 v12, v95, v12
	v_cmp_ge_i32_e64 s[8:9], v66, v63
	s_nop 1
	s_nop 0
	v_cndmask_b32_e64 v12, 0, v12, s[8:9]
	v_bfe_u32 v13, v12, 16, 1
	v_add3_u32 v12, v12, v13, s27
	ds_write_b16_d16_hi v16, v12 offset:272
	v_mul_f32_e64 v12, v93, v14
	v_mul_f32_e64 v12, v95, v12
	v_cmp_ge_i32_e64 s[8:9], v65, v63
	s_nop 1
	s_nop 0
	v_cndmask_b32_e64 v12, 0, v12, s[8:9]
	v_bfe_u32 v13, v12, 16, 1
	v_add3_u32 v12, v12, v13, s27
	ds_write_b16_d16_hi v16, v12 offset:544
	v_mul_f32_e64 v12, v94, v15
	v_mul_f32_e64 v12, v95, v12
	v_cmp_ge_i32_e64 s[8:9], v64, v63
	s_nop 1
	s_nop 0
	v_cndmask_b32_e64 v12, 0, v12, s[8:9]
	v_bfe_u32 v13, v12, 16, 1
	v_add3_u32 v12, v12, v13, s27
	ds_write_b16_d16_hi v16, v12 offset:816
	v_bfe_u32 v12, v8, 16, 1
	v_add3_u32 v8, v8, v12, s27
	ds_write_b16_d16_hi v16, v8 offset:32
	v_mul_f32_e64 v8, v92, v9
	v_mul_f32_e64 v8, v96, v8
	v_cndmask_b32_e64 v8, 0, v8, vcc
	v_bfe_u32 v9, v8, 16, 1
	v_add3_u32 v8, v8, v9, s27
	ds_write_b16_d16_hi v16, v8 offset:304
	v_mul_f32_e64 v8, v93, v10
	v_mul_f32_e64 v8, v96, v8
	v_cmp_ge_i32_e64 vcc, v65, v116
	s_ashr_i32 s9, s30, 31
	s_sub_i32 s8, s30, 29
	v_cndmask_b32_e64 v8, 0, v8, vcc
	v_bfe_u32 v9, v8, 16, 1
	v_add3_u32 v8, v8, v9, s27
	ds_write_b16_d16_hi v16, v8 offset:576
	v_mul_f32_e64 v8, v94, v11
	v_mul_f32_e64 v8, v96, v8
	v_cmp_ge_i32_e64 vcc, v64, v116
	s_cmp_lt_i32 s30, 29
	s_nop 0
	s_cselect_b32 s31, s28, 0x1444800
	v_cndmask_b32_e64 v8, 0, v8, vcc
	v_bfe_u32 v9, v8, 16, 1
	v_cmp_ge_i32_e64 vcc, v67, v117
	v_add3_u32 v8, v8, v9, s27
	ds_write_b16_d16_hi v16, v8 offset:848
	v_cndmask_b32_e64 v4, 0, v4, vcc
	v_bfe_u32 v8, v4, 16, 1
	v_add3_u32 v4, v4, v8, s27
	ds_write_b16_d16_hi v16, v4 offset:64
	v_mul_f32_e64 v4, v92, v5
	v_mul_f32_e64 v4, v97, v4
	v_cmp_ge_i32_e64 vcc, v66, v117
	s_cselect_b32 s8, s30, s8
	s_cselect_b32 s9, s9, 0
	v_cndmask_b32_e64 v4, 0, v4, vcc
	v_bfe_u32 v5, v4, 16, 1
	v_add3_u32 v4, v4, v5, s27
	ds_write_b16_d16_hi v16, v4 offset:336
	v_mul_f32_e64 v4, v93, v6
	v_mul_f32_e64 v4, v97, v4
	v_cmp_ge_i32_e64 vcc, v65, v117
	s_add_u32 s30, s10, s31
	s_addc_u32 s31, s11, 0
	v_cndmask_b32_e64 v4, 0, v4, vcc
	v_bfe_u32 v5, v4, 16, 1
	v_add3_u32 v4, v4, v5, s27
	ds_write_b16_d16_hi v16, v4 offset:608
	v_mul_f32_e64 v4, v94, v7
	v_mul_f32_e64 v4, v97, v4
	v_cmp_ge_i32_e64 vcc, v64, v117
	s_lshl_b64 s[8:9], s[8:9], 19
	s_add_u32 s8, s30, s8
	v_cndmask_b32_e64 v4, 0, v4, vcc
	v_bfe_u32 v5, v4, 16, 1
	v_cmp_ge_i32_e64 vcc, v67, v118
	v_add3_u32 v4, v4, v5, s27
	ds_write_b16_d16_hi v16, v4 offset:880
	v_cndmask_b32_e64 v0, 0, v0, vcc
	v_bfe_u32 v4, v0, 16, 1
	v_add3_u32 v0, v0, v4, s27
	ds_write_b16_d16_hi v16, v0 offset:96
	v_mul_f32_e64 v0, v92, v1
	v_mul_f32_e64 v0, v98, v0
	v_cmp_ge_i32_e64 vcc, v66, v118
	s_addc_u32 s9, s31, s9
	s_add_u32 s8, s8, s7
	v_cndmask_b32_e64 v0, 0, v0, vcc
	v_bfe_u32 v1, v0, 16, 1
	v_add3_u32 v0, v0, v1, s27
	ds_write_b16_d16_hi v16, v0 offset:368
	v_mul_f32_e64 v0, v93, v2
	v_mul_f32_e64 v0, v98, v0
	v_cmp_ge_i32_e64 vcc, v65, v118
	s_addc_u32 s9, s9, 0
	s_nop 0
	v_cndmask_b32_e64 v0, 0, v0, vcc
	v_bfe_u32 v1, v0, 16, 1
	v_add3_u32 v0, v0, v1, s27
	ds_write_b16_d16_hi v16, v0 offset:640
	v_mul_f32_e64 v0, v94, v3
	v_mul_f32_e64 v0, v98, v0
	v_cmp_ge_i32_e64 vcc, v64, v118
	s_nop 1
	s_nop 0
	v_cndmask_b32_e64 v4, 0, v0, vcc
	v_sub_u32_e32 v0, 0x7f, v61
	v_cvt_f32_i32_e64 v0, v0
	v_mul_f32_e64 v1, v62, v0
	v_cmp_gt_f32_e64 vcc, s21, v1
	s_nop 1
	s_nop 0
	v_cndmask_b32_e64 v1, 0, v56, vcc
	v_fmac_f32_e64 v1, v62, v0
	v_exp_f32_e64 v0, v1
	v_cndmask_b32_e64 v1, 0, v59, vcc
	v_ldexp_f32 v0, v0, v1
	v_pk_mul_f32 v[2:3], v[0:1], v[22:23] op_sel_hi:[0,1]
	v_cvt_pk_bf16_f32 v5, v2, v3
	v_pk_mul_f32 v[2:3], v[0:1], v[26:27] op_sel_hi:[0,1]
	v_cvt_pk_bf16_f32 v6, v2, v3
	v_pk_mul_f32 v[2:3], v[0:1], v[20:21] op_sel_hi:[0,1]
	v_cvt_pk_bf16_f32 v7, v2, v3
	v_pk_mul_f32 v[2:3], v[0:1], v[24:25] op_sel_hi:[0,1]
	v_mul_f32_e32 v1, 0xc2000000, v62
	v_cmp_gt_f32_e64 vcc, s21, v1
	s_and_b64 s[30:31], vcc, exec
	s_nop 0
	s_cselect_b32 s30, 0xffffffc0, 0
	v_cndmask_b32_e64 v1, 0, v56, vcc
	v_fmac_f32_e32 v1, 0xc2000000, v62
	v_exp_f32_e64 v1, v1
	v_cvt_pk_bf16_f32 v8, v2, v3
	v_ldexp_f32 v1, v1, s30
	v_mul_f32_e64 v0, v1, v0
	v_pk_mul_f32 v[2:3], v[0:1], v[34:35] op_sel_hi:[0,1]
	v_cvt_pk_bf16_f32 v9, v2, v3
	v_pk_mul_f32 v[2:3], v[0:1], v[38:39] op_sel_hi:[0,1]
	v_cvt_pk_bf16_f32 v10, v2, v3
	v_pk_mul_f32 v[2:3], v[0:1], v[32:33] op_sel_hi:[0,1]
	v_cvt_pk_bf16_f32 v11, v2, v3
; #define LAS __attribute__((address_space(3)))
; __device__ __forceinline__ void ret_unit_a(PR P, LAS unsigned char* lds, const int bh, const int n, const int wv) {
;     ...
;     for (int it = 0; it < 4; ++it) { const int idx = it * 512 + tid, j = idx >> 4, f = (idx & 15) * 4; LAS bf16_t* d = KB + f * RS + j;
;         d[0] = (bf16_t)(kth[it][0] & 0xffffu); d[RS] = (bf16_t)(kth[it][0] >> 16); d[2 * RS] = (bf16_t)(kth[it][1] & 0xffffu); d[3 * RS] = (bf16_t)(kth[it][1] >> 16);
;         LAS bf16_t* d2 = d + 64 * RS;
;         d2[0] = (bf16_t)(kth[it][2] & 0xffffu); d2[RS] = (bf16_t)(kth[it][2] >> 16); d2[2 * RS] = (bf16_t)(kth[it][3] & 0xffffu); d2[3 * RS] = (bf16_t)(kth[it][3] >> 16); }
;     __syncthreads();
;     f32x4 accY[2][4], accS[2][4];
; #pragma unroll
;     for (int mt = 0; mt < 2; ++mt)
; #pragma unroll
;         for (int nt = 0; nt < 4; ++nt) { accY[mt][nt] = (f32x4){0.f, 0.f, 0.f, 0.f}; accS[mt][nt] = (f32x4){0.f, 0.f, 0.f, 0.f}; }
; #pragma unroll
;     for (int ks = 0; ks < 4; ++ks) { bf16x8 ap[2], av[2];
; #pragma unroll
;         for (int mt = 0; mt < 2; ++mt) { ap[mt] = *(const LAS bf16x8*)(QP + (wr * 32 + mt * 16 + fr) * RS + ks * 32 + fq * 8); av[mt] = *(const LAS bf16x8*)(VT + (wr * 32 + mt * 16 + fr) * RS + ks * 32 + fq * 8); }
; #pragma unroll
;         for (int nt = 0; nt < 4; ++nt) { const bf16x8 bv = *(const LAS bf16x8*)(VT + (wc * 64 + nt * 16 + fr) * RS + ks * 32 + fq * 8), bkt = *(const LAS bf16x8*)(KB + (wc * 64 + nt * 16 + fr) * RS + ks * 32 + fq * 8);
; #pragma unroll
;             for (int mt = 0; mt < 2; ++mt) { accY[mt][nt] = __builtin_amdgcn_mfma_f32_16x16x32_bf16(ap[mt], bv, accY[mt][nt], 0, 0, 0); accS[mt][nt] = __builtin_amdgcn_mfma_f32_16x16x32_bf16(av[mt], bkt, accS[mt][nt], 0, 0, 0); } }
;         __builtin_amdgcn_sched_barrier(0); }
	v_pk_mul_f32 v[2:3], v[0:1], v[36:37] op_sel_hi:[0,1]
	v_mul_f32_e64 v0, v1, v0
	v_cvt_pk_bf16_f32 v12, v2, v3
	v_pk_mul_f32 v[2:3], v[0:1], v[44:45] op_sel_hi:[0,1]
	v_cvt_pk_bf16_f32 v13, v2, v3
	v_pk_mul_f32 v[2:3], v[0:1], v[46:47] op_sel_hi:[0,1]
	v_cvt_pk_bf16_f32 v14, v2, v3
	v_pk_mul_f32 v[2:3], v[0:1], v[40:41] op_sel_hi:[0,1]
	v_cvt_pk_bf16_f32 v15, v2, v3
	v_pk_mul_f32 v[2:3], v[0:1], v[42:43] op_sel_hi:[0,1]
	v_mul_f32_e64 v0, v1, v0
	v_cvt_pk_bf16_f32 v17, v2, v3
	v_pk_mul_f32 v[2:3], v[0:1], v[50:51] op_sel_hi:[0,1]
	v_cvt_pk_bf16_f32 v18, v2, v3
	v_pk_mul_f32 v[2:3], v[0:1], v[54:55] op_sel_hi:[0,1]
	v_cvt_pk_bf16_f32 v19, v2, v3
	v_pk_mul_f32 v[2:3], v[0:1], v[48:49] op_sel_hi:[0,1]
	v_pk_mul_f32 v[0:1], v[0:1], v[52:53] op_sel_hi:[0,1]
	v_cvt_pk_bf16_f32 v0, v0, v1
	v_bfe_u32 v1, v4, 16, 1
	v_add3_u32 v1, v4, v1, s27
	ds_write_b16_d16_hi v16, v1 offset:912
	v_mad_u32_u24 v1, v60, s25, 0
	v_cvt_pk_bf16_f32 v2, v2, v3
	v_add_u32_e64 v3, v1, v79
	ds_write_b16 v3, v5 offset:34816
	ds_write_b16_d16_hi v3, v5 offset:35088
	ds_write_b16 v3, v6 offset:35360
	ds_write_b16_d16_hi v3, v6 offset:35632
	ds_write_b16 v3, v7 offset:52224
	ds_write_b16_d16_hi v3, v7 offset:52496
	ds_write_b16 v3, v8 offset:52768
	ds_write_b16_d16_hi v3, v8 offset:53040
	v_add_u32_e64 v3, v1, v78
	ds_write_b16 v3, v9 offset:34816
	ds_write_b16_d16_hi v3, v9 offset:35088
	ds_write_b16 v3, v10 offset:35360
	ds_write_b16_d16_hi v3, v10 offset:35632
	ds_write_b16 v3, v11 offset:52224
	ds_write_b16_d16_hi v3, v11 offset:52496
	ds_write_b16 v3, v12 offset:52768
	ds_write_b16_d16_hi v3, v12 offset:53040
	v_add_u32_e64 v3, v1, v76
	v_add_u32_e64 v1, v1, v74
	ds_write_b16 v3, v13 offset:34816
	ds_write_b16_d16_hi v3, v13 offset:35088
	ds_write_b16 v3, v14 offset:35360
	ds_write_b16_d16_hi v3, v14 offset:35632
	ds_write_b16 v3, v15 offset:52224
	ds_write_b16_d16_hi v3, v15 offset:52496
	ds_write_b16 v3, v17 offset:52768
	ds_write_b16_d16_hi v3, v17 offset:53040
	ds_write_b16 v1, v18 offset:34816
	ds_write_b16_d16_hi v1, v18 offset:35088
	ds_write_b16 v1, v19 offset:35360
	ds_write_b16_d16_hi v1, v19 offset:35632
	ds_write_b16 v1, v2 offset:52224
	ds_write_b16_d16_hi v1, v2 offset:52496
	ds_write_b16 v1, v0 offset:52768
	ds_write_b16_d16_hi v1, v0 offset:53040
	s_waitcnt lgkmcnt(0)
	s_barrier
	ds_read_b128 v[0:3], v68
	v_mul_u32_u24_e32 v5, 0x88, v63
	v_add_u32_e64 v4, s26, v75
	v_lshlrev_b32_e64 v16, 1, v5
	v_add_u32_e64 v61, v4, v16
	v_add_u32_e64 v62, v73, v16
	v_add_u32_e64 v60, v4, v77
	ds_read_b128 v[4:7], v61
	ds_read_b128 v[8:11], v60
	ds_read_b128 v[12:15], v68 offset:4352
	ds_read_b128 v[16:19], v61 offset:4352
	ds_read_b128 v[24:27], v62 offset:34816
	ds_read_b128 v[32:35], v60 offset:4352
	ds_read_b128 v[36:39], v62 offset:39168
	ds_read_b128 v[52:55], v61 offset:8704
	ds_read_b128 v[74:77], v61 offset:13056
	ds_read_b128 v[82:85], v62 offset:43520
	ds_read_b128 v[86:89], v62 offset:47872
	s_waitcnt lgkmcnt(10)
	s_nop 0
	v_mfma_f32_16x16x32_bf16 v[20:23], v[0:3], v[4:7], 0
	s_waitcnt lgkmcnt(6)
	s_nop 0
	v_mfma_f32_16x16x32_bf16 v[40:43], v[8:11], v[24:27], 0
	v_mfma_f32_16x16x32_bf16 v[4:7], v[12:15], v[4:7], 0
	s_waitcnt lgkmcnt(5)
	s_nop 0
	v_mfma_f32_16x16x32_bf16 v[24:27], v[32:35], v[24:27], 0
	v_mfma_f32_16x16x32_bf16 v[44:47], v[0:3], v[16:19], 0
	s_waitcnt lgkmcnt(4)
	s_nop 0
	v_mfma_f32_16x16x32_bf16 v[48:51], v[8:11], v[36:39], 0
	v_mfma_f32_16x16x32_bf16 v[16:19], v[12:15], v[16:19], 0
	v_mfma_f32_16x16x32_bf16 v[36:39], v[32:35], v[36:39], 0
	s_waitcnt lgkmcnt(3)
	s_nop 0
	v_mfma_f32_16x16x32_bf16 v[78:81], v[0:3], v[52:55], 0
	s_waitcnt lgkmcnt(1)
	s_nop 0
	v_mfma_f32_16x16x32_bf16 v[90:93], v[8:11], v[82:85], 0
	v_mfma_f32_16x16x32_bf16 v[52:55], v[12:15], v[52:55], 0
	v_mfma_f32_16x16x32_bf16 v[82:85], v[32:35], v[82:85], 0
	v_mfma_f32_16x16x32_bf16 v[0:3], v[0:3], v[74:77], 0
	s_waitcnt lgkmcnt(0)
	s_nop 0
	v_mfma_f32_16x16x32_bf16 v[8:11], v[8:11], v[86:89], 0
	v_mfma_f32_16x16x32_bf16 v[12:15], v[12:15], v[74:77], 0
	v_mfma_f32_16x16x32_bf16 v[32:35], v[32:35], v[86:89], 0
	ds_read_b128 v[74:77], v68 offset:64
	ds_read_b128 v[86:89], v61 offset:64
	ds_read_b128 v[94:97], v60 offset:64
	ds_read_b128 v[98:101], v68 offset:4416
	ds_read_b128 v[102:105], v61 offset:4416
	ds_read_b128 v[106:109], v62 offset:34880
	ds_read_b128 v[110:113], v60 offset:4416
	ds_read_b128 v[114:117], v62 offset:39232
	s_waitcnt lgkmcnt(6)
	s_nop 0
	v_mfma_f32_16x16x32_bf16 v[20:23], v[74:77], v[86:89], v[20:23]
	s_waitcnt lgkmcnt(2)
	s_nop 0
	v_mfma_f32_16x16x32_bf16 v[40:43], v[94:97], v[106:109], v[40:43]
	v_mfma_f32_16x16x32_bf16 v[4:7], v[98:101], v[86:89], v[4:7]
	s_waitcnt lgkmcnt(1)
	s_nop 0
	v_mfma_f32_16x16x32_bf16 v[24:27], v[110:113], v[106:109], v[24:27]
	v_mfma_f32_16x16x32_bf16 v[44:47], v[74:77], v[102:105], v[44:47]
	s_waitcnt lgkmcnt(0)
	s_nop 0
	v_mfma_f32_16x16x32_bf16 v[48:51], v[94:97], v[114:117], v[48:51]
	v_mfma_f32_16x16x32_bf16 v[16:19], v[98:101], v[102:105], v[16:19]
	ds_read_b128 v[86:89], v61 offset:8768
	ds_read_b128 v[102:105], v61 offset:13120
	v_mfma_f32_16x16x32_bf16 v[36:39], v[110:113], v[114:117], v[36:39]
	ds_read_b128 v[106:109], v62 offset:43584
	ds_read_b128 v[114:117], v62 offset:47936
	s_waitcnt lgkmcnt(3)
	s_nop 0
	v_mfma_f32_16x16x32_bf16 v[78:81], v[74:77], v[86:89], v[78:81]
	s_waitcnt lgkmcnt(1)
	s_nop 0
	v_mfma_f32_16x16x32_bf16 v[90:93], v[94:97], v[106:109], v[90:93]
	v_mfma_f32_16x16x32_bf16 v[52:55], v[98:101], v[86:89], v[52:55]
	v_mfma_f32_16x16x32_bf16 v[82:85], v[110:113], v[106:109], v[82:85]
	v_mfma_f32_16x16x32_bf16 v[0:3], v[74:77], v[102:105], v[0:3]
	s_waitcnt lgkmcnt(0)
; #define LAS __attribute__((address_space(3)))
; __device__ __forceinline__ bf16_t f2bf(float f) { unsigned u = __float_as_uint(f); u += 0x7FFFu + ((u >> 16) & 1u); return (bf16_t)(u >> 16); }
; __device__ __forceinline__ void ret_unit_a(PR P, LAS unsigned char* lds, const int bh, const int n, const int wv) {
;     ...
;     for (int ks = 0; ks < 4; ++ks) { bf16x8 ap[2], av[2];
; #pragma unroll
;         for (int mt = 0; mt < 2; ++mt) { ap[mt] = *(const LAS bf16x8*)(QP + (wr * 32 + mt * 16 + fr) * RS + ks * 32 + fq * 8); av[mt] = *(const LAS bf16x8*)(VT + (wr * 32 + mt * 16 + fr) * RS + ks * 32 + fq * 8); }
; #pragma unroll
;         for (int nt = 0; nt < 4; ++nt) { const bf16x8 bv = *(const LAS bf16x8*)(VT + (wc * 64 + nt * 16 + fr) * RS + ks * 32 + fq * 8), bkt = *(const LAS bf16x8*)(KB + (wc * 64 + nt * 16 + fr) * RS + ks * 32 + fq * 8);
; #pragma unroll
;             for (int mt = 0; mt < 2; ++mt) { accY[mt][nt] = __builtin_amdgcn_mfma_f32_16x16x32_bf16(ap[mt], bv, accY[mt][nt], 0, 0, 0); accS[mt][nt] = __builtin_amdgcn_mfma_f32_16x16x32_bf16(av[mt], bkt, accS[mt][nt], 0, 0, 0); } }
;         __builtin_amdgcn_sched_barrier(0); }
; #pragma unroll
;     for (int mt = 0; mt < 2; ++mt)
; #pragma unroll
;         for (int nt = 0; nt < 4; ++nt)
; #pragma unroll
;             for (int j = 0; j < 4; ++j) { const int r = wr * 32 + mt * 16 + fq * 4 + j, c = wc * 64 + nt * 16 + fr;
;                 Y[(size_t)(row0 + r) * 1024 + 512 + h * 128 + c] = f2bf(accY[mt][nt][j]); KVB[r * 128 + c] = f2bf(accS[mt][nt][j]); }
	s_nop 0
	v_mfma_f32_16x16x32_bf16 v[8:11], v[94:97], v[114:117], v[8:11]
	v_mfma_f32_16x16x32_bf16 v[12:15], v[98:101], v[102:105], v[12:15]
	v_mfma_f32_16x16x32_bf16 v[32:35], v[110:113], v[114:117], v[32:35]
	ds_read_b128 v[74:77], v68 offset:128
	ds_read_b128 v[86:89], v61 offset:128
	ds_read_b128 v[94:97], v60 offset:128
	ds_read_b128 v[98:101], v68 offset:4480
	ds_read_b128 v[102:105], v61 offset:4480
	ds_read_b128 v[106:109], v62 offset:34944
	ds_read_b128 v[110:113], v60 offset:4480
	ds_read_b128 v[114:117], v62 offset:39296
	s_waitcnt lgkmcnt(6)
	s_nop 0
	v_mfma_f32_16x16x32_bf16 v[20:23], v[74:77], v[86:89], v[20:23]
	s_waitcnt lgkmcnt(2)
	s_nop 0
	v_mfma_f32_16x16x32_bf16 v[40:43], v[94:97], v[106:109], v[40:43]
	v_mfma_f32_16x16x32_bf16 v[4:7], v[98:101], v[86:89], v[4:7]
	s_waitcnt lgkmcnt(1)
	s_nop 0
	v_mfma_f32_16x16x32_bf16 v[24:27], v[110:113], v[106:109], v[24:27]
	v_mfma_f32_16x16x32_bf16 v[44:47], v[74:77], v[102:105], v[44:47]
	s_waitcnt lgkmcnt(0)
	s_nop 0
	v_mfma_f32_16x16x32_bf16 v[48:51], v[94:97], v[114:117], v[48:51]
	v_mfma_f32_16x16x32_bf16 v[16:19], v[98:101], v[102:105], v[16:19]
	ds_read_b128 v[86:89], v61 offset:8832
	ds_read_b128 v[102:105], v61 offset:13184
	v_mfma_f32_16x16x32_bf16 v[36:39], v[110:113], v[114:117], v[36:39]
	ds_read_b128 v[106:109], v62 offset:43648
	ds_read_b128 v[114:117], v62 offset:48000
	s_waitcnt lgkmcnt(3)
	s_nop 0
	v_mfma_f32_16x16x32_bf16 v[78:81], v[74:77], v[86:89], v[78:81]
	s_waitcnt lgkmcnt(1)
	s_nop 0
	v_mfma_f32_16x16x32_bf16 v[90:93], v[94:97], v[106:109], v[90:93]
	v_mfma_f32_16x16x32_bf16 v[52:55], v[98:101], v[86:89], v[52:55]
	v_mfma_f32_16x16x32_bf16 v[82:85], v[110:113], v[106:109], v[82:85]
	v_mfma_f32_16x16x32_bf16 v[0:3], v[74:77], v[102:105], v[0:3]
	s_waitcnt lgkmcnt(0)
	s_nop 0
	v_mfma_f32_16x16x32_bf16 v[74:77], v[94:97], v[114:117], v[8:11]
	v_mfma_f32_16x16x32_bf16 v[86:89], v[98:101], v[102:105], v[12:15]
	v_mfma_f32_16x16x32_bf16 v[32:35], v[110:113], v[114:117], v[32:35]
	ds_read_b128 v[94:97], v68 offset:192
	ds_read_b128 v[8:11], v61 offset:192
	ds_read_b128 v[98:101], v60 offset:192
	ds_read_b128 v[102:105], v68 offset:4544
	ds_read_b128 v[12:15], v61 offset:4544
	s_waitcnt lgkmcnt(3)
	s_nop 0
	v_mfma_f32_16x16x32_bf16 v[106:109], v[94:97], v[8:11], v[20:23]
	s_nop 2
	s_nop 0
	ds_read_b128 v[20:23], v62 offset:35008
	ds_read_b128 v[110:113], v60 offset:4544
	ds_read_b128 v[114:117], v62 offset:39360
	s_waitcnt lgkmcnt(2)
	s_nop 0
	v_mfma_f32_16x16x32_bf16 v[40:43], v[98:101], v[20:23], v[40:43]
	v_mfma_f32_16x16x32_bf16 v[118:121], v[102:105], v[8:11], v[4:7]
	s_waitcnt lgkmcnt(1)
	s_nop 0
	v_mfma_f32_16x16x32_bf16 v[24:27], v[110:113], v[20:23], v[24:27]
	s_waitcnt lgkmcnt(0)
	s_nop 0
	v_mfma_f32_16x16x32_bf16 v[48:51], v[98:101], v[114:117], v[48:51]
	v_mfma_f32_16x16x32_bf16 v[20:23], v[102:105], v[12:15], v[16:19]
	v_mfma_f32_16x16x32_bf16 v[16:19], v[110:113], v[114:117], v[36:39]
	ds_read_b128 v[4:7], v61 offset:8896
	s_nop 1
	s_nop 0
	ds_read_b128 v[36:39], v61 offset:13248
	ds_read_b128 v[8:11], v62 offset:43712
	ds_read_b128 v[114:117], v62 offset:48064
	v_mfma_f32_16x16x32_bf16 v[44:47], v[94:97], v[12:15], v[44:47]
	s_waitcnt lgkmcnt(3)
	s_nop 0
	v_mfma_f32_16x16x32_bf16 v[78:81], v[94:97], v[4:7], v[78:81]
	s_waitcnt lgkmcnt(1)
	s_nop 0
	v_mfma_f32_16x16x32_bf16 v[90:93], v[98:101], v[8:11], v[90:93]
	v_mfma_f32_16x16x32_bf16 v[12:15], v[102:105], v[4:7], v[52:55]
	v_mfma_f32_16x16x32_bf16 v[8:11], v[110:113], v[8:11], v[82:85]
	v_mfma_f32_16x16x32_bf16 v[52:55], v[94:97], v[36:39], v[0:3]
	s_waitcnt lgkmcnt(0)
	s_nop 0
	v_mfma_f32_16x16x32_bf16 v[74:77], v[98:101], v[114:117], v[74:77]
	v_mfma_f32_16x16x32_bf16 v[4:7], v[102:105], v[36:39], v[86:89]
	v_mfma_f32_16x16x32_bf16 v[0:3], v[110:113], v[114:117], v[32:35]
	s_add_u32 s30, s4, s12
	s_nop 1
	v_add_u32_e64 v34, s29, v72
	s_addc_u32 s31, s5, 0
	s_nop 0
	v_ashrrev_i32_e64 v35, 31, v34
	v_lshl_add_u64 v[32:33], s[30:31], 0, v[28:29]
	v_bfe_u32 v28, v106, 16, 1
	v_lshlrev_b64 v[34:35], 11, v[34:35]
	v_lshlrev_b32_e64 v62, 7, v72
	v_add3_u32 v28, v106, v28, s27
	v_lshl_add_u64 v[34:35], v[32:33], 0, v[34:35]
	v_or_b32_e64 v36, v62, v63
	global_store_short_d16_hi v[34:35], v28, off
	v_bfe_u32 v28, v40, 16, 1
	v_ashrrev_i32_e64 v37, 31, v36
	v_add3_u32 v28, v40, v28, s27
	v_lshl_add_u64 v[38:39], v[36:37], 1, s[8:9]
	global_store_short_d16_hi v[38:39], v28, off
	v_add_u32_e64 v38, s29, v71
	v_ashrrev_i32_e64 v39, 31, v38
	v_bfe_u32 v28, v107, 16, 1
	v_lshlrev_b64 v[38:39], 11, v[38:39]
	v_add3_u32 v28, v107, v28, s27
	v_lshl_add_u64 v[38:39], v[32:33], 0, v[38:39]
	v_lshlrev_b32_e64 v82, 7, v71
	global_store_short_d16_hi v[38:39], v28, off
	v_bfe_u32 v28, v41, 16, 1
	v_or_b32_e64 v40, v82, v63
	v_add3_u32 v28, v41, v28, s27
	v_ashrrev_i32_e64 v41, 31, v40
	v_lshl_add_u64 v[60:61], v[40:41], 1, s[8:9]
	global_store_short_d16_hi v[60:61], v28, off
	v_add_u32_e64 v60, s29, v70
	v_ashrrev_i32_e64 v61, 31, v60
	v_bfe_u32 v28, v108, 16, 1
	v_lshlrev_b64 v[60:61], 11, v[60:61]
	v_lshlrev_b32_e64 v83, 7, v70
	v_add3_u32 v28, v108, v28, s27
	v_lshl_add_u64 v[60:61], v[32:33], 0, v[60:61]
	v_or_b32_e64 v70, v83, v63
	global_store_short_d16_hi v[60:61], v28, off
	v_bfe_u32 v28, v42, 16, 1
	v_ashrrev_i32_e64 v71, 31, v70
	v_add3_u32 v28, v42, v28, s27
	v_lshl_add_u64 v[72:73], v[70:71], 1, s[8:9]
	global_store_short_d16_hi v[72:73], v28, off
	v_add_u32_e64 v72, s29, v69
	v_ashrrev_i32_e64 v73, 31, v72
	v_bfe_u32 v28, v109, 16, 1
	v_lshlrev_b64 v[72:73], 11, v[72:73]
	v_add3_u32 v28, v109, v28, s27
	v_lshl_add_u64 v[72:73], v[32:33], 0, v[72:73]
	v_lshlrev_b32_e64 v84, 7, v69
; __device__ __forceinline__ bf16_t f2bf(float f) { unsigned u = __float_as_uint(f); u += 0x7FFFu + ((u >> 16) & 1u); return (bf16_t)(u >> 16); }
; __device__ __forceinline__ void ret_unit_a(PR P, LAS unsigned char* lds, const int bh, const int n, const int wv) {
;     ...
;     for (int mt = 0; mt < 2; ++mt)
; #pragma unroll
;         for (int nt = 0; nt < 4; ++nt)
; #pragma unroll
;             for (int j = 0; j < 4; ++j) { const int r = wr * 32 + mt * 16 + fq * 4 + j, c = wc * 64 + nt * 16 + fr;
;                 Y[(size_t)(row0 + r) * 1024 + 512 + h * 128 + c] = f2bf(accY[mt][nt][j]); KVB[r * 128 + c] = f2bf(accS[mt][nt][j]); }
	global_store_short_d16_hi v[72:73], v28, off
	v_bfe_u32 v28, v43, 16, 1
	v_or_b32_e64 v42, v84, v63
	v_add3_u32 v28, v43, v28, s27
	v_ashrrev_i32_e64 v43, 31, v42
	v_lshl_add_u64 v[68:69], v[42:43], 1, s[8:9]
	global_store_short_d16_hi v[68:69], v28, off
	v_bfe_u32 v28, v44, 16, 1
	v_add3_u32 v28, v44, v28, s27
	global_store_short_d16_hi v[34:35], v28, off offset:32
	v_bfe_u32 v28, v48, 16, 1
	v_ashrrev_i32_e64 v37, 31, v62
	v_add3_u32 v28, v48, v28, s27
	v_lshl_add_u64 v[36:37], v[36:37], 1, s[8:9]
	global_store_short_d16_hi v[36:37], v28, off offset:32
	v_bfe_u32 v28, v45, 16, 1
	v_add3_u32 v28, v45, v28, s27
	global_store_short_d16_hi v[38:39], v28, off offset:32
	v_bfe_u32 v28, v49, 16, 1
	v_ashrrev_i32_e64 v41, 31, v82
	v_add3_u32 v28, v49, v28, s27
	v_lshl_add_u64 v[40:41], v[40:41], 1, s[8:9]
	global_store_short_d16_hi v[40:41], v28, off offset:32
	v_bfe_u32 v28, v46, 16, 1
	v_add3_u32 v28, v46, v28, s27
	global_store_short_d16_hi v[60:61], v28, off offset:32
	v_bfe_u32 v28, v50, 16, 1
	v_ashrrev_i32_e64 v71, 31, v83
	v_add3_u32 v28, v50, v28, s27
	v_lshl_add_u64 v[44:45], v[70:71], 1, s[8:9]
	global_store_short_d16_hi v[44:45], v28, off offset:32
	v_bfe_u32 v28, v47, 16, 1
	v_add3_u32 v28, v47, v28, s27
	global_store_short_d16_hi v[72:73], v28, off offset:32
	v_bfe_u32 v28, v51, 16, 1
	v_ashrrev_i32_e64 v43, 31, v84
	v_add3_u32 v28, v51, v28, s27
	v_lshl_add_u64 v[42:43], v[42:43], 1, s[8:9]
	global_store_short_d16_hi v[42:43], v28, off offset:32
	v_bfe_u32 v28, v78, 16, 1
	v_add3_u32 v28, v78, v28, s27
	global_store_short_d16_hi v[34:35], v28, off offset:64
	v_bfe_u32 v28, v90, 16, 1
	v_add3_u32 v28, v90, v28, s27
	global_store_short_d16_hi v[36:37], v28, off offset:64
	v_bfe_u32 v28, v79, 16, 1
	v_add3_u32 v28, v79, v28, s27
	global_store_short_d16_hi v[38:39], v28, off offset:64
	v_bfe_u32 v28, v91, 16, 1
	v_add3_u32 v28, v91, v28, s27
	global_store_short_d16_hi v[40:41], v28, off offset:64
	v_bfe_u32 v28, v80, 16, 1
	v_add3_u32 v28, v80, v28, s27
	global_store_short_d16_hi v[60:61], v28, off offset:64
	v_bfe_u32 v28, v92, 16, 1
	v_add3_u32 v28, v92, v28, s27
	global_store_short_d16_hi v[44:45], v28, off offset:64
	v_bfe_u32 v28, v81, 16, 1
	v_add3_u32 v28, v81, v28, s27
	global_store_short_d16_hi v[72:73], v28, off offset:64
	v_bfe_u32 v28, v93, 16, 1
	v_add3_u32 v28, v93, v28, s27
	global_store_short_d16_hi v[42:43], v28, off offset:64
	v_bfe_u32 v28, v52, 16, 1
	v_add3_u32 v28, v52, v28, s27
	global_store_short_d16_hi v[34:35], v28, off offset:96
	v_bfe_u32 v28, v74, 16, 1
	v_add3_u32 v28, v74, v28, s27
	global_store_short_d16_hi v[36:37], v28, off offset:96
	v_bfe_u32 v28, v53, 16, 1
	v_add3_u32 v28, v53, v28, s27
	global_store_short_d16_hi v[38:39], v28, off offset:96
	v_bfe_u32 v28, v75, 16, 1
	v_add3_u32 v28, v75, v28, s27
	global_store_short_d16_hi v[40:41], v28, off offset:96
	v_bfe_u32 v28, v54, 16, 1
	v_add3_u32 v28, v54, v28, s27
	global_store_short_d16_hi v[60:61], v28, off offset:96
	v_bfe_u32 v28, v76, 16, 1
	v_add3_u32 v28, v76, v28, s27
	global_store_short_d16_hi v[44:45], v28, off offset:96
	v_bfe_u32 v28, v55, 16, 1
	v_add3_u32 v28, v55, v28, s27
	global_store_short_d16_hi v[72:73], v28, off offset:96
	v_bfe_u32 v28, v77, 16, 1
	v_add_u32_e64 v34, s29, v67
	v_add3_u32 v28, v77, v28, s27
	v_ashrrev_i32_e64 v35, 31, v34
	global_store_short_d16_hi v[42:43], v28, off offset:96
	v_bfe_u32 v28, v118, 16, 1
	v_lshlrev_b64 v[34:35], 11, v[34:35]
	v_add3_u32 v28, v118, v28, s27
	v_lshl_add_u64 v[34:35], v[32:33], 0, v[34:35]
	global_store_short_d16_hi v[34:35], v28, off
	v_bfe_u32 v28, v24, 16, 1
	v_add3_u32 v24, v24, v28, s27
	v_lshlrev_b32_e64 v28, 7, v67
	v_or_b32_e64 v36, v28, v63
	v_ashrrev_i32_e64 v37, 31, v36
	v_lshl_add_u64 v[38:39], v[36:37], 1, s[8:9]
	global_store_short_d16_hi v[38:39], v24, off
	v_add_u32_e64 v38, s29, v66
	v_ashrrev_i32_e64 v39, 31, v38
	v_bfe_u32 v24, v119, 16, 1
	v_lshlrev_b64 v[38:39], 11, v[38:39]
	v_add3_u32 v24, v119, v24, s27
	v_lshl_add_u64 v[38:39], v[32:33], 0, v[38:39]
	global_store_short_d16_hi v[38:39], v24, off
	v_bfe_u32 v24, v25, 16, 1
	v_lshlrev_b32_e64 v46, 7, v66
	v_add3_u32 v37, v25, v24, s27
	v_or_b32_e64 v24, v46, v63
	v_ashrrev_i32_e64 v25, 31, v24
	v_lshl_add_u64 v[40:41], v[24:25], 1, s[8:9]
	global_store_short_d16_hi v[40:41], v37, off
	v_add_u32_e64 v40, s29, v65
	v_ashrrev_i32_e64 v41, 31, v40
	v_bfe_u32 v25, v120, 16, 1
	v_lshlrev_b64 v[40:41], 11, v[40:41]
	v_lshlrev_b32_e64 v47, 7, v65
	v_add3_u32 v25, v120, v25, s27
	v_lshl_add_u64 v[40:41], v[32:33], 0, v[40:41]
	v_or_b32_e64 v42, v47, v63
	global_store_short_d16_hi v[40:41], v25, off
	v_bfe_u32 v25, v26, 16, 1
	v_ashrrev_i32_e64 v43, 31, v42
	v_add3_u32 v25, v26, v25, s27
	v_lshl_add_u64 v[44:45], v[42:43], 1, s[8:9]
	global_store_short_d16_hi v[44:45], v25, off
	v_add_u32_e64 v44, s29, v64
	v_ashrrev_i32_e64 v45, 31, v44
	v_bfe_u32 v25, v121, 16, 1
	v_lshlrev_b64 v[44:45], 11, v[44:45]
	v_add3_u32 v25, v121, v25, s27
	v_lshl_add_u64 v[32:33], v[32:33], 0, v[44:45]
	v_lshlrev_b32_e64 v48, 7, v64
	global_store_short_d16_hi v[32:33], v25, off
	v_bfe_u32 v25, v27, 16, 1
	v_or_b32_e64 v26, v48, v63
	v_add3_u32 v25, v27, v25, s27
	v_ashrrev_i32_e64 v27, 31, v26
	v_lshl_add_u64 v[44:45], v[26:27], 1, s[8:9]
	global_store_short_d16_hi v[44:45], v25, off
	v_bfe_u32 v25, v20, 16, 1
; __device__ __forceinline__ int fresh_tid(int wv) { int l; asm volatile("v_mbcnt_lo_u32_b32 %0, -1, 0\n\tv_mbcnt_hi_u32_b32 %0, -1, %0" : "=v"(l)); return wv * 64 + l; }
; __device__ __forceinline__ bf16_t f2bf(float f) { unsigned u = __float_as_uint(f); u += 0x7FFFu + ((u >> 16) & 1u); return (bf16_t)(u >> 16); }
; __device__ __forceinline__ unsigned xb_ld(unsigned* p)              { return __hip_atomic_load(p, __ATOMIC_RELAXED, __HIP_MEMORY_SCOPE_AGENT); }
; __device__ __forceinline__ unsigned xb_add(unsigned* p, unsigned v) { return __hip_atomic_fetch_add(p, v, __ATOMIC_RELAXED, __HIP_MEMORY_SCOPE_AGENT); }
; __device__ __forceinline__ void ret_unit_a(PR P, LAS unsigned char* lds, const int bh, const int n, const int wv) {
;     ...
;     for (int mt = 0; mt < 2; ++mt)
; #pragma unroll
;         for (int nt = 0; nt < 4; ++nt)
; #pragma unroll
;             for (int j = 0; j < 4; ++j) { const int r = wr * 32 + mt * 16 + fq * 4 + j, c = wc * 64 + nt * 16 + fr;
;                 Y[(size_t)(row0 + r) * 1024 + 512 + h * 128 + c] = f2bf(accY[mt][nt][j]); KVB[r * 128 + c] = f2bf(accS[mt][nt][j]); }
; __device__ __forceinline__ void sub_barrier(unsigned* cnt, const unsigned target, const int wv) {
;     asm volatile("s_waitcnt vmcnt(0)" ::: "memory");
;     __syncthreads();
;     if (fresh_tid(wv) == 0) {
;         __builtin_amdgcn_fence(__ATOMIC_RELEASE, "agent");
;         asm volatile("s_waitcnt vmcnt(0)" ::: "memory");
;         (void)xb_add(cnt, 1u);
;         unsigned sp = 0u;
;         while (xb_ld(cnt) < target) { __builtin_amdgcn_s_sleep(2); if (++sp > (1u << 20)) break; }
;         __builtin_amdgcn_fence(__ATOMIC_ACQUIRE, "agent");
;         asm volatile("s_waitcnt vmcnt(0)" ::: "memory");
;     }
;     __syncthreads();
; }
	v_add3_u32 v20, v20, v25, s27
	global_store_short_d16_hi v[34:35], v20, off offset:32
	v_bfe_u32 v20, v16, 16, 1
	v_ashrrev_i32_e64 v37, 31, v28
	v_add3_u32 v16, v16, v20, s27
	v_lshl_add_u64 v[36:37], v[36:37], 1, s[8:9]
	global_store_short_d16_hi v[36:37], v16, off offset:32
	v_bfe_u32 v16, v21, 16, 1
	v_add3_u32 v16, v21, v16, s27
	global_store_short_d16_hi v[38:39], v16, off offset:32
	v_bfe_u32 v16, v17, 16, 1
	v_ashrrev_i32_e64 v25, 31, v46
	v_add3_u32 v20, v17, v16, s27
	v_lshl_add_u64 v[16:17], v[24:25], 1, s[8:9]
	global_store_short_d16_hi v[16:17], v20, off offset:32
	v_bfe_u32 v20, v22, 16, 1
	v_add3_u32 v20, v22, v20, s27
	global_store_short_d16_hi v[40:41], v20, off offset:32
	v_bfe_u32 v20, v18, 16, 1
	v_ashrrev_i32_e64 v43, 31, v47
	v_add3_u32 v18, v18, v20, s27
	v_lshl_add_u64 v[20:21], v[42:43], 1, s[8:9]
	global_store_short_d16_hi v[20:21], v18, off offset:32
	v_bfe_u32 v18, v23, 16, 1
	v_add3_u32 v18, v23, v18, s27
	global_store_short_d16_hi v[32:33], v18, off offset:32
	v_bfe_u32 v18, v19, 16, 1
	v_ashrrev_i32_e64 v27, 31, v48
	v_add3_u32 v22, v19, v18, s27
	v_lshl_add_u64 v[18:19], v[26:27], 1, s[8:9]
	global_store_short_d16_hi v[18:19], v22, off offset:32
	v_bfe_u32 v22, v12, 16, 1
	v_add3_u32 v12, v12, v22, s27
	global_store_short_d16_hi v[34:35], v12, off offset:64
	v_bfe_u32 v12, v8, 16, 1
	v_add3_u32 v8, v8, v12, s27
	global_store_short_d16_hi v[36:37], v8, off offset:64
	v_bfe_u32 v8, v13, 16, 1
	v_add3_u32 v8, v13, v8, s27
	global_store_short_d16_hi v[38:39], v8, off offset:64
	v_bfe_u32 v8, v9, 16, 1
	v_add3_u32 v8, v9, v8, s27
	global_store_short_d16_hi v[16:17], v8, off offset:64
	v_bfe_u32 v8, v14, 16, 1
	v_add3_u32 v8, v14, v8, s27
	global_store_short_d16_hi v[40:41], v8, off offset:64
	v_bfe_u32 v8, v10, 16, 1
	v_add3_u32 v8, v10, v8, s27
	global_store_short_d16_hi v[20:21], v8, off offset:64
	v_bfe_u32 v8, v15, 16, 1
	v_add3_u32 v8, v15, v8, s27
	global_store_short_d16_hi v[32:33], v8, off offset:64
	v_bfe_u32 v8, v11, 16, 1
	v_add3_u32 v8, v11, v8, s27
	global_store_short_d16_hi v[18:19], v8, off offset:64
	v_bfe_u32 v8, v4, 16, 1
	v_add3_u32 v4, v4, v8, s27
	global_store_short_d16_hi v[34:35], v4, off offset:96
	v_bfe_u32 v4, v0, 16, 1
	v_add3_u32 v0, v0, v4, s27
	global_store_short_d16_hi v[36:37], v0, off offset:96
	v_bfe_u32 v0, v5, 16, 1
	v_add3_u32 v0, v5, v0, s27
	global_store_short_d16_hi v[38:39], v0, off offset:96
	v_bfe_u32 v0, v1, 16, 1
	v_add3_u32 v0, v1, v0, s27
	global_store_short_d16_hi v[16:17], v0, off offset:96
	v_bfe_u32 v0, v6, 16, 1
	v_add3_u32 v0, v6, v0, s27
	global_store_short_d16_hi v[40:41], v0, off offset:96
	v_bfe_u32 v0, v2, 16, 1
	v_add3_u32 v0, v2, v0, s27
	global_store_short_d16_hi v[20:21], v0, off offset:96
	v_bfe_u32 v0, v7, 16, 1
	v_add3_u32 v0, v7, v0, s27
	global_store_short_d16_hi v[32:33], v0, off offset:96
	v_bfe_u32 v0, v3, 16, 1
	s_addk_i32 s55, 0x80
	s_nop 0
	v_add3_u32 v0, v3, v0, s27
	s_cmpk_eq_i32 s55, 0x180
	s_nop 0
	global_store_short_d16_hi v[18:19], v0, off offset:96
	s_waitcnt vmcnt(63) expcnt(7) lgkmcnt(15)
	s_barrier
	s_cbranch_scc0 .LBB0_618
	s_waitcnt vmcnt(0)
	s_add_u32 s12, s10, 0x3700
	s_addc_u32 s13, s11, 0
	s_barrier
	v_mbcnt_lo_u32_b32 v0, -1, 0
	v_mbcnt_hi_u32_b32 v0, -1, v0
	s_nop 0
	s_nop 0
	v_cmp_eq_u32_e64 vcc, s74, v0
	s_and_saveexec_b64 s[8:9], vcc
	s_cbranch_execz .LBB0_636
	s_mov_b64 s[18:19], exec
	s_nop 0
	buffer_wbl2 sc1
	buffer_inv sc1
	s_waitcnt vmcnt(0)
	s_waitcnt vmcnt(0)
	v_mbcnt_lo_u32_b32 v0, s18, 0
	v_mbcnt_hi_u32_b32 v0, s19, v0
	v_cmp_eq_u32_e64 vcc, 0, v0
	s_and_saveexec_b64 s[20:21], vcc
	s_cbranch_execz .LBB0_622
	s_bcnt1_i32_b64 s18, s[18:19]
	s_nop 0
	v_mov_b32_e64 v0, 0
	v_mov_b32_e64 v1, s18
	global_atomic_add v0, v1, s[12:13]
	.p2alignl 3, 3212836864
.LBB0_622:
	s_or_b64 exec, exec, s[20:21]
	s_nop 0
	s_mov_b32 s21, 0x100000
	v_mov_b32_e64 v0, 0
	s_movk_i32 s20, 0x7f
	s_movk_i32 s22, 0x80
	s_branch .LBB0_625
	.p2alignl 3, 3212836864
.LBB0_623:
	.p2alignl 3, 3212836864
.LBB0_624:
	s_and_b64 vcc, exec, s[18:19]
	s_cbranch_vccnz .LBB0_635
	.p2alignl 3, 3212836864
.LBB0_625:
	global_load_dword v1, v0, s[12:13] sc1
	s_mov_b64 s[18:19], -1
	s_waitcnt vmcnt(0)
	v_cmp_lt_u32_e64 vcc, s20, v1
	s_cbranch_vccnz .LBB0_624
	s_cmp_lg_u32 s21, 0
	s_sleep 2
	s_cbranch_scc0 .LBB0_623
	global_load_dword v1, v0, s[12:13] sc1
	s_waitcnt vmcnt(0)
	s_nop 0
	v_cmp_gt_u32_e64 vcc, s22, v1
	s_cbranch_vccz .LBB0_624
	s_sleep 2
	global_load_dword v1, v0, s[12:13] sc1
	s_waitcnt vmcnt(0)
	s_nop 0
	v_cmp_gt_u32_e64 vcc, s22, v1
	s_cbranch_vccz .LBB0_624
	s_sleep 2
	global_load_dword v1, v0, s[12:13] sc1
	s_waitcnt vmcnt(0)
	s_nop 0
	v_cmp_gt_u32_e64 vcc, s22, v1
	s_cbranch_vccz .LBB0_624
	s_sleep 2
	global_load_dword v1, v0, s[12:13] sc1
	s_waitcnt vmcnt(0)
	s_nop 0
	v_cmp_gt_u32_e64 vcc, s22, v1
	s_cbranch_vccz .LBB0_624
	s_sleep 2
	global_load_dword v1, v0, s[12:13] sc1
	s_waitcnt vmcnt(0)
	s_nop 0
	v_cmp_gt_u32_e64 vcc, s22, v1
	s_cbranch_vccz .LBB0_624
	s_sleep 2
	global_load_dword v1, v0, s[12:13] sc1
	s_waitcnt vmcnt(0)
	s_nop 0
	v_cmp_gt_u32_e64 vcc, s22, v1
	s_cbranch_vccz .LBB0_624
	s_sleep 2
	global_load_dword v1, v0, s[12:13] sc1
	s_waitcnt vmcnt(0)
	s_nop 0
	v_cmp_gt_u32_e64 vcc, s22, v1
	s_cbranch_vccz .LBB0_624
	s_sleep 2
	s_add_i32 s21, s21, -8
	s_mov_b64 s[18:19], 0
	s_branch .LBB0_624
	.p2alignl 3, 3212836864

; __device__ __forceinline__ unsigned cvt_pk_bf16(float lo, float hi) { const f32x2_t v = {lo, hi}; const bf16x2_t b = __builtin_convertvector(v, bf16x2_t); return __builtin_bit_cast(unsigned, b); }
; __device__ __forceinline__ float lo_bf(unsigned x) { return __uint_as_float(x << 16); }
; __device__ __forceinline__ float hi_bf(unsigned x) { return __uint_as_float(x & 0xffff0000u); }
; __device__ __forceinline__ bf16_t* kvb_ptr(unsigned char* ws, int bh) { return (bf16_t*)(bh < 29 ? ws + WS_LA + (size_t)bh * 524288 : ws + WS_WIN + 17301504 + (size_t)(bh - 29) * 524288); }
; __device__ __forceinline__ void ret_prefix(PR P, const int item) {
;     const int bh = item >> 11, i8 = (item & 2047) * 8; const int h = bh & 3;
;     bf16_t* KVB = kvb_ptr(P.ws, bh) + i8;
;     const float lg2 = log2f(1.0f - exp2f(-5.0f - (float)h)); const float c_dec = exp2f(lg2 * 128.0f);
;     u32x4 kv[16];
; #pragma unroll
;     for (int n = 0; n < 16; ++n) kv[n] = *(const u32x4*)(KVB + (size_t)n * 16384);
;     float S[8];
; #pragma unroll
;     for (int x = 0; x < 8; ++x) S[x] = 0.f;
; #pragma unroll
;     for (int n = 0; n < 16; ++n) { u32x4 w; w.x = pg8::cvt_pk_bf16(S[0], S[1]); w.y = pg8::cvt_pk_bf16(S[2], S[3]); w.z = pg8::cvt_pk_bf16(S[4], S[5]); w.w = pg8::cvt_pk_bf16(S[6], S[7]);
;         *(u32x4*)(KVB + (size_t)n * 16384) = w;
;         const float k8[8] = {lo_bf(kv[n].x), hi_bf(kv[n].x), lo_bf(kv[n].y), hi_bf(kv[n].y), lo_bf(kv[n].z), hi_bf(kv[n].z), lo_bf(kv[n].w), hi_bf(kv[n].w)};
; #pragma unroll
;         for (int x = 0; x < 8; ++x) S[x] = S[x] * c_dec + k8[x]; }
.LBB0_636:
	s_or_b64 exec, exec, s[8:9]
	s_lshl_b32 s8, s49, 9
	s_add_i32 s8, s33, s8
	s_barrier
	v_mbcnt_lo_u32_b32 v66, -1, 0
	v_mbcnt_hi_u32_b32 v66, -1, v66
	v_mov_b32_e32 v4, 0xcb64800
	v_add_u32_e64 v47, s8, v66
	v_ashrrev_i32_e64 v44, 11, v47
	v_subrev_u32_e64 v0, 29, v44
	v_cmp_gt_i32_e64 vcc, 29, v44
	v_ashrrev_i32_e64 v45, 31, v44
	v_mov_b32_e64 v1, 0
	v_cndmask_b32_e64 v2, v0, v44, vcc
	v_mov_b32_e32 v0, 0x1444800
	v_cndmask_b32_e64 v3, 0, v45, vcc
	v_cndmask_b32_e64 v0, v0, v4, vcc
	v_and_b32_e64 v6, 3, v44
	v_lshl_add_u64 v[4:5], s[10:11], 0, v[0:1]
	v_lshlrev_b64 v[2:3], 19, v[2:3]
	v_lshl_add_u64 v[2:3], v[4:5], 0, v[2:3]
	v_cvt_f32_ubyte0_e64 v4, v6
	v_sub_f32_e32 v4, 0xc0a00000, v4
	s_mov_b32 s18, 0xc2fc0000
	v_mov_b32_e32 v5, 0x42800000
	v_cmp_gt_f32_e64 vcc, s18, v4
	v_not_b32_e64 v46, 63
	v_lshlrev_b32_e64 v0, 4, v47
	v_cndmask_b32_e64 v6, 0, v5, vcc
	v_add_f32_e64 v4, v4, v6
	v_exp_f32_e64 v4, v4
	v_cndmask_b32_e64 v6, 0, v46, vcc
	v_and_b32_e32 v0, 0x7ff0, v0
	s_mov_b32 s19, 0x800000
	v_ldexp_f32 v4, v4, v6
	v_sub_f32_e64 v4, 1.0, v4
	v_cmp_gt_f32_e64 vcc, s19, v4
	v_lshl_add_u64 v[92:93], v[2:3], 0, v[0:1]
	v_mov_b32_e32 v0, 0x42000000
	s_mov_b32 s19, 0x8000
	v_cndmask_b32_e64 v6, 0, 32, vcc
	v_cndmask_b32_e64 v0, 0, v0, vcc
	v_add_co_u32_e64 v94, vcc, s19, v92
	s_load_dwordx2 s[8:9], s[38:39], 0xd0
	s_nop 0
	s_nop 0
	v_addc_co_u32_e64 v95, vcc, 0, v93, vcc
	global_load_dwordx4 v[68:71], v[92:93], off
	global_load_dwordx4 v[72:75], v[94:95], off
	s_mov_b32 s19, 0x10000
	v_add_co_u32_e64 v96, vcc, s19, v92
	s_mov_b32 s19, 0x18000
	s_nop 0
	s_nop 0
	v_addc_co_u32_e64 v97, vcc, 0, v93, vcc
	v_add_co_u32_e64 v98, vcc, s19, v92
	s_mov_b32 s19, 0x20000
	s_nop 0
	s_nop 0
	v_addc_co_u32_e64 v99, vcc, 0, v93, vcc
	global_load_dwordx4 v[76:79], v[96:97], off
	global_load_dwordx4 v[80:83], v[98:99], off
	v_add_co_u32_e64 v100, vcc, s19, v92
	s_mov_b32 s19, 0x28000
	s_nop 0
	s_nop 0
	v_addc_co_u32_e64 v101, vcc, 0, v93, vcc
	v_add_co_u32_e64 v102, vcc, s19, v92
	s_mov_b32 s19, 0x30000
	s_nop 0
	s_nop 0
	v_addc_co_u32_e64 v103, vcc, 0, v93, vcc
	global_load_dwordx4 v[84:87], v[100:101], off
	global_load_dwordx4 v[88:91], v[102:103], off
	v_add_co_u32_e64 v104, vcc, s19, v92
	s_mov_b32 s19, 0x38000
	s_nop 0
	s_nop 0
	v_addc_co_u32_e64 v105, vcc, 0, v93, vcc
	v_add_co_u32_e64 v64, vcc, s19, v92
	s_mov_b32 s19, 0x40000
	s_nop 0
	s_nop 0
	v_addc_co_u32_e64 v65, vcc, 0, v93, vcc
	global_load_dwordx4 v[40:43], v[104:105], off
	global_load_dwordx4 v[36:39], v[64:65], off
	v_add_co_u32_e64 v62, vcc, s19, v92
	s_mov_b32 s19, 0x48000
	s_nop 0
	s_nop 0
	v_addc_co_u32_e64 v63, vcc, 0, v93, vcc
	v_add_co_u32_e64 v60, vcc, s19, v92
	s_mov_b32 s19, 0x50000
	s_nop 0
	s_nop 0
	v_addc_co_u32_e64 v61, vcc, 0, v93, vcc
	global_load_dwordx4 v[32:35], v[62:63], off
	global_load_dwordx4 v[28:31], v[60:61], off
	v_add_co_u32_e64 v58, vcc, s19, v92
	s_mov_b32 s19, 0x58000
	s_nop 0
	s_nop 0
	v_addc_co_u32_e64 v59, vcc, 0, v93, vcc
	v_add_co_u32_e64 v56, vcc, s19, v92
	s_mov_b32 s19, 0x60000
	s_nop 0
	s_nop 0
	v_addc_co_u32_e64 v57, vcc, 0, v93, vcc
	global_load_dwordx4 v[24:27], v[58:59], off
	global_load_dwordx4 v[20:23], v[56:57], off
	v_add_co_u32_e64 v54, vcc, s19, v92
	s_mov_b32 s19, 0x68000
	s_nop 0
	s_nop 0
	v_addc_co_u32_e64 v55, vcc, 0, v93, vcc
	v_ldexp_f32 v4, v4, v6
	v_add_co_u32_e64 v52, vcc, s19, v92
	v_log_f32_e64 v4, v4
	s_nop 0
	s_nop 0
	v_addc_co_u32_e64 v53, vcc, 0, v93, vcc
	global_load_dwordx4 v[16:19], v[54:55], off
	global_load_dwordx4 v[12:15], v[52:53], off
	s_mov_b32 s19, 0x70000
	v_add_co_u32_e64 v50, vcc, s19, v92
	s_mov_b32 s19, 0x78000
	s_nop 0
	s_nop 0
	v_addc_co_u32_e64 v51, vcc, 0, v93, vcc
	v_sub_f32_e64 v0, v4, v0
	v_add_co_u32_e64 v48, vcc, s19, v92
	v_mul_f32_e32 v2, 0x43000000, v0
	s_nop 0
	s_nop 0
	v_addc_co_u32_e64 v49, vcc, 0, v93, vcc
	v_cmp_gt_f32_e64 vcc, s18, v2
	v_mov_b32_e64 v3, v1
	s_mov_b32 s18, 0x4308000
	v_cndmask_b32_e64 v2, 0, v5, vcc
	v_fmac_f32_e32 v2, 0x43000000, v0
	v_exp_f32_e64 v0, v2
	global_load_dwordx4 v[8:11], v[50:51], off
	global_load_dwordx4 v[4:7], v[48:49], off
	v_cndmask_b32_e64 v2, 0, v46, vcc
	v_ldexp_f32 v46, v0, v2
	v_mov_b32_e64 v0, v1
	v_mov_b32_e64 v2, v1
	global_store_dwordx4 v[92:93], v[0:3], off
	s_nop 1
	s_nop 0
	v_mul_f32_e64 v0, 0, v46
	s_waitcnt vmcnt(16)
	s_nop 0
	v_lshlrev_b32_e64 v2, 16, v68
	v_and_b32_e32 v3, 0xffff0000, v68
	v_lshlrev_b32_e64 v68, 16, v69
	v_and_b32_e32 v69, 0xffff0000, v69
	v_pk_add_f32 v[92:93], v[0:1], v[68:69] op_sel_hi:[0,1]
	v_lshlrev_b32_e64 v68, 16, v70
	v_and_b32_e32 v69, 0xffff0000, v70
	v_pk_add_f32 v[106:107], v[0:1], v[68:69] op_sel_hi:[0,1]
	v_lshlrev_b32_e64 v68, 16, v71
	v_and_b32_e32 v69, 0xffff0000, v71
	v_pk_add_f32 v[2:3], v[0:1], v[2:3] op_sel_hi:[0,1]
	v_pk_add_f32 v[108:109], v[0:1], v[68:69] op_sel_hi:[0,1]
	v_cvt_pk_bf16_f32 v68, v2, v3
	v_cvt_pk_bf16_f32 v69, v92, v93
	v_cvt_pk_bf16_f32 v70, v106, v107
	v_cvt_pk_bf16_f32 v71, v108, v109
	global_store_dwordx4 v[94:95], v[68:71], off
	v_lshlrev_b32_e64 v0, 12, v66
	v_and_b32_e32 v0, 0xf000, v0
	s_waitcnt vmcnt(16)
	s_nop 0
	v_lshlrev_b32_e64 v68, 16, v72
	v_and_b32_e32 v69, 0xffff0000, v72
	v_pk_fma_f32 v[2:3], v[46:47], v[2:3], v[68:69] op_sel_hi:[0,1,1]
	v_lshlrev_b32_e64 v68, 16, v73
	v_and_b32_e32 v69, 0xffff0000, v73
	v_pk_fma_f32 v[72:73], v[46:47], v[92:93], v[68:69] op_sel_hi:[0,1,1]
	v_lshlrev_b32_e64 v68, 16, v74
	v_and_b32_e32 v69, 0xffff0000, v74
	v_pk_fma_f32 v[92:93], v[46:47], v[106:107], v[68:69] op_sel_hi:[0,1,1]
	v_lshlrev_b32_e64 v68, 16, v75
	v_and_b32_e32 v69, 0xffff0000, v75
	v_pk_fma_f32 v[74:75], v[46:47], v[108:109], v[68:69] op_sel_hi:[0,1,1]
	v_cvt_pk_bf16_f32 v68, v2, v3
	v_cvt_pk_bf16_f32 v69, v72, v73
	v_cvt_pk_bf16_f32 v70, v92, v93
	v_cvt_pk_bf16_f32 v71, v74, v75
	global_store_dwordx4 v[96:97], v[68:71], off
	s_waitcnt vmcnt(16)
; __device__ __forceinline__ unsigned cvt_pk_bf16(float lo, float hi) { const f32x2_t v = {lo, hi}; const bf16x2_t b = __builtin_convertvector(v, bf16x2_t); return __builtin_bit_cast(unsigned, b); }
; __device__ __forceinline__ float lo_bf(unsigned x) { return __uint_as_float(x << 16); }
; __device__ __forceinline__ float hi_bf(unsigned x) { return __uint_as_float(x & 0xffff0000u); }
; __device__ __forceinline__ void ret_prefix(PR P, const int item) {
;     ...
;     for (int n = 0; n < 16; ++n) { u32x4 w; w.x = pg8::cvt_pk_bf16(S[0], S[1]); w.y = pg8::cvt_pk_bf16(S[2], S[3]); w.z = pg8::cvt_pk_bf16(S[4], S[5]); w.w = pg8::cvt_pk_bf16(S[6], S[7]);
;         *(u32x4*)(KVB + (size_t)n * 16384) = w;
;         const float k8[8] = {lo_bf(kv[n].x), hi_bf(kv[n].x), lo_bf(kv[n].y), hi_bf(kv[n].y), lo_bf(kv[n].z), hi_bf(kv[n].z), lo_bf(kv[n].w), hi_bf(kv[n].w)};
; #pragma unroll
;         for (int x = 0; x < 8; ++x) S[x] = S[x] * c_dec + k8[x]; }
	s_nop 0
	v_lshlrev_b32_e64 v68, 16, v76
	v_and_b32_e32 v69, 0xffff0000, v76
	v_pk_fma_f32 v[2:3], v[46:47], v[2:3], v[68:69] op_sel_hi:[0,1,1]
	v_lshlrev_b32_e64 v68, 16, v77
	v_and_b32_e32 v69, 0xffff0000, v77
	v_pk_fma_f32 v[72:73], v[46:47], v[72:73], v[68:69] op_sel_hi:[0,1,1]
	v_lshlrev_b32_e64 v68, 16, v78
	v_and_b32_e32 v69, 0xffff0000, v78
	v_pk_fma_f32 v[76:77], v[46:47], v[92:93], v[68:69] op_sel_hi:[0,1,1]
	v_lshlrev_b32_e64 v68, 16, v79
	v_and_b32_e32 v69, 0xffff0000, v79
	v_pk_fma_f32 v[74:75], v[46:47], v[74:75], v[68:69] op_sel_hi:[0,1,1]
	v_cvt_pk_bf16_f32 v68, v2, v3
	v_cvt_pk_bf16_f32 v69, v72, v73
	v_cvt_pk_bf16_f32 v70, v76, v77
	v_cvt_pk_bf16_f32 v71, v74, v75
	global_store_dwordx4 v[98:99], v[68:71], off
	s_waitcnt vmcnt(16)
	s_nop 0
	v_lshlrev_b32_e64 v68, 16, v80
	v_and_b32_e32 v69, 0xffff0000, v80
	v_pk_fma_f32 v[2:3], v[46:47], v[2:3], v[68:69] op_sel_hi:[0,1,1]
	v_lshlrev_b32_e64 v68, 16, v81
	v_and_b32_e32 v69, 0xffff0000, v81
	v_pk_fma_f32 v[72:73], v[46:47], v[72:73], v[68:69] op_sel_hi:[0,1,1]
	v_lshlrev_b32_e64 v68, 16, v82
	v_and_b32_e32 v69, 0xffff0000, v82
	v_pk_fma_f32 v[76:77], v[46:47], v[76:77], v[68:69] op_sel_hi:[0,1,1]
	v_lshlrev_b32_e64 v68, 16, v83
	v_and_b32_e32 v69, 0xffff0000, v83
	v_pk_fma_f32 v[74:75], v[46:47], v[74:75], v[68:69] op_sel_hi:[0,1,1]
	v_cvt_pk_bf16_f32 v68, v2, v3
	v_cvt_pk_bf16_f32 v69, v72, v73
	v_cvt_pk_bf16_f32 v70, v76, v77
	v_cvt_pk_bf16_f32 v71, v74, v75
	global_store_dwordx4 v[100:101], v[68:71], off
	s_waitcnt vmcnt(16)
	s_nop 0
	v_lshlrev_b32_e64 v68, 16, v84
	v_and_b32_e32 v69, 0xffff0000, v84
	v_pk_fma_f32 v[2:3], v[46:47], v[2:3], v[68:69] op_sel_hi:[0,1,1]
	v_lshlrev_b32_e64 v68, 16, v85
	v_and_b32_e32 v69, 0xffff0000, v85
	v_pk_fma_f32 v[72:73], v[46:47], v[72:73], v[68:69] op_sel_hi:[0,1,1]
	v_lshlrev_b32_e64 v68, 16, v86
	v_and_b32_e32 v69, 0xffff0000, v86
	v_pk_fma_f32 v[76:77], v[46:47], v[76:77], v[68:69] op_sel_hi:[0,1,1]
	v_lshlrev_b32_e64 v68, 16, v87
	v_and_b32_e32 v69, 0xffff0000, v87
	v_pk_fma_f32 v[74:75], v[46:47], v[74:75], v[68:69] op_sel_hi:[0,1,1]
	v_cvt_pk_bf16_f32 v68, v2, v3
	v_cvt_pk_bf16_f32 v69, v72, v73
	v_cvt_pk_bf16_f32 v70, v76, v77
	v_cvt_pk_bf16_f32 v71, v74, v75
	global_store_dwordx4 v[102:103], v[68:71], off
	s_waitcnt vmcnt(16)
	s_nop 0
	v_lshlrev_b32_e64 v68, 16, v88
	v_and_b32_e32 v69, 0xffff0000, v88
	v_pk_fma_f32 v[2:3], v[46:47], v[2:3], v[68:69] op_sel_hi:[0,1,1]
	v_lshlrev_b32_e64 v68, 16, v89
	v_and_b32_e32 v69, 0xffff0000, v89
	v_pk_fma_f32 v[72:73], v[46:47], v[72:73], v[68:69] op_sel_hi:[0,1,1]
	v_lshlrev_b32_e64 v68, 16, v90
	v_and_b32_e32 v69, 0xffff0000, v90
	v_pk_fma_f32 v[76:77], v[46:47], v[76:77], v[68:69] op_sel_hi:[0,1,1]
	v_lshlrev_b32_e64 v68, 16, v91
	v_and_b32_e32 v69, 0xffff0000, v91
	v_pk_fma_f32 v[74:75], v[46:47], v[74:75], v[68:69] op_sel_hi:[0,1,1]
	v_cvt_pk_bf16_f32 v68, v2, v3
	v_cvt_pk_bf16_f32 v69, v72, v73
	v_cvt_pk_bf16_f32 v70, v76, v77
	v_cvt_pk_bf16_f32 v71, v74, v75
	global_store_dwordx4 v[104:105], v[68:71], off
	s_waitcnt vmcnt(16)
	s_nop 0
	v_lshlrev_b32_e64 v68, 16, v40
	v_and_b32_e32 v69, 0xffff0000, v40
	v_lshlrev_b32_e64 v40, 16, v41
	v_and_b32_e32 v41, 0xffff0000, v41
	v_pk_fma_f32 v[2:3], v[46:47], v[2:3], v[68:69] op_sel_hi:[0,1,1]
	v_pk_fma_f32 v[68:69], v[46:47], v[72:73], v[40:41] op_sel_hi:[0,1,1]
	v_lshlrev_b32_e64 v40, 16, v42
	v_and_b32_e32 v41, 0xffff0000, v42
	v_pk_fma_f32 v[70:71], v[46:47], v[76:77], v[40:41] op_sel_hi:[0,1,1]
	v_lshlrev_b32_e64 v40, 16, v43
	v_and_b32_e32 v41, 0xffff0000, v43
	v_pk_fma_f32 v[72:73], v[46:47], v[74:75], v[40:41] op_sel_hi:[0,1,1]
	v_cvt_pk_bf16_f32 v40, v2, v3
	v_cvt_pk_bf16_f32 v41, v68, v69
	v_cvt_pk_bf16_f32 v42, v70, v71
	v_cvt_pk_bf16_f32 v43, v72, v73
	global_store_dwordx4 v[64:65], v[40:43], off
	s_waitcnt vmcnt(16)
	s_nop 0
	v_lshlrev_b32_e64 v40, 16, v36
	v_and_b32_e32 v41, 0xffff0000, v36
	v_lshlrev_b32_e64 v36, 16, v37
	v_and_b32_e32 v37, 0xffff0000, v37
	v_pk_fma_f32 v[2:3], v[46:47], v[2:3], v[40:41] op_sel_hi:[0,1,1]
	v_pk_fma_f32 v[40:41], v[46:47], v[68:69], v[36:37] op_sel_hi:[0,1,1]
	v_lshlrev_b32_e64 v36, 16, v38
	v_and_b32_e32 v37, 0xffff0000, v38
	v_pk_fma_f32 v[42:43], v[46:47], v[70:71], v[36:37] op_sel_hi:[0,1,1]
	v_lshlrev_b32_e64 v36, 16, v39
	v_and_b32_e32 v37, 0xffff0000, v39
	v_pk_fma_f32 v[64:65], v[46:47], v[72:73], v[36:37] op_sel_hi:[0,1,1]
	v_cvt_pk_bf16_f32 v36, v2, v3
	v_cvt_pk_bf16_f32 v37, v40, v41
	v_cvt_pk_bf16_f32 v38, v42, v43
	v_cvt_pk_bf16_f32 v39, v64, v65
	global_store_dwordx4 v[62:63], v[36:39], off
	s_waitcnt vmcnt(16)
	s_nop 0
	v_lshlrev_b32_e64 v36, 16, v32
	v_and_b32_e32 v37, 0xffff0000, v32
	v_lshlrev_b32_e64 v32, 16, v33
	v_and_b32_e32 v33, 0xffff0000, v33
	v_pk_fma_f32 v[2:3], v[46:47], v[2:3], v[36:37] op_sel_hi:[0,1,1]
	v_pk_fma_f32 v[36:37], v[46:47], v[40:41], v[32:33] op_sel_hi:[0,1,1]
	v_lshlrev_b32_e64 v32, 16, v34
	v_and_b32_e32 v33, 0xffff0000, v34
	v_pk_fma_f32 v[38:39], v[46:47], v[42:43], v[32:33] op_sel_hi:[0,1,1]
	v_lshlrev_b32_e64 v32, 16, v35
	v_and_b32_e32 v33, 0xffff0000, v35
	v_pk_fma_f32 v[40:41], v[46:47], v[64:65], v[32:33] op_sel_hi:[0,1,1]
	v_cvt_pk_bf16_f32 v32, v2, v3
	v_cvt_pk_bf16_f32 v33, v36, v37
	v_cvt_pk_bf16_f32 v34, v38, v39
	v_cvt_pk_bf16_f32 v35, v40, v41
	global_store_dwordx4 v[60:61], v[32:35], off
	s_waitcnt vmcnt(16)
; __device__ __forceinline__ int fresh_tid(int wv) { int l; asm volatile("v_mbcnt_lo_u32_b32 %0, -1, 0\n\tv_mbcnt_hi_u32_b32 %0, -1, %0" : "=v"(l)); return wv * 64 + l; }
; __device__ __forceinline__ unsigned cvt_pk_bf16(float lo, float hi) { const f32x2_t v = {lo, hi}; const bf16x2_t b = __builtin_convertvector(v, bf16x2_t); return __builtin_bit_cast(unsigned, b); }
; __device__ __forceinline__ float lo_bf(unsigned x) { return __uint_as_float(x << 16); }
; __device__ __forceinline__ float hi_bf(unsigned x) { return __uint_as_float(x & 0xffff0000u); }
; __device__ __forceinline__ unsigned xb_add(unsigned* p, unsigned v) { return __hip_atomic_fetch_add(p, v, __ATOMIC_RELAXED, __HIP_MEMORY_SCOPE_AGENT); }
; __device__ __forceinline__ void ret_prefix(PR P, const int item) {
;     ...
;     for (int n = 0; n < 16; ++n) { u32x4 w; w.x = pg8::cvt_pk_bf16(S[0], S[1]); w.y = pg8::cvt_pk_bf16(S[2], S[3]); w.z = pg8::cvt_pk_bf16(S[4], S[5]); w.w = pg8::cvt_pk_bf16(S[6], S[7]);
;         *(u32x4*)(KVB + (size_t)n * 16384) = w;
;         const float k8[8] = {lo_bf(kv[n].x), hi_bf(kv[n].x), lo_bf(kv[n].y), hi_bf(kv[n].y), lo_bf(kv[n].z), hi_bf(kv[n].z), lo_bf(kv[n].w), hi_bf(kv[n].w)};
; #pragma unroll
;         for (int x = 0; x < 8; ++x) S[x] = S[x] * c_dec + k8[x]; }
;     const int e = i8 >> 7, d0 = i8 & 127;
; #pragma unroll
;     for (int x = 0; x < 8; ++x) P.out[O_RTP + ((size_t)bh * 128 + d0 + x) * 128 + e] = S[x];
; __device__ __forceinline__ void sub_barrier(unsigned* cnt, const unsigned target, const int wv) {
;     asm volatile("s_waitcnt vmcnt(0)" ::: "memory");
;     __syncthreads();
;     if (fresh_tid(wv) == 0) {
;         __builtin_amdgcn_fence(__ATOMIC_RELEASE, "agent");
;         asm volatile("s_waitcnt vmcnt(0)" ::: "memory");
;         (void)xb_add(cnt, 1u);
	s_nop 0
	v_lshlrev_b32_e64 v32, 16, v28
	v_and_b32_e32 v33, 0xffff0000, v28
	v_lshlrev_b32_e64 v28, 16, v29
	v_and_b32_e32 v29, 0xffff0000, v29
	v_pk_fma_f32 v[2:3], v[46:47], v[2:3], v[32:33] op_sel_hi:[0,1,1]
	v_pk_fma_f32 v[32:33], v[46:47], v[36:37], v[28:29] op_sel_hi:[0,1,1]
	v_lshlrev_b32_e64 v28, 16, v30
	v_and_b32_e32 v29, 0xffff0000, v30
	v_pk_fma_f32 v[34:35], v[46:47], v[38:39], v[28:29] op_sel_hi:[0,1,1]
	v_lshlrev_b32_e64 v28, 16, v31
	v_and_b32_e32 v29, 0xffff0000, v31
	v_pk_fma_f32 v[36:37], v[46:47], v[40:41], v[28:29] op_sel_hi:[0,1,1]
	v_cvt_pk_bf16_f32 v28, v2, v3
	v_cvt_pk_bf16_f32 v29, v32, v33
	v_cvt_pk_bf16_f32 v30, v34, v35
	v_cvt_pk_bf16_f32 v31, v36, v37
	global_store_dwordx4 v[58:59], v[28:31], off
	s_waitcnt vmcnt(16)
	s_nop 0
	v_lshlrev_b32_e64 v28, 16, v24
	v_and_b32_e32 v29, 0xffff0000, v24
	v_lshlrev_b32_e64 v24, 16, v25
	v_and_b32_e32 v25, 0xffff0000, v25
	v_pk_fma_f32 v[2:3], v[46:47], v[2:3], v[28:29] op_sel_hi:[0,1,1]
	v_pk_fma_f32 v[28:29], v[46:47], v[32:33], v[24:25] op_sel_hi:[0,1,1]
	v_lshlrev_b32_e64 v24, 16, v26
	v_and_b32_e32 v25, 0xffff0000, v26
	v_pk_fma_f32 v[30:31], v[46:47], v[34:35], v[24:25] op_sel_hi:[0,1,1]
	v_lshlrev_b32_e64 v24, 16, v27
	v_and_b32_e32 v25, 0xffff0000, v27
	v_pk_fma_f32 v[32:33], v[46:47], v[36:37], v[24:25] op_sel_hi:[0,1,1]
	v_cvt_pk_bf16_f32 v24, v2, v3
	v_cvt_pk_bf16_f32 v25, v28, v29
	v_cvt_pk_bf16_f32 v26, v30, v31
	v_cvt_pk_bf16_f32 v27, v32, v33
	global_store_dwordx4 v[56:57], v[24:27], off
	s_waitcnt vmcnt(16)
	s_nop 0
	v_lshlrev_b32_e64 v24, 16, v20
	v_and_b32_e32 v25, 0xffff0000, v20
	v_lshlrev_b32_e64 v20, 16, v21
	v_and_b32_e32 v21, 0xffff0000, v21
	v_pk_fma_f32 v[2:3], v[46:47], v[2:3], v[24:25] op_sel_hi:[0,1,1]
	v_pk_fma_f32 v[24:25], v[46:47], v[28:29], v[20:21] op_sel_hi:[0,1,1]
	v_lshlrev_b32_e64 v20, 16, v22
	v_and_b32_e32 v21, 0xffff0000, v22
	v_pk_fma_f32 v[26:27], v[46:47], v[30:31], v[20:21] op_sel_hi:[0,1,1]
	v_lshlrev_b32_e64 v20, 16, v23
	v_and_b32_e32 v21, 0xffff0000, v23
	v_pk_fma_f32 v[28:29], v[46:47], v[32:33], v[20:21] op_sel_hi:[0,1,1]
	v_cvt_pk_bf16_f32 v20, v2, v3
	v_cvt_pk_bf16_f32 v21, v24, v25
	v_cvt_pk_bf16_f32 v22, v26, v27
	v_cvt_pk_bf16_f32 v23, v28, v29
	global_store_dwordx4 v[54:55], v[20:23], off
	s_waitcnt vmcnt(16)
	s_nop 0
	v_lshlrev_b32_e64 v20, 16, v16
	v_and_b32_e32 v21, 0xffff0000, v16
	v_lshlrev_b32_e64 v16, 16, v17
	v_and_b32_e32 v17, 0xffff0000, v17
	v_pk_fma_f32 v[2:3], v[46:47], v[2:3], v[20:21] op_sel_hi:[0,1,1]
	v_pk_fma_f32 v[20:21], v[46:47], v[24:25], v[16:17] op_sel_hi:[0,1,1]
	v_lshlrev_b32_e64 v16, 16, v18
	v_and_b32_e32 v17, 0xffff0000, v18
	v_pk_fma_f32 v[22:23], v[46:47], v[26:27], v[16:17] op_sel_hi:[0,1,1]
	v_lshlrev_b32_e64 v16, 16, v19
	v_and_b32_e32 v17, 0xffff0000, v19
	v_pk_fma_f32 v[24:25], v[46:47], v[28:29], v[16:17] op_sel_hi:[0,1,1]
	v_cvt_pk_bf16_f32 v16, v2, v3
	v_cvt_pk_bf16_f32 v17, v20, v21
	v_cvt_pk_bf16_f32 v18, v22, v23
	v_cvt_pk_bf16_f32 v19, v24, v25
	global_store_dwordx4 v[52:53], v[16:19], off
	s_waitcnt vmcnt(16)
	s_nop 0
	v_lshlrev_b32_e64 v16, 16, v12
	v_and_b32_e32 v17, 0xffff0000, v12
	v_lshlrev_b32_e64 v12, 16, v13
	v_and_b32_e32 v13, 0xffff0000, v13
	v_pk_fma_f32 v[2:3], v[46:47], v[2:3], v[16:17] op_sel_hi:[0,1,1]
	v_pk_fma_f32 v[16:17], v[46:47], v[20:21], v[12:13] op_sel_hi:[0,1,1]
	v_lshlrev_b32_e64 v12, 16, v14
	v_and_b32_e32 v13, 0xffff0000, v14
	v_pk_fma_f32 v[18:19], v[46:47], v[22:23], v[12:13] op_sel_hi:[0,1,1]
	v_lshlrev_b32_e64 v12, 16, v15
	v_and_b32_e32 v13, 0xffff0000, v15
	v_pk_fma_f32 v[20:21], v[46:47], v[24:25], v[12:13] op_sel_hi:[0,1,1]
	v_cvt_pk_bf16_f32 v12, v2, v3
	v_cvt_pk_bf16_f32 v13, v16, v17
	v_cvt_pk_bf16_f32 v14, v18, v19
	v_cvt_pk_bf16_f32 v15, v20, v21
	global_store_dwordx4 v[50:51], v[12:15], off
	s_waitcnt vmcnt(16)
	s_nop 0
	v_lshlrev_b32_e64 v12, 16, v8
	v_and_b32_e32 v13, 0xffff0000, v8
	v_lshlrev_b32_e64 v8, 16, v9
	v_and_b32_e32 v9, 0xffff0000, v9
	v_pk_fma_f32 v[2:3], v[46:47], v[2:3], v[12:13] op_sel_hi:[0,1,1]
	v_pk_fma_f32 v[12:13], v[46:47], v[16:17], v[8:9] op_sel_hi:[0,1,1]
	v_lshlrev_b32_e64 v8, 16, v10
	v_and_b32_e32 v9, 0xffff0000, v10
	v_pk_fma_f32 v[14:15], v[46:47], v[18:19], v[8:9] op_sel_hi:[0,1,1]
	v_lshlrev_b32_e64 v8, 16, v11
	v_and_b32_e32 v9, 0xffff0000, v11
	v_pk_fma_f32 v[16:17], v[46:47], v[20:21], v[8:9] op_sel_hi:[0,1,1]
	v_cvt_pk_bf16_f32 v8, v2, v3
	v_cvt_pk_bf16_f32 v9, v12, v13
	v_cvt_pk_bf16_f32 v10, v14, v15
	v_cvt_pk_bf16_f32 v11, v16, v17
	global_store_dwordx4 v[48:49], v[8:11], off
	s_waitcnt vmcnt(16)
	s_nop 0
	v_lshlrev_b32_e64 v8, 16, v4
	v_and_b32_e32 v4, 0xffff0000, v4
	v_fmac_f32_e64 v8, v46, v2
	v_fmac_f32_e64 v4, v46, v3
	v_lshlrev_b64 v[2:3], 16, v[44:45]
	s_waitcnt lgkmcnt(0)
	s_nop 0
	v_lshl_add_u64 v[2:3], s[8:9], 0, v[2:3]
	v_lshl_add_u64 v[2:3], v[2:3], 0, v[0:1]
	v_lshrrev_b32_e64 v0, 2, v47
	v_and_b32_e32 v0, 0x1fc, v0
	v_lshl_add_u64 v[0:1], v[2:3], 0, v[0:1]
	v_add_co_u32_e64 v0, vcc, s18, v0
	v_lshlrev_b32_e64 v9, 16, v5
	v_and_b32_e32 v5, 0xffff0000, v5
	v_lshlrev_b32_e64 v10, 16, v6
	v_and_b32_e32 v6, 0xffff0000, v6
	v_lshlrev_b32_e64 v11, 16, v7
	v_and_b32_e32 v7, 0xffff0000, v7
	v_addc_co_u32_e64 v1, vcc, 0, v1, vcc
	v_fmac_f32_e64 v9, v46, v12
	v_fmac_f32_e64 v5, v46, v13
	v_fmac_f32_e64 v10, v46, v14
	v_fmac_f32_e64 v6, v46, v15
	v_fmac_f32_e64 v11, v46, v16
	v_fmac_f32_e64 v7, v46, v17
	global_store_dword v[0:1], v8, off
	global_store_dword v[0:1], v4, off offset:512
	global_store_dword v[0:1], v9, off offset:1024
	global_store_dword v[0:1], v5, off offset:1536
	global_store_dword v[0:1], v10, off offset:2048
	global_store_dword v[0:1], v6, off offset:2560
	global_store_dword v[0:1], v11, off offset:3072
	global_store_dword v[0:1], v7, off offset:3584
	s_waitcnt vmcnt(0)
	s_barrier
	v_mbcnt_lo_u32_b32 v0, -1, 0
	v_mbcnt_hi_u32_b32 v0, -1, v0
	s_nop 0
	s_nop 0
	v_cmp_eq_u32_e64 vcc, s74, v0
	s_and_saveexec_b64 s[18:19], vcc
	s_cbranch_execz .LBB0_653
	s_mov_b64 s[20:21], exec
	s_nop 0
	buffer_wbl2 sc1
	buffer_inv sc1
	s_waitcnt vmcnt(0)
	s_waitcnt vmcnt(0)
	v_mbcnt_lo_u32_b32 v0, s20, 0
	v_mbcnt_hi_u32_b32 v0, s21, v0
	v_cmp_eq_u32_e64 vcc, 0, v0
	s_and_saveexec_b64 s[22:23], vcc
	s_cbranch_execz .LBB0_639
	s_bcnt1_i32_b64 s20, s[20:21]
	s_nop 0
	v_mov_b32_e64 v0, 0
	v_mov_b32_e64 v1, s20
	global_atomic_add v0, v1, s[12:13]
	.p2alignl 3, 3212836864
.LBB0_639:
	s_or_b64 exec, exec, s[22:23]
	s_nop 0
	s_mov_b32 s23, 0x100000
	v_mov_b32_e64 v0, 0
	s_movk_i32 s22, 0xff
	s_movk_i32 s24, 0x100
	s_branch .LBB0_642
	.p2alignl 3, 3212836864

; __device__ __forceinline__ unsigned xb_ld(unsigned* p)              { return __hip_atomic_load(p, __ATOMIC_RELAXED, __HIP_MEMORY_SCOPE_AGENT); }
; __device__ __forceinline__ void sub_barrier(unsigned* cnt, const unsigned target, const int wv) {
;     ...
;         unsigned sp = 0u;
;         while (xb_ld(cnt) < target) { __builtin_amdgcn_s_sleep(2); if (++sp > (1u << 20)) break; }
;         __builtin_amdgcn_fence(__ATOMIC_ACQUIRE, "agent");
;         asm volatile("s_waitcnt vmcnt(0)" ::: "memory");
.LBB0_641:
	s_and_b64 vcc, exec, s[20:21]
	s_cbranch_vccnz .LBB0_652
	.p2alignl 3, 3212836864
.LBB0_642:
	global_load_dword v1, v0, s[12:13] sc1
	s_mov_b64 s[20:21], -1
	s_waitcnt vmcnt(0)
	v_cmp_lt_u32_e64 vcc, s22, v1
	s_cbranch_vccnz .LBB0_641
	s_cmp_lg_u32 s23, 0
	s_sleep 2
	s_cbranch_scc0 .LBB0_640
	global_load_dword v1, v0, s[12:13] sc1
	s_waitcnt vmcnt(0)
	s_nop 0
	v_cmp_gt_u32_e64 vcc, s24, v1
	s_cbranch_vccz .LBB0_641
	s_sleep 2
	global_load_dword v1, v0, s[12:13] sc1
	s_waitcnt vmcnt(0)
	s_nop 0
	v_cmp_gt_u32_e64 vcc, s24, v1
	s_cbranch_vccz .LBB0_641
	s_sleep 2
	global_load_dword v1, v0, s[12:13] sc1
	s_waitcnt vmcnt(0)
	s_nop 0
	v_cmp_gt_u32_e64 vcc, s24, v1
	s_cbranch_vccz .LBB0_641
	s_sleep 2
	global_load_dword v1, v0, s[12:13] sc1
	s_waitcnt vmcnt(0)
	s_nop 0
	v_cmp_gt_u32_e64 vcc, s24, v1
	s_cbranch_vccz .LBB0_641
	s_sleep 2
	global_load_dword v1, v0, s[12:13] sc1
	s_waitcnt vmcnt(0)
	s_nop 0
	v_cmp_gt_u32_e64 vcc, s24, v1
	s_cbranch_vccz .LBB0_641
	s_sleep 2
	global_load_dword v1, v0, s[12:13] sc1
	s_waitcnt vmcnt(0)
	s_nop 0
	v_cmp_gt_u32_e64 vcc, s24, v1
	s_cbranch_vccz .LBB0_641
	s_sleep 2
	global_load_dword v1, v0, s[12:13] sc1
	s_waitcnt vmcnt(0)
	s_nop 0
	v_cmp_gt_u32_e64 vcc, s24, v1
	s_cbranch_vccz .LBB0_641
	s_sleep 2
	s_add_i32 s23, s23, -8
	s_mov_b64 s[20:21], 0
	s_branch .LBB0_641
	.p2alignl 3, 3212836864

; #define LAS __attribute__((address_space(3)))
; template <bool WITH_K>
; __device__ __forceinline__ void ret_load_qk(PR P, LAS bf16_t* QP, LAS bf16_t* KB, unsigned (&kth)[4][4], const int tidv, const int row0, const int n, const int h, const float kd0, const float g32) {
;     const bf16_t* PS = (const bf16_t*)(P.ws + WS_BIG); const float* rc = (const float*)(P.ws + WS_ROPE); const float* rs = rc + 2052 * 64;
;     float kd = kd0;
; #pragma unroll
;     for (int it = 0; it < 4; ++it) { const int idx = it * 512 + tidv, i = idx >> 4, f = (idx & 15) * 4;
;         const bf16_t* src = PS + (size_t)(row0 + i) * NCOLS + 1792 + h * 128;
;         const u32x2 q1 = *(const u32x2*)(src + f), q2 = *(const u32x2*)(src + 64 + f);
;         u32x2 k1 = (u32x2){0u, 0u}, k2 = k1; if (WITH_K) { k1 = *(const u32x2*)(src + 512 + f); k2 = *(const u32x2*)(src + 576 + f); }
;         const float4 cs = *(const float4*)(rc + (size_t)(n * 128 + i) * 64 + f), sn = *(const float4*)(rs + (size_t)(n * 128 + i) * 64 + f);
;         const float c4[4] = {cs.x, cs.y, cs.z, cs.w}, s4[4] = {sn.x, sn.y, sn.z, sn.w};
;         const float qa[4] = {lo_bf(q1.x), hi_bf(q1.x), lo_bf(q1.y), hi_bf(q1.y)}, qb[4] = {lo_bf(q2.x), hi_bf(q2.x), lo_bf(q2.y), hi_bf(q2.y)};
;         float qo1[4], qo2[4];
; #pragma unroll
;         for (int x = 0; x < 4; ++x) { qo1[x] = qa[x] * c4[x] - qb[x] * s4[x]; qo2[x] = qa[x] * s4[x] + qb[x] * c4[x]; }
;         u32x2 w; w.x = pg8::cvt_pk_bf16(qo1[0], qo1[1]); w.y = pg8::cvt_pk_bf16(qo1[2], qo1[3]); *(LAS u32x2*)(QP + i * RS + f) = w;
;         w.x = pg8::cvt_pk_bf16(qo2[0], qo2[1]); w.y = pg8::cvt_pk_bf16(qo2[2], qo2[3]); *(LAS u32x2*)(QP + i * RS + 64 + f) = w;
; __device__ __forceinline__ void ret_unit_c(PR P, LAS unsigned char* lds, const int bh, const int n, const int wv) {
;     LAS bf16_t* QP = (LAS bf16_t*)lds; LAS bf16_t* ST = QP + 3 * BUFE; LAS float* YST = (LAS float*)(QP + BUFE);
;     const int tid = fresh_tid(wv), lane = tid & 63, wid = tid >> 6, wr = wid >> 1, wc = wid & 1, fr = lane & 15, fq = lane >> 4;
;     const int b = bh >> 2, h = bh & 3;
;     const bf16_t* PS = (const bf16_t*)(P.ws + WS_BIG); bf16_t* Y = (bf16_t*)(P.ws + WS_XN); const bf16_t* KVB = kvb_ptr(P.ws, bh) + (size_t)n * 16384;
;     const float lg2 = log2f(1.0f - exp2f(-5.0f - (float)h));
;     const int row0 = b * 2048 + n * 128;
.LBB0_653:
	s_or_b64 exec, exec, s[18:19]
	s_barrier
	s_load_dwordx2 s[12:13], s[38:39], 0xa8
	s_movk_i32 s28, 0xff80
	s_mov_b32 s19, 0
	s_mov_b32 s29, 0xcb64800
	s_mov_b32 s30, 0xc2fc0000
	v_mov_b32_e32 v62, 0x42800000
	v_mov_b32_e64 v29, 0
	s_movk_i32 s31, 0x1e00
	s_nop 0
	v_mov_b64_e64 v[30:31], s[10:11]
	s_mov_b64 s[20:21], 0x3d45600
	s_mov_b32 s34, 0x3d45000
	s_movk_i32 s35, 0x110
	s_nop 0
	s_add_i32 s36, 0, 0x19800
	s_mov_b32 s37, 0x800000
	v_mov_b32_e32 v63, 0x42000000
	v_not_b32_e64 v64, 63
	s_movk_i32 s40, 0x210
	s_nop 0
	s_mov_b64 s[22:23], 0x1bc4c00
	s_mov_b32 s41, 0x1bc4000
	s_movk_i32 s42, 0x1600
	s_nop 0
	s_mov_b64 s[24:25], 0x3d46200
	s_mov_b32 s43, 0x3d46000
	v_mov_b32_e32 v65, 0x3727c5ac
	.p2alignl 3, 3212836864
.LBB0_654:
	s_add_i32 s18, s2, s28
	s_ashr_i32 s18, s18, 4
	s_and_b32 s44, s18, 3
	s_sub_i32 s26, s18, 29
	s_ashr_i32 s27, s18, 31
	s_cmp_lt_i32 s18, 29
	s_cselect_b32 s45, s29, 0x1444800
	s_cselect_b32 s27, s27, 0
	s_cselect_b32 s26, s18, s26
	s_add_u32 s45, s10, s45
	s_addc_u32 s46, s11, 0
	s_lshl_b64 s[26:27], s[26:27], 19
	s_add_u32 s26, s45, s26
	s_addc_u32 s27, s46, s27
	s_nop 0
	v_cvt_f32_ubyte0_e64 v0, s44
	s_add_u32 s26, s26, s7
	s_nop 0
	v_sub_f32_e32 v34, 0xc0a00000, v0
	s_addc_u32 s27, s27, 0
	s_nop 0
	v_cmp_gt_f32_e64 vcc, s30, v34
	s_and_b64 s[46:47], vcc, exec
	s_nop 0
	s_cselect_b32 s55, 0xffffffc0, 0
	s_lshl_b32 s18, s18, 9
	s_nop 0
	v_mbcnt_lo_u32_b32 v2, -1, 0
	v_mbcnt_hi_u32_b32 v2, -1, v2
	s_and_b32 s18, s18, 0xfffff800
	v_add_u32_e64 v3, s33, v2
	s_or_b32 s45, s18, s6
	s_nop 0
	v_lshlrev_b32_e64 v0, 2, v2
	v_ashrrev_i32_e64 v46, 4, v3
	v_and_b32_e64 v6, 60, v0
	v_add_u32_e64 v4, s45, v46
	v_lshlrev_b32_e64 v28, 2, v6
	v_mad_i64_i32 v[4:5], s[46:47], v4, s31, v[30:31]
	s_lshl_b32 s18, s44, 8
	s_nop 0
	v_lshl_add_u64 v[0:1], s[14:15], 0, v[28:29]
	v_lshl_add_u64 v[20:21], s[16:17], 0, v[28:29]
	v_lshl_add_u64 v[4:5], v[4:5], 0, s[18:19]
	v_lshlrev_b32_e64 v28, 1, v6
	v_lshl_add_u64 v[4:5], v[4:5], 0, v[28:29]
	v_cndmask_b32_e64 v35, 0, v62, vcc
	v_lshl_add_u64 v[6:7], v[4:5], 0, s[20:21]
	v_add_co_u32_e64 v4, vcc, s34, v4
	v_add_f32_e64 v34, v34, v35
	s_nop 0
	s_nop 0
	v_addc_co_u32_e64 v5, vcc, 0, v5, vcc
	global_load_dwordx2 v[22:23], v[4:5], off offset:1536
	global_load_dwordx2 v[24:25], v[6:7], off offset:128
	v_add_u32_e64 v4, s6, v46
	v_ashrrev_i32_e64 v5, 31, v4
	v_lshlrev_b64 v[8:9], 8, v[4:5]
	v_add_u32_e32 v4, 0x200, v3
	v_ashrrev_i32_e64 v47, 4, v4
	v_add_u32_e64 v4, s45, v47
	v_mad_i64_i32 v[4:5], s[46:47], v4, s31, v[30:31]
	v_lshl_add_u64 v[4:5], v[4:5], 0, s[18:19]
	v_lshl_add_u64 v[12:13], v[4:5], 0, v[28:29]
	v_add_co_u32_e64 v4, vcc, s34, v12
	v_exp_f32_e64 v34, v34
	s_nop 0
	s_nop 0
	v_addc_co_u32_e64 v5, vcc, 0, v13, vcc
	v_lshl_add_u64 v[12:13], v[12:13], 0, s[20:21]
	global_load_dwordx2 v[26:27], v[4:5], off offset:1536
	global_load_dwordx2 v[32:33], v[12:13], off offset:128
	v_lshl_add_u64 v[4:5], v[20:21], 0, v[8:9]
	global_load_dwordx4 v[4:7], v[4:5], off
	v_lshl_add_u64 v[8:9], v[0:1], 0, v[8:9]
	v_add_u32_e64 v12, s6, v47
	global_load_dwordx4 v[8:11], v[8:9], off
	v_ashrrev_i32_e64 v13, 31, v12
	v_lshlrev_b64 v[12:13], 8, v[12:13]
	v_lshl_add_u64 v[16:17], v[0:1], 0, v[12:13]
	v_lshl_add_u64 v[12:13], v[20:21], 0, v[12:13]
	global_load_dwordx4 v[12:15], v[12:13], off
	s_nop 0
	s_nop 0
	global_load_dwordx4 v[16:19], v[16:17], off
	v_ldexp_f32 v34, v34, s55
	v_sub_f32_e64 v57, 1.0, v34
	v_mul_lo_u32 v48, v46, s35
	v_add3_u32 v44, 0, v48, v28
	v_mul_lo_u32 v49, v47, s35
	v_bfe_u32 v56, v3, 6, 1
	s_waitcnt vmcnt(7)
	s_nop 0
	v_lshlrev_b32_e64 v34, 16, v22
	v_and_b32_e32 v35, 0xffff0000, v22
	s_waitcnt vmcnt(6)
	s_nop 0
	v_lshlrev_b32_e64 v36, 16, v24
	v_and_b32_e32 v37, 0xffff0000, v24
	v_lshlrev_b32_e64 v22, 16, v23
	v_and_b32_e32 v23, 0xffff0000, v23
	v_lshlrev_b32_e64 v24, 16, v25
	v_and_b32_e32 v25, 0xffff0000, v25
	s_waitcnt vmcnt(5)
	s_nop 0
	v_lshlrev_b32_e64 v38, 16, v26
	v_and_b32_e32 v39, 0xffff0000, v26
	s_waitcnt vmcnt(3)
	s_nop 0
	v_pk_mul_f32 v[40:41], v[4:5], v[34:35]
	v_pk_mul_f32 v[4:5], v[4:5], v[36:37]
	v_pk_mul_f32 v[42:43], v[6:7], v[22:23]
	v_pk_mul_f32 v[6:7], v[6:7], v[24:25]
	s_waitcnt vmcnt(2)
	s_nop 0
	v_pk_fma_f32 v[36:37], v[8:9], v[36:37], v[40:41]
	v_pk_fma_f32 v[4:5], v[8:9], v[34:35], v[4:5] neg_lo:[0,0,1] neg_hi:[0,0,1]
	v_pk_fma_f32 v[8:9], v[10:11], v[24:25], v[42:43]
	v_pk_fma_f32 v[6:7], v[10:11], v[22:23], v[6:7] neg_lo:[0,0,1] neg_hi:[0,0,1]
	v_cvt_pk_bf16_f32 v4, v4, v5
	v_cvt_pk_bf16_f32 v5, v6, v7
	v_cvt_pk_bf16_f32 v6, v36, v37
	v_cvt_pk_bf16_f32 v7, v8, v9
	ds_write2_b64 v44, v[4:5], v[6:7] offset1:16
	v_lshlrev_b32_e64 v4, 16, v32
	v_and_b32_e32 v5, 0xffff0000, v32
	s_waitcnt vmcnt(1)
	s_nop 0
	v_pk_mul_f32 v[6:7], v[12:13], v[38:39]
	v_lshlrev_b32_e64 v8, 16, v27
	v_and_b32_e32 v9, 0xffff0000, v27
	s_waitcnt vmcnt(0)
; __device__ __forceinline__ unsigned cvt_pk_bf16(float lo, float hi) { const f32x2_t v = {lo, hi}; const bf16x2_t b = __builtin_convertvector(v, bf16x2_t); return __builtin_bit_cast(unsigned, b); }
; #define LAS __attribute__((address_space(3)))
; __device__ __forceinline__ float lo_bf(unsigned x) { return __uint_as_float(x << 16); }
; __device__ __forceinline__ float hi_bf(unsigned x) { return __uint_as_float(x & 0xffff0000u); }
; template <bool WITH_K>
; __device__ __forceinline__ void ret_load_qk(PR P, LAS bf16_t* QP, LAS bf16_t* KB, unsigned (&kth)[4][4], const int tidv, const int row0, const int n, const int h, const float kd0, const float g32) {
;     ...
;     for (int it = 0; it < 4; ++it) { const int idx = it * 512 + tidv, i = idx >> 4, f = (idx & 15) * 4;
;         const bf16_t* src = PS + (size_t)(row0 + i) * NCOLS + 1792 + h * 128;
;         const u32x2 q1 = *(const u32x2*)(src + f), q2 = *(const u32x2*)(src + 64 + f);
;         u32x2 k1 = (u32x2){0u, 0u}, k2 = k1; if (WITH_K) { k1 = *(const u32x2*)(src + 512 + f); k2 = *(const u32x2*)(src + 576 + f); }
;         const float4 cs = *(const float4*)(rc + (size_t)(n * 128 + i) * 64 + f), sn = *(const float4*)(rs + (size_t)(n * 128 + i) * 64 + f);
;         const float c4[4] = {cs.x, cs.y, cs.z, cs.w}, s4[4] = {sn.x, sn.y, sn.z, sn.w};
;         const float qa[4] = {lo_bf(q1.x), hi_bf(q1.x), lo_bf(q1.y), hi_bf(q1.y)}, qb[4] = {lo_bf(q2.x), hi_bf(q2.x), lo_bf(q2.y), hi_bf(q2.y)};
;         float qo1[4], qo2[4];
; #pragma unroll
;         for (int x = 0; x < 4; ++x) { qo1[x] = qa[x] * c4[x] - qb[x] * s4[x]; qo2[x] = qa[x] * s4[x] + qb[x] * c4[x]; }
;         u32x2 w; w.x = pg8::cvt_pk_bf16(qo1[0], qo1[1]); w.y = pg8::cvt_pk_bf16(qo1[2], qo1[3]); *(LAS u32x2*)(QP + i * RS + f) = w;
;         w.x = pg8::cvt_pk_bf16(qo2[0], qo2[1]); w.y = pg8::cvt_pk_bf16(qo2[2], qo2[3]); *(LAS u32x2*)(QP + i * RS + 64 + f) = w;
; __device__ __forceinline__ void ret_unit_c(PR P, LAS unsigned char* lds, const int bh, const int n, const int wv) {
;     ...
; #pragma unroll
;     for (int it = 0; it < 4; ++it) { const int idx = it * 512 + tid, e = idx >> 4, d8 = (idx & 15) * 8;
;         *(LAS u32x4*)(ST + e * RS + d8) = *(const u32x4*)(KVB + e * 128 + d8); }
;     __syncthreads();
	s_nop 0
	v_pk_fma_f32 v[6:7], v[16:17], v[4:5], v[6:7]
	v_pk_mul_f32 v[4:5], v[12:13], v[4:5]
	v_lshlrev_b32_e64 v10, 16, v33
	v_and_b32_e32 v11, 0xffff0000, v33
	v_pk_mul_f32 v[12:13], v[14:15], v[8:9]
	v_pk_fma_f32 v[4:5], v[16:17], v[38:39], v[4:5] neg_lo:[0,0,1] neg_hi:[0,0,1]
	v_pk_fma_f32 v[12:13], v[18:19], v[10:11], v[12:13]
	v_pk_mul_f32 v[10:11], v[14:15], v[10:11]
	v_cvt_pk_bf16_f32 v4, v4, v5
	v_pk_fma_f32 v[8:9], v[18:19], v[8:9], v[10:11] neg_lo:[0,0,1] neg_hi:[0,0,1]
	v_cvt_pk_bf16_f32 v6, v6, v7
	v_cvt_pk_bf16_f32 v5, v8, v9
	v_add3_u32 v8, 0, v49, v28
	v_cvt_pk_bf16_f32 v7, v12, v13
	ds_write2_b64 v8, v[4:5], v[6:7] offset1:16
	v_add_u32_e32 v4, 0x400, v3
	v_ashrrev_i32_e64 v50, 4, v4
	v_add_u32_e64 v4, s45, v50
	v_mad_i64_i32 v[4:5], s[46:47], v4, s31, v[30:31]
	v_lshl_add_u64 v[4:5], v[4:5], 0, s[18:19]
	v_lshl_add_u64 v[4:5], v[4:5], 0, v[28:29]
	v_lshl_add_u64 v[6:7], v[4:5], 0, s[20:21]
	v_add_co_u32_e64 v4, vcc, s34, v4
	v_mul_lo_u32 v52, v50, s35
	s_nop 0
	s_nop 0
	v_addc_co_u32_e64 v5, vcc, 0, v5, vcc
	global_load_dwordx2 v[22:23], v[4:5], off offset:1536
	global_load_dwordx2 v[24:25], v[6:7], off offset:128
	v_add_u32_e32 v4, 0x600, v3
	v_ashrrev_i32_e64 v51, 4, v4
	v_add_u32_e64 v4, s45, v51
	v_mad_i64_i32 v[4:5], s[46:47], v4, s31, v[30:31]
	v_lshl_add_u64 v[4:5], v[4:5], 0, s[18:19]
	v_lshl_add_u64 v[4:5], v[4:5], 0, v[28:29]
	v_add_co_u32_e64 v6, vcc, s34, v4
	v_add_u32_e64 v8, s6, v51
	s_nop 0
	s_nop 0
	v_addc_co_u32_e64 v7, vcc, 0, v5, vcc
	v_lshl_add_u64 v[4:5], v[4:5], 0, s[20:21]
	global_load_dwordx2 v[26:27], v[6:7], off offset:1536
	global_load_dwordx2 v[32:33], v[4:5], off offset:128
	v_add_u32_e64 v4, s6, v50
	v_ashrrev_i32_e64 v5, 31, v4
	v_lshlrev_b64 v[12:13], 8, v[4:5]
	v_ashrrev_i32_e64 v9, 31, v8
	v_lshl_add_u64 v[4:5], v[20:21], 0, v[12:13]
	v_lshlrev_b64 v[16:17], 8, v[8:9]
	global_load_dwordx4 v[4:7], v[4:5], off
	v_lshl_add_u64 v[8:9], v[20:21], 0, v[16:17]
	v_lshl_add_u64 v[12:13], v[0:1], 0, v[12:13]
	global_load_dwordx4 v[8:11], v[8:9], off
	v_lshl_add_u64 v[0:1], v[0:1], 0, v[16:17]
	global_load_dwordx4 v[12:15], v[12:13], off
	v_mul_lo_u32 v53, v51, s35
	global_load_dwordx4 v[16:19], v[0:1], off
	v_lshlrev_b32_e64 v216, 4, v2
	v_and_b32_e32 v216, 0xf0, v216
	v_mov_b32_e64 v217, 0
	v_lshl_add_u64 v[218:219], s[26:27], 0, v[216:217]
	v_lshlrev_b32_e64 v220, 7, v46
	v_ashrrev_i32_e64 v221, 31, v220
	v_lshl_add_u64 v[220:221], v[220:221], 1, v[218:219]
	v_lshlrev_b32_e64 v222, 7, v47
	v_ashrrev_i32_e64 v223, 31, v222
	v_lshl_add_u64 v[222:223], v[222:223], 1, v[218:219]
	v_lshlrev_b32_e64 v224, 7, v50
	v_ashrrev_i32_e64 v225, 31, v224
	v_lshl_add_u64 v[224:225], v[224:225], 1, v[218:219]
	v_lshlrev_b32_e64 v226, 7, v51
	v_ashrrev_i32_e64 v227, 31, v226
	v_lshl_add_u64 v[226:227], v[226:227], 1, v[218:219]
	global_load_dwordx4 v[200:203], v[220:221], off
	global_load_dwordx4 v[204:207], v[222:223], off
	global_load_dwordx4 v[208:211], v[224:225], off
	global_load_dwordx4 v[212:215], v[226:227], off
	v_add3_u32 v54, 0, v52, v28
	v_add3_u32 v28, 0, v53, v28
	s_waitcnt vmcnt(11)
	s_nop 0
	v_lshlrev_b32_e64 v0, 16, v22
	v_and_b32_e32 v1, 0xffff0000, v22
	s_waitcnt vmcnt(10)
	s_nop 0
	v_lshlrev_b32_e64 v20, 16, v24
	v_and_b32_e32 v21, 0xffff0000, v24
	v_lshlrev_b32_e64 v22, 16, v23
	v_and_b32_e32 v23, 0xffff0000, v23
	v_lshlrev_b32_e64 v24, 16, v25
	v_and_b32_e32 v25, 0xffff0000, v25
	s_waitcnt vmcnt(9)
	s_nop 0
	v_lshlrev_b32_e64 v34, 16, v26
	v_and_b32_e32 v35, 0xffff0000, v26
	s_waitcnt vmcnt(8)
	s_nop 0
	v_lshlrev_b32_e64 v36, 16, v32
	v_and_b32_e32 v37, 0xffff0000, v32
	v_lshlrev_b32_e64 v26, 16, v27
	v_and_b32_e32 v27, 0xffff0000, v27
	v_lshlrev_b32_e64 v32, 16, v33
	v_and_b32_e32 v33, 0xffff0000, v33
	s_waitcnt vmcnt(7)
	s_nop 0
	v_pk_mul_f32 v[38:39], v[4:5], v[0:1]
	v_pk_mul_f32 v[4:5], v[4:5], v[20:21]
	v_pk_mul_f32 v[40:41], v[6:7], v[22:23]
	v_pk_mul_f32 v[6:7], v[6:7], v[24:25]
	s_waitcnt vmcnt(6)
	s_nop 0
	v_pk_mul_f32 v[42:43], v[8:9], v[34:35]
	v_pk_mul_f32 v[8:9], v[8:9], v[36:37]
	v_pk_mul_f32 v[44:45], v[10:11], v[26:27]
	v_pk_mul_f32 v[10:11], v[10:11], v[32:33]
	s_waitcnt vmcnt(5)
	s_nop 0
	v_pk_fma_f32 v[20:21], v[12:13], v[20:21], v[38:39]
	v_pk_fma_f32 v[0:1], v[12:13], v[0:1], v[4:5] neg_lo:[0,0,1] neg_hi:[0,0,1]
	v_pk_fma_f32 v[4:5], v[14:15], v[24:25], v[40:41]
	v_pk_fma_f32 v[6:7], v[14:15], v[22:23], v[6:7] neg_lo:[0,0,1] neg_hi:[0,0,1]
	s_waitcnt vmcnt(4)
	s_nop 0
	v_pk_fma_f32 v[12:13], v[16:17], v[36:37], v[42:43]
	v_pk_fma_f32 v[8:9], v[16:17], v[34:35], v[8:9] neg_lo:[0,0,1] neg_hi:[0,0,1]
	v_pk_fma_f32 v[14:15], v[18:19], v[32:33], v[44:45]
	v_pk_fma_f32 v[10:11], v[18:19], v[26:27], v[10:11] neg_lo:[0,0,1] neg_hi:[0,0,1]
	v_cvt_pk_bf16_f32 v0, v0, v1
	v_cvt_pk_bf16_f32 v1, v6, v7
	v_cvt_pk_bf16_f32 v6, v20, v21
	v_cvt_pk_bf16_f32 v7, v4, v5
	v_cvt_pk_bf16_f32 v4, v8, v9
	v_cvt_pk_bf16_f32 v5, v10, v11
	v_cvt_pk_bf16_f32 v8, v12, v13
	v_cvt_pk_bf16_f32 v9, v14, v15
	ds_write2_b64 v54, v[0:1], v[6:7] offset1:16
	ds_write2_b64 v28, v[4:5], v[8:9] offset1:16
	v_lshlrev_b32_e64 v0, 4, v2
	v_and_b32_e32 v28, 0xf0, v0
	v_ashrrev_i32_e64 v66, 2, v3
	v_and_b32_e64 v1, 15, v2
	v_and_b32_e32 v3, 0xffffffe0, v66
	v_bfe_u32 v0, v2, 4, 2
	v_or_b32_e64 v23, v3, v1
	v_lshlrev_b32_e64 v20, 4, v0
	v_add_u32_e64 v22, s36, v28
	v_mul_lo_u32 v23, v23, s35
	v_add_u32_e64 v24, v22, v48
	v_add3_u32 v28, 0, v20, v23
	v_add_u32_e64 v25, v22, v49
	v_add_u32_e64 v26, v22, v52
	v_add_u32_e64 v22, v22, v53
	v_lshl_or_b32 v21, v56, 6, v1
	s_waitcnt vmcnt(3)
	s_nop 0
	ds_write_b128 v24, v[200:203]
	s_waitcnt vmcnt(2)
	s_nop 0
	ds_write_b128 v25, v[204:207]
	s_waitcnt vmcnt(1)
	s_nop 0
	ds_write_b128 v26, v[208:211]
	s_waitcnt vmcnt(0)
	s_nop 0
	ds_write_b128 v22, v[212:215]
	s_waitcnt lgkmcnt(0)
	s_barrier
; #define LAS __attribute__((address_space(3)))
; __device__ __forceinline__ void ret_unit_c(PR P, LAS unsigned char* lds, const int bh, const int n, const int wv) {
;     ...
;     f32x4 accY[2][4];
; #pragma unroll
;     for (int mt = 0; mt < 2; ++mt)
; #pragma unroll
;         for (int nt = 0; nt < 4; ++nt) accY[mt][nt] = (f32x4){0.f, 0.f, 0.f, 0.f};
; #pragma unroll
;     for (int ks = 0; ks < 4; ++ks) { bf16x8 aq[2];
; #pragma unroll
;         for (int mt = 0; mt < 2; ++mt) aq[mt] = *(const LAS bf16x8*)(QP + (wr * 32 + mt * 16 + fr) * RS + ks * 32 + fq * 8);
; #pragma unroll
;         for (int nt = 0; nt < 4; ++nt) { const bf16x8 bs = *(const LAS bf16x8*)(ST + (wc * 64 + nt * 16 + fr) * RS + ks * 32 + fq * 8);
; #pragma unroll
;             for (int mt = 0; mt < 2; ++mt) accY[mt][nt] = __builtin_amdgcn_mfma_f32_16x16x32_bf16(aq[mt], bs, accY[mt][nt], 0, 0, 0); }
;         __builtin_amdgcn_sched_barrier(0); }
; #pragma unroll
;     for (int mt = 0; mt < 2; ++mt)
; #pragma unroll
;         for (int j = 0; j < 4; ++j) { const int r = wr * 32 + mt * 16 + fq * 4 + j; const float qd = exp2f(lg2 * (float)(r + 1));
; #pragma unroll
;             for (int nt = 0; nt < 4; ++nt) YST[r * 132 + wc * 64 + nt * 16 + fr] = accY[mt][nt][j] * qd; }
	ds_read_b128 v[4:7], v28
	v_mul_u32_u24_e32 v8, 0x110, v21
	v_add3_u32 v58, s36, v20, v8
	ds_read_b128 v[8:11], v28 offset:4352
	ds_read_b128 v[12:15], v58
	ds_read_b128 v[16:19], v58 offset:4352
	ds_read_b128 v[32:35], v58 offset:8704
	ds_read_b128 v[36:39], v58 offset:13056
	s_waitcnt lgkmcnt(3)
	s_nop 0
	v_mfma_f32_16x16x32_bf16 v[20:23], v[4:7], v[12:15], 0
	v_mfma_f32_16x16x32_bf16 v[12:15], v[8:11], v[12:15], 0
	s_waitcnt lgkmcnt(2)
	s_nop 0
	v_mfma_f32_16x16x32_bf16 v[24:27], v[4:7], v[16:19], 0
	v_mfma_f32_16x16x32_bf16 v[16:19], v[8:11], v[16:19], 0
	s_waitcnt lgkmcnt(1)
	s_nop 0
	v_mfma_f32_16x16x32_bf16 v[40:43], v[4:7], v[32:35], 0
	v_mfma_f32_16x16x32_bf16 v[32:35], v[8:11], v[32:35], 0
	s_waitcnt lgkmcnt(0)
	s_nop 0
	v_mfma_f32_16x16x32_bf16 v[4:7], v[4:7], v[36:39], 0
	v_mfma_f32_16x16x32_bf16 v[8:11], v[8:11], v[36:39], 0
	ds_read_b128 v[36:39], v28 offset:64
	ds_read_b128 v[44:47], v28 offset:4416
	ds_read_b128 v[48:51], v58 offset:64
	ds_read_b128 v[52:55], v58 offset:4416
	s_waitcnt lgkmcnt(1)
	s_nop 0
	v_mfma_f32_16x16x32_bf16 v[20:23], v[36:39], v[48:51], v[20:23]
	v_mfma_f32_16x16x32_bf16 v[12:15], v[44:47], v[48:51], v[12:15]
	s_waitcnt lgkmcnt(0)
	s_nop 0
	v_mfma_f32_16x16x32_bf16 v[24:27], v[36:39], v[52:55], v[24:27]
	v_mfma_f32_16x16x32_bf16 v[16:19], v[44:47], v[52:55], v[16:19]
	ds_read_b128 v[48:51], v58 offset:8768
	ds_read_b128 v[52:55], v58 offset:13120
	s_waitcnt lgkmcnt(1)
	s_nop 0
	v_mfma_f32_16x16x32_bf16 v[40:43], v[36:39], v[48:51], v[40:43]
	v_mfma_f32_16x16x32_bf16 v[32:35], v[44:47], v[48:51], v[32:35]
	s_waitcnt lgkmcnt(0)
	s_nop 0
	v_mfma_f32_16x16x32_bf16 v[4:7], v[36:39], v[52:55], v[4:7]
	v_mfma_f32_16x16x32_bf16 v[8:11], v[44:47], v[52:55], v[8:11]
	ds_read_b128 v[36:39], v28 offset:128
	ds_read_b128 v[44:47], v28 offset:4480
	ds_read_b128 v[48:51], v58 offset:128
	ds_read_b128 v[52:55], v58 offset:4480
	s_waitcnt lgkmcnt(1)
	s_nop 0
	v_mfma_f32_16x16x32_bf16 v[20:23], v[36:39], v[48:51], v[20:23]
	v_mfma_f32_16x16x32_bf16 v[12:15], v[44:47], v[48:51], v[12:15]
	s_waitcnt lgkmcnt(0)
	s_nop 0
	v_mfma_f32_16x16x32_bf16 v[24:27], v[36:39], v[52:55], v[24:27]
	v_mfma_f32_16x16x32_bf16 v[16:19], v[44:47], v[52:55], v[16:19]
	ds_read_b128 v[48:51], v58 offset:8832
	ds_read_b128 v[52:55], v58 offset:13184
	s_waitcnt lgkmcnt(1)
	s_nop 0
	v_mfma_f32_16x16x32_bf16 v[40:43], v[36:39], v[48:51], v[40:43]
	v_mfma_f32_16x16x32_bf16 v[32:35], v[44:47], v[48:51], v[32:35]
	s_waitcnt lgkmcnt(0)
	s_nop 0
	v_mfma_f32_16x16x32_bf16 v[4:7], v[36:39], v[52:55], v[4:7]
	v_mfma_f32_16x16x32_bf16 v[8:11], v[44:47], v[52:55], v[8:11]
	ds_read_b128 v[36:39], v28 offset:192
	ds_read_b128 v[44:47], v28 offset:4544
	ds_read_b128 v[48:51], v58 offset:192
	ds_read_b128 v[52:55], v58 offset:4544
	s_waitcnt lgkmcnt(1)
	s_nop 0
	v_mfma_f32_16x16x32_bf16 v[20:23], v[36:39], v[48:51], v[20:23]
	v_mfma_f32_16x16x32_bf16 v[12:15], v[44:47], v[48:51], v[12:15]
	s_waitcnt lgkmcnt(0)
	s_nop 0
	v_mfma_f32_16x16x32_bf16 v[24:27], v[36:39], v[52:55], v[24:27]
	v_mfma_f32_16x16x32_bf16 v[16:19], v[44:47], v[52:55], v[16:19]
	ds_read_b128 v[48:51], v58 offset:8896
	ds_read_b128 v[52:55], v58 offset:13248
	s_waitcnt lgkmcnt(1)
	s_nop 0
	v_mfma_f32_16x16x32_bf16 v[40:43], v[36:39], v[48:51], v[40:43]
	v_mfma_f32_16x16x32_bf16 v[32:35], v[44:47], v[48:51], v[32:35]
	s_waitcnt lgkmcnt(0)
	s_nop 0
	v_mfma_f32_16x16x32_bf16 v[4:7], v[36:39], v[52:55], v[4:7]
	v_mfma_f32_16x16x32_bf16 v[8:11], v[44:47], v[52:55], v[8:11]
	v_cmp_gt_f32_e64 vcc, s37, v57
	s_and_b64 s[26:27], vcc, exec
	s_cselect_b32 s26, 32, 0
	v_ldexp_f32 v36, v57, s26
	v_lshl_or_b32 v0, v0, 2, v3
	v_log_f32_e64 v36, v36
	v_or_b32_e64 v3, 1, v0
	v_cvt_f32_i32_e64 v3, v3
	v_cndmask_b32_e64 v28, 0, v63, vcc
	v_sub_f32_e64 v28, v36, v28
	v_lshlrev_b32_e64 v1, 2, v1
	v_mul_f32_e64 v36, v28, v3
	v_cmp_gt_f32_e64 vcc, s30, v36
	v_lshlrev_b32_e64 v2, 5, v2
	s_nop 0
	s_nop 0
	v_cndmask_b32_e64 v36, 0, v62, vcc
	v_fmac_f32_e64 v36, v28, v3
	v_exp_f32_e64 v3, v36
	v_cndmask_b32_e64 v37, 0, v64, vcc
	v_lshl_add_u32 v36, v56, 8, 0
	v_ldexp_f32 v3, v3, v37
	v_mul_lo_u32 v37, v0, s40
	v_add3_u32 v1, v36, v1, v37
	v_or_b32_e64 v36, 2, v0
	v_cvt_f32_i32_e64 v36, v36
	v_mul_f32_e64 v20, v3, v20
	v_mul_f32_e64 v24, v3, v24
	v_add_u32_e32 v37, 0x8800, v1
	ds_write2_b32 v37, v20, v24 offset1:16
	v_mul_f32_e64 v24, v28, v36
	v_cmp_gt_f32_e64 vcc, s30, v24
	v_mul_f32_e64 v20, v3, v40
	v_mul_f32_e64 v3, v3, v4
	v_cndmask_b32_e64 v24, 0, v62, vcc
	v_fmac_f32_e64 v24, v28, v36
	v_exp_f32_e64 v24, v24
	ds_write2_b32 v37, v20, v3 offset0:32 offset1:48
	v_or_b32_e64 v20, 3, v0
	v_cvt_f32_i32_e64 v20, v20
	v_cndmask_b32_e64 v3, 0, v64, vcc
	v_ldexp_f32 v3, v24, v3
	v_mul_f32_e64 v4, v3, v21
	v_mul_f32_e64 v21, v3, v25
	ds_write2_b32 v37, v4, v21 offset0:132 offset1:148
	v_mul_f32_e64 v21, v28, v20
	v_cmp_gt_f32_e64 vcc, s30, v21
	v_mul_f32_e64 v4, v3, v41
	v_mul_f32_e64 v3, v3, v5
	v_cndmask_b32_e64 v21, 0, v62, vcc
	v_fmac_f32_e64 v21, v28, v20
	v_exp_f32_e64 v20, v21
	ds_write2_b32 v37, v4, v3 offset0:164 offset1:180
	v_cndmask_b32_e64 v3, 0, v64, vcc
	v_add_u32_e32 v21, 0x8c00, v1
	v_ldexp_f32 v3, v20, v3
	v_add_u32_e64 v20, 4, v0
	v_cvt_f32_i32_e64 v20, v20
	v_mul_f32_e64 v4, v3, v22
	v_mul_f32_e64 v5, v3, v26
	ds_write2_b32 v21, v4, v5 offset0:8 offset1:24
	v_mul_f32_e64 v5, v28, v20
	v_cmp_gt_f32_e64 vcc, s30, v5
	v_mul_f32_e64 v4, v3, v42
	v_mul_f32_e64 v3, v3, v6
	v_cndmask_b32_e64 v5, 0, v62, vcc
	v_fmac_f32_e64 v5, v28, v20
	v_exp_f32_e64 v5, v5
	ds_write2_b32 v21, v4, v3 offset0:40 offset1:56
	v_cndmask_b32_e64 v3, 0, v64, vcc
	v_ldexp_f32 v3, v5, v3
	v_or_b32_e64 v5, 17, v0
	v_cvt_f32_i32_e64 v5, v5
; #define LAS __attribute__((address_space(3)))
; __device__ __forceinline__ float lo_bf(unsigned x) { return __uint_as_float(x << 16); }
; __device__ __forceinline__ float hi_bf(unsigned x) { return __uint_as_float(x & 0xffff0000u); }
; __device__ __forceinline__ float quad_sum(float v) { v += dppf<0xB1>(v); v += dppf<0x4E>(v); return v; }
; __device__ __forceinline__ void ret_unit_c(PR P, LAS unsigned char* lds, const int bh, const int n, const int wv) {
;     ...
; #pragma unroll
;     for (int mt = 0; mt < 2; ++mt)
; #pragma unroll
;         for (int j = 0; j < 4; ++j) { const int r = wr * 32 + mt * 16 + fq * 4 + j; const float qd = exp2f(lg2 * (float)(r + 1));
; #pragma unroll
;             for (int nt = 0; nt < 4; ++nt) YST[r * 132 + wc * 64 + nt * 16 + fr] = accY[mt][nt][j] * qd; }
;     __syncthreads();
;     { const int i = tid >> 2, part = tid & 3; float yv[32]; float s = 0.f;
;       bf16_t* yo = Y + (size_t)(row0 + i) * 1024 + 512 + h * 128 + part * 32;
; #pragma unroll
;       for (int x = 0; x < 4; ++x) { const u32x4 y1 = *(const u32x4*)(yo + x * 8); const f32x4 ta = *(const LAS f32x4*)(YST + i * 132 + part * 32 + x * 8), tb = *(const LAS f32x4*)(YST + i * 132 + part * 32 + x * 8 + 4);
;           yv[x * 8 + 0] = ta[0] + lo_bf(y1.x); yv[x * 8 + 1] = ta[1] + hi_bf(y1.x); yv[x * 8 + 2] = ta[2] + lo_bf(y1.y); yv[x * 8 + 3] = ta[3] + hi_bf(y1.y);
;           yv[x * 8 + 4] = tb[0] + lo_bf(y1.z); yv[x * 8 + 5] = tb[1] + hi_bf(y1.z); yv[x * 8 + 6] = tb[2] + lo_bf(y1.w); yv[x * 8 + 7] = tb[3] + hi_bf(y1.w); }
; #pragma unroll
;       for (int x = 0; x < 32; ++x) s += yv[x];
;       s = quad_sum(s); const float mean = s * (1.0f / 128.0f); float s2 = 0.f;
; #pragma unroll
;       for (int x = 0; x < 32; ++x) { yv[x] -= mean; s2 += yv[x] * yv[x]; }
;       s2 = quad_sum(s2); const float rstd = rsqrtf(s2 * (1.0f / 128.0f) + 1e-5f);
;       const bf16_t* gp = PS + (size_t)(row0 + i) * NCOLS + 1792 + 1536 + h * 128 + part * 32; const float* gw = P.gn_w + h * 128 + part * 32;
; #pragma unroll
;       for (int x = 0; x < 4; ++x) { const u32x4 g4 = *(const u32x4*)(gp + x * 8); const float4 w0 = *(const float4*)(gw + x * 8), w1 = *(const float4*)(gw + x * 8 + 4);
	v_mul_f32_e64 v4, v3, v23
	v_mul_f32_e64 v6, v3, v27
	ds_write2_b32 v21, v4, v6 offset0:140 offset1:156
	v_mul_f32_e64 v6, v28, v5
	v_cmp_gt_f32_e64 vcc, s30, v6
	v_mul_f32_e64 v4, v3, v43
	v_mul_f32_e64 v3, v3, v7
	v_cndmask_b32_e64 v6, 0, v62, vcc
	v_fmac_f32_e64 v6, v28, v5
	v_exp_f32_e64 v5, v6
	v_or_b32_e64 v6, 18, v0
	v_cvt_f32_i32_e64 v6, v6
	ds_write2_b32 v21, v4, v3 offset0:172 offset1:188
	v_cndmask_b32_e64 v3, 0, v64, vcc
	v_ldexp_f32 v3, v5, v3
	v_mul_f32_e64 v4, v3, v12
	v_mul_f32_e64 v5, v3, v16
	v_add_u32_e32 v7, 0xa800, v1
	ds_write2_b32 v7, v4, v5 offset0:64 offset1:80
	v_mul_f32_e64 v5, v28, v6
	v_cmp_gt_f32_e64 vcc, s30, v5
	v_mul_f32_e64 v4, v3, v32
	v_mul_f32_e64 v3, v3, v8
	v_cndmask_b32_e64 v5, 0, v62, vcc
	v_fmac_f32_e64 v5, v28, v6
	v_exp_f32_e64 v5, v5
	ds_write2_b32 v7, v4, v3 offset0:96 offset1:112
	v_cndmask_b32_e64 v3, 0, v64, vcc
	v_add_u32_e32 v1, 0xac00, v1
	v_ldexp_f32 v3, v5, v3
	v_or_b32_e64 v5, 19, v0
	v_cvt_f32_i32_e64 v5, v5
	v_mul_f32_e64 v4, v3, v13
	v_mul_f32_e64 v6, v3, v17
	ds_write2_b32 v7, v4, v6 offset0:196 offset1:212
	v_mul_f32_e64 v6, v28, v5
	v_cmp_gt_f32_e64 vcc, s30, v6
	v_add_u32_e64 v0, 20, v0
	v_mul_f32_e64 v4, v3, v33
	v_cndmask_b32_e64 v6, 0, v62, vcc
	v_fmac_f32_e64 v6, v28, v5
	v_exp_f32_e64 v5, v6
	v_mul_f32_e64 v3, v3, v9
	v_cvt_f32_i32_e64 v0, v0
	ds_write2_b32 v7, v4, v3 offset0:228 offset1:244
	v_cndmask_b32_e64 v3, 0, v64, vcc
	v_ldexp_f32 v3, v5, v3
	v_mul_f32_e64 v4, v3, v14
	v_mul_f32_e64 v5, v3, v18
	ds_write2_b32 v1, v4, v5 offset0:72 offset1:88
	v_mul_f32_e64 v5, v28, v0
	v_cmp_gt_f32_e64 vcc, s30, v5
	v_mul_f32_e64 v4, v3, v34
	v_mul_f32_e64 v3, v3, v10
	v_cndmask_b32_e64 v5, 0, v62, vcc
	v_fmac_f32_e64 v5, v28, v0
	v_exp_f32_e64 v0, v5
	ds_write2_b32 v1, v4, v3 offset0:104 offset1:120
	v_cndmask_b32_e64 v3, 0, v64, vcc
	v_and_b32_e32 v10, 0x60, v2
	v_ldexp_f32 v0, v0, v3
	v_mul_f32_e64 v3, v0, v15
	v_mul_f32_e64 v4, v0, v19
	ds_write2_b32 v1, v3, v4 offset0:204 offset1:220
	v_add_u32_e64 v4, s45, v66
	v_mul_f32_e64 v3, v0, v35
	v_mul_f32_e64 v0, v0, v11
	v_ashrrev_i32_e64 v5, 31, v4
	ds_write2_b32 v1, v3, v0 offset0:236 offset1:252
	v_lshlrev_b64 v[0:1], 11, v[4:5]
	v_lshl_add_u64 v[6:7], s[10:11], 0, v[0:1]
	v_lshl_add_u64 v[0:1], v[6:7], 0, s[18:19]
	v_lshlrev_b32_e64 v28, 1, v10
	v_lshl_add_u64 v[8:9], v[0:1], 0, v[28:29]
	v_mad_i64_i32 v[4:5], s[26:27], v4, s42, v[6:7]
	v_add_co_u32_e64 v34, vcc, s41, v8
	v_lshl_add_u64 v[4:5], v[4:5], 0, s[18:19]
	s_nop 0
	s_nop 0
	v_addc_co_u32_e64 v35, vcc, 0, v9, vcc
	v_lshl_add_u64 v[12:13], v[4:5], 0, v[28:29]
	v_lshl_add_u64 v[32:33], v[8:9], 0, s[22:23]
	v_add_co_u32_e64 v4, vcc, s43, v12
	s_waitcnt lgkmcnt(0)
	s_barrier
	global_load_dwordx4 v[0:3], v[32:33], off offset:48
	v_addc_co_u32_e64 v5, vcc, 0, v13, vcc
	global_load_dwordx4 v[58:61], v[4:5], off offset:512
	global_load_dwordx4 v[52:55], v[34:35], off offset:3072
	v_mul_lo_u32 v4, v66, s40
	global_load_dwordx4 v[20:23], v[32:33], off offset:32
	global_load_dwordx4 v[66:69], v[32:33], off offset:16
	v_lshlrev_b32_e64 v28, 2, v10
	v_add3_u32 v8, 0, v4, v28
	ds_read_b128 v[70:73], v8 offset:34816
	ds_read_b128 v[44:47], v8 offset:34832
	ds_read_b128 v[74:77], v8 offset:34848
	ds_read_b128 v[78:81], v8 offset:34864
	ds_read_b128 v[4:7], v8 offset:34912
	ds_read_b128 v[24:27], v8 offset:34880
	ds_read_b128 v[82:85], v8 offset:34896
	ds_read_b128 v[8:11], v8 offset:34928
	s_lshl_b32 s18, s44, 9
	s_add_u32 s26, s12, s18
	s_addc_u32 s27, s13, 0
	s_addk_i32 s28, 0x80
	s_cmpk_eq_i32 s28, 0x180
	s_waitcnt vmcnt(4)
	v_and_b32_e32 v15, 0xffff0000, v0
	v_lshlrev_b32_e64 v14, 16, v0
	s_waitcnt lgkmcnt(3)
	s_nop 0
	v_pk_add_f32 v[40:41], v[4:5], v[14:15]
	v_and_b32_e32 v5, 0xffff0000, v1
	v_lshlrev_b32_e64 v4, 16, v1
	v_and_b32_e32 v1, 0xffff0000, v2
	v_lshlrev_b32_e64 v0, 16, v2
	s_waitcnt vmcnt(3)
	s_nop 0
	v_lshlrev_b32_e64 v38, 16, v60
	s_waitcnt lgkmcnt(0)
	s_nop 0
	v_pk_add_f32 v[48:49], v[8:9], v[0:1]
	v_lshl_add_u64 v[8:9], v[12:13], 0, s[24:25]
	s_waitcnt vmcnt(2)
	s_nop 0
	v_lshlrev_b32_e64 v12, 16, v55
	v_and_b32_e32 v13, 0xffff0000, v55
	v_and_b32_e32 v39, 0xffff0000, v60
	v_mul_f32_e32 v37, 0xbfb8aa3b, v38
	v_pk_add_f32 v[56:57], v[46:47], v[12:13]
	v_exp_f32_e64 v46, v37
	v_mul_f32_e32 v37, 0xbfb8aa3b, v39
	v_exp_f32_e64 v47, v37
	v_lshlrev_b32_e64 v36, 16, v61
	v_add_f32_e64 v46, 1.0, v46
	v_rcp_f32_e64 v46, v46
	v_add_f32_e64 v47, 1.0, v47
	v_rcp_f32_e64 v47, v47
	v_and_b32_e32 v37, 0xffff0000, v61
	v_lshlrev_b32_e64 v60, 16, v54
	v_and_b32_e32 v61, 0xffff0000, v54
	v_pk_add_f32 v[60:61], v[44:45], v[60:61]
	v_lshlrev_b32_e64 v44, 16, v59
	v_and_b32_e32 v45, 0xffff0000, v59
	v_pk_mul_f32 v[38:39], v[46:47], v[38:39]
	v_lshlrev_b32_e64 v46, 16, v53
	v_and_b32_e32 v47, 0xffff0000, v53
	v_mul_f32_e32 v53, 0xbfb8aa3b, v44
	v_mul_f32_e32 v54, 0xbfb8aa3b, v45
	v_exp_f32_e64 v53, v53
	v_exp_f32_e64 v54, v54
	v_pk_add_f32 v[72:73], v[72:73], v[46:47]
	v_and_b32_e32 v55, 0xffff0000, v52
	v_add_f32_e64 v46, 1.0, v53
	v_add_f32_e64 v47, 1.0, v54
	v_lshlrev_b32_e64 v54, 16, v52
	v_lshlrev_b32_e64 v52, 16, v58
	v_and_b32_e32 v53, 0xffff0000, v58
	v_pk_add_f32 v[70:71], v[70:71], v[54:55]
	v_mul_f32_e32 v55, 0xbfb8aa3b, v52
	v_mul_f32_e32 v58, 0xbfb8aa3b, v53
	v_exp_f32_e64 v55, v55
	v_exp_f32_e64 v58, v58
	v_add_f32_e64 v54, 0, v70
	v_add_f32_e64 v59, v71, v54
	v_add_f32_e64 v54, 1.0, v55
	v_add_f32_e64 v55, 1.0, v58
	v_add_f32_e64 v58, v72, v59
	v_mul_f32_e32 v59, 0xbfb8aa3b, v36
	v_mul_f32_e32 v86, 0xbfb8aa3b, v37
	v_add_f32_e64 v58, v73, v58
	v_exp_f32_e64 v59, v59
	v_exp_f32_e64 v86, v86
	v_add_f32_e64 v58, v60, v58
	v_and_b32_e32 v1, 0xffff0000, v3
	v_lshlrev_b32_e64 v0, 16, v3
	v_add_f32_e64 v58, v61, v58
	v_pk_add_f32 v[42:43], v[6:7], v[4:5]
	v_pk_add_f32 v[50:51], v[10:11], v[0:1]
	global_load_dwordx4 v[0:3], v[8:9], off offset:48
	global_load_dwordx4 v[4:7], v[8:9], off offset:32
	s_nop 0
	s_nop 0
	global_load_dwordx4 v[8:11], v[8:9], off offset:16
	s_nop 0
	s_nop 0
	global_load_dwordx4 v[12:15], v28, s[26:27] offset:16
	global_load_dwordx4 v[16:19], v28, s[26:27]
	v_add_f32_e64 v58, v56, v58
	v_add_f32_e64 v88, v57, v58
	v_add_f32_e64 v58, 1.0, v59
	v_add_f32_e64 v59, 1.0, v86
	s_waitcnt vmcnt(5)
; #define LAS __attribute__((address_space(3)))
; __device__ __forceinline__ float lo_bf(unsigned x) { return __uint_as_float(x << 16); }
; __device__ __forceinline__ float hi_bf(unsigned x) { return __uint_as_float(x & 0xffff0000u); }
; __device__ __forceinline__ float quad_sum(float v) { v += dppf<0xB1>(v); v += dppf<0x4E>(v); return v; }
; __device__ __forceinline__ void ret_unit_c(PR P, LAS unsigned char* lds, const int bh, const int n, const int wv) {
;     ...
;     { const int i = tid >> 2, part = tid & 3; float yv[32]; float s = 0.f;
;       bf16_t* yo = Y + (size_t)(row0 + i) * 1024 + 512 + h * 128 + part * 32;
; #pragma unroll
;       for (int x = 0; x < 4; ++x) { const u32x4 y1 = *(const u32x4*)(yo + x * 8); const f32x4 ta = *(const LAS f32x4*)(YST + i * 132 + part * 32 + x * 8), tb = *(const LAS f32x4*)(YST + i * 132 + part * 32 + x * 8 + 4);
;           yv[x * 8 + 0] = ta[0] + lo_bf(y1.x); yv[x * 8 + 1] = ta[1] + hi_bf(y1.x); yv[x * 8 + 2] = ta[2] + lo_bf(y1.y); yv[x * 8 + 3] = ta[3] + hi_bf(y1.y);
;           yv[x * 8 + 4] = tb[0] + lo_bf(y1.z); yv[x * 8 + 5] = tb[1] + hi_bf(y1.z); yv[x * 8 + 6] = tb[2] + lo_bf(y1.w); yv[x * 8 + 7] = tb[3] + hi_bf(y1.w); }
; #pragma unroll
;       for (int x = 0; x < 32; ++x) s += yv[x];
;       s = quad_sum(s); const float mean = s * (1.0f / 128.0f); float s2 = 0.f;
; #pragma unroll
;       for (int x = 0; x < 32; ++x) { yv[x] -= mean; s2 += yv[x] * yv[x]; }
;       s2 = quad_sum(s2); const float rstd = rsqrtf(s2 * (1.0f / 128.0f) + 1e-5f);
	s_nop 0
	v_lshlrev_b32_e64 v86, 16, v69
	v_and_b32_e32 v87, 0xffff0000, v69
	v_pk_add_f32 v[80:81], v[80:81], v[86:87]
	v_lshlrev_b32_e64 v86, 16, v68
	v_and_b32_e32 v87, 0xffff0000, v68
	v_pk_add_f32 v[68:69], v[78:79], v[86:87]
	v_lshlrev_b32_e64 v78, 16, v67
	v_and_b32_e32 v79, 0xffff0000, v67
	v_pk_add_f32 v[76:77], v[76:77], v[78:79]
	v_lshlrev_b32_e64 v78, 16, v66
	v_and_b32_e32 v79, 0xffff0000, v66
	v_pk_add_f32 v[66:67], v[74:75], v[78:79]
	v_lshlrev_b32_e64 v78, 16, v22
	v_add_f32_e64 v74, v66, v88
	v_add_f32_e64 v74, v67, v74
	v_add_f32_e64 v74, v76, v74
	v_add_f32_e64 v74, v77, v74
	v_add_f32_e64 v74, v68, v74
	v_add_f32_e64 v74, v69, v74
	v_add_f32_e64 v74, v80, v74
	v_and_b32_e32 v79, 0xffff0000, v22
	v_add_f32_e64 v86, v81, v74
	v_lshlrev_b32_e64 v74, 16, v23
	v_and_b32_e32 v75, 0xffff0000, v23
	v_pk_add_f32 v[22:23], v[82:83], v[78:79]
	v_lshlrev_b32_e64 v78, 16, v21
	v_and_b32_e32 v79, 0xffff0000, v21
	v_pk_add_f32 v[26:27], v[26:27], v[78:79]
	v_lshlrev_b32_e64 v78, 16, v20
	v_and_b32_e32 v79, 0xffff0000, v20
	v_pk_add_f32 v[20:21], v[24:25], v[78:79]
	v_pk_add_f32 v[74:75], v[84:85], v[74:75]
	v_add_f32_e64 v24, v20, v86
	v_add_f32_e64 v24, v21, v24
	v_add_f32_e64 v24, v26, v24
	v_add_f32_e64 v24, v27, v24
	v_add_f32_e64 v24, v22, v24
	v_add_f32_e64 v24, v23, v24
	v_add_f32_e64 v24, v74, v24
	v_add_f32_e64 v24, v75, v24
	v_add_f32_e64 v24, v40, v24
	v_add_f32_e64 v24, v41, v24
	v_add_f32_e64 v24, v42, v24
	v_add_f32_e64 v24, v43, v24
	v_add_f32_e64 v24, v48, v24
	v_add_f32_e64 v24, v49, v24
	v_add_f32_e64 v24, v50, v24
	v_add_f32_e64 v24, v51, v24
	v_rcp_f32_e64 v46, v46
	v_rcp_f32_e64 v47, v47
	v_add_f32_dpp v24, v24, v24 quad_perm:[1,0,3,2] row_mask:0xf bank_mask:0xf bound_ctrl:1
	v_rcp_f32_e64 v54, v54
	v_rcp_f32_e64 v55, v55
	v_add_f32_dpp v24, v24, v24 quad_perm:[2,3,0,1] row_mask:0xf bank_mask:0xf bound_ctrl:1
	v_mul_f32_e32 v78, 0x3c000000, v24
	v_pk_add_f32 v[70:71], v[70:71], v[78:79] op_sel_hi:[1,0] neg_lo:[0,1] neg_hi:[0,1]
	v_pk_add_f32 v[72:73], v[72:73], v[78:79] op_sel_hi:[1,0] neg_lo:[0,1] neg_hi:[0,1]
	v_pk_mul_f32 v[82:83], v[70:71], v[70:71]
	v_pk_mul_f32 v[84:85], v[72:73], v[72:73]
	v_add_f32_e64 v82, v82, v83
	v_pk_add_f32 v[60:61], v[60:61], v[78:79] op_sel_hi:[1,0] neg_lo:[0,1] neg_hi:[0,1]
	v_add_f32_e64 v82, v84, v82
	v_pk_mul_f32 v[86:87], v[60:61], v[60:61]
	v_add_f32_e64 v82, v85, v82
	v_pk_add_f32 v[56:57], v[56:57], v[78:79] op_sel_hi:[1,0] neg_lo:[0,1] neg_hi:[0,1]
	v_add_f32_e64 v82, v86, v82
	v_pk_mul_f32 v[88:89], v[56:57], v[56:57]
	v_add_f32_e64 v82, v87, v82
	v_pk_add_f32 v[66:67], v[66:67], v[78:79] op_sel_hi:[1,0] neg_lo:[0,1] neg_hi:[0,1]
	v_add_f32_e64 v82, v88, v82
	v_pk_mul_f32 v[90:91], v[66:67], v[66:67]
	v_add_f32_e64 v82, v89, v82
	v_pk_add_f32 v[76:77], v[76:77], v[78:79] op_sel_hi:[1,0] neg_lo:[0,1] neg_hi:[0,1]
	v_add_f32_e64 v82, v90, v82
	v_pk_mul_f32 v[92:93], v[76:77], v[76:77]
	v_add_f32_e64 v82, v91, v82
	v_pk_add_f32 v[68:69], v[68:69], v[78:79] op_sel_hi:[1,0] neg_lo:[0,1] neg_hi:[0,1]
	v_add_f32_e64 v82, v92, v82
	v_pk_mul_f32 v[94:95], v[68:69], v[68:69]
	v_add_f32_e64 v82, v93, v82
	v_pk_add_f32 v[80:81], v[80:81], v[78:79] op_sel_hi:[1,0] neg_lo:[0,1] neg_hi:[0,1]
	v_add_f32_e64 v82, v94, v82
	v_pk_mul_f32 v[96:97], v[80:81], v[80:81]
	v_add_f32_e64 v82, v95, v82
	v_pk_add_f32 v[98:99], v[20:21], v[78:79] op_sel_hi:[1,0] neg_lo:[0,1] neg_hi:[0,1]
	v_add_f32_e64 v82, v96, v82
	v_pk_mul_f32 v[100:101], v[98:99], v[98:99]
	v_add_f32_e64 v82, v97, v82
	v_pk_add_f32 v[26:27], v[26:27], v[78:79] op_sel_hi:[1,0] neg_lo:[0,1] neg_hi:[0,1]
	v_add_f32_e64 v82, v100, v82
	v_pk_mul_f32 v[102:103], v[26:27], v[26:27]
	v_add_f32_e64 v82, v101, v82
	v_pk_add_f32 v[104:105], v[22:23], v[78:79] op_sel_hi:[1,0] neg_lo:[0,1] neg_hi:[0,1]
	v_add_f32_e64 v82, v102, v82
	v_pk_mul_f32 v[106:107], v[104:105], v[104:105]
	v_add_f32_e64 v82, v103, v82
	v_pk_add_f32 v[74:75], v[74:75], v[78:79] op_sel_hi:[1,0] neg_lo:[0,1] neg_hi:[0,1]
	v_add_f32_e64 v82, v106, v82
	v_pk_mul_f32 v[108:109], v[74:75], v[74:75]
	v_add_f32_e64 v82, v107, v82
	v_pk_add_f32 v[40:41], v[40:41], v[78:79] op_sel_hi:[1,0] neg_lo:[0,1] neg_hi:[0,1]
	v_add_f32_e64 v82, v108, v82
	v_pk_add_f32 v[22:23], v[48:49], v[78:79] op_sel_hi:[1,0] neg_lo:[0,1] neg_hi:[0,1]
	v_pk_add_f32 v[20:21], v[50:51], v[78:79] op_sel_hi:[1,0] neg_lo:[0,1] neg_hi:[0,1]
	v_pk_add_f32 v[24:25], v[42:43], v[78:79] op_sel_hi:[1,0] neg_lo:[0,1] neg_hi:[0,1]
	v_pk_mul_f32 v[78:79], v[40:41], v[40:41]
	v_add_f32_e64 v82, v109, v82
	v_add_f32_e64 v78, v78, v82
	v_pk_mul_f32 v[42:43], v[24:25], v[24:25]
	v_add_f32_e64 v78, v79, v78
	v_add_f32_e64 v42, v42, v78
	v_pk_mul_f32 v[48:49], v[22:23], v[22:23]
	v_add_f32_e64 v42, v43, v42
	v_add_f32_e64 v42, v48, v42
	v_pk_mul_f32 v[50:51], v[20:21], v[20:21]
	v_add_f32_e64 v42, v49, v42
	v_add_f32_e64 v42, v50, v42
	v_add_f32_e64 v42, v51, v42
	v_rcp_f32_e64 v58, v58
	v_rcp_f32_e64 v59, v59
	v_add_f32_dpp v42, v42, v42 quad_perm:[1,0,3,2] row_mask:0xf bank_mask:0xf bound_ctrl:1
	v_pk_mul_f32 v[36:37], v[58:59], v[36:37]
	s_nop 0
	s_nop 0
	v_add_f32_dpp v42, v42, v42 quad_perm:[2,3,0,1] row_mask:0xf bank_mask:0xf bound_ctrl:1
	v_fmamk_f32 v42, v42, 0x3c000000, v65
	v_mul_f32_e32 v43, 0x4b800000, v42
	v_cmp_gt_f32_e64 vcc, s37, v42
	s_nop 1
	s_nop 0
	v_cndmask_b32_e64 v42, v42, v43, vcc
	v_rsq_f32_e64 v48, v42
	v_pk_mul_f32 v[42:43], v[46:47], v[44:45]
	v_pk_mul_f32 v[44:45], v[54:55], v[52:53]
	v_mul_f32_e32 v46, 0x45800000, v48
	v_cndmask_b32_e64 v46, v48, v46, vcc
	v_pk_mul_f32 v[48:49], v[70:71], v[46:47] op_sel_hi:[1,0]
	s_waitcnt vmcnt(0)
; __device__ __forceinline__ unsigned cvt_pk_bf16(float lo, float hi) { const f32x2_t v = {lo, hi}; const bf16x2_t b = __builtin_convertvector(v, bf16x2_t); return __builtin_bit_cast(unsigned, b); }
; __device__ __forceinline__ float lo_bf(unsigned x) { return __uint_as_float(x << 16); }
; __device__ __forceinline__ float hi_bf(unsigned x) { return __uint_as_float(x & 0xffff0000u); }
; __device__ __forceinline__ void ret_unit_c(PR P, LAS unsigned char* lds, const int bh, const int n, const int wv) {
;     ...
;       const bf16_t* gp = PS + (size_t)(row0 + i) * NCOLS + 1792 + 1536 + h * 128 + part * 32; const float* gw = P.gn_w + h * 128 + part * 32;
; #pragma unroll
;       for (int x = 0; x < 4; ++x) { const u32x4 g4 = *(const u32x4*)(gp + x * 8); const float4 w0 = *(const float4*)(gw + x * 8), w1 = *(const float4*)(gw + x * 8 + 4);
;           const float gg[8] = {lo_bf(g4.x), hi_bf(g4.x), lo_bf(g4.y), hi_bf(g4.y), lo_bf(g4.z), hi_bf(g4.z), lo_bf(g4.w), hi_bf(g4.w)}; const float ww[8] = {w0.x, w0.y, w0.z, w0.w, w1.x, w1.y, w1.z, w1.w};
;           float o[8];
; #pragma unroll
;           for (int z = 0; z < 8; ++z) o[z] = yv[x * 8 + z] * rstd * ww[z] * (gg[z] * __builtin_amdgcn_rcpf(1.0f + __expf(-gg[z])));
;           u32x4 w; w.x = pg8::cvt_pk_bf16(o[0], o[1]); w.y = pg8::cvt_pk_bf16(o[2], o[3]); w.z = pg8::cvt_pk_bf16(o[4], o[5]); w.w = pg8::cvt_pk_bf16(o[6], o[7]);
;           *(u32x4*)(yo + x * 8) = w; } }
	s_nop 0
	v_pk_mul_f32 v[16:17], v[16:17], v[48:49]
	s_nop 0
	s_nop 0
	v_pk_mul_f32 v[16:17], v[44:45], v[16:17]
	v_pk_mul_f32 v[44:45], v[72:73], v[46:47] op_sel_hi:[1,0]
	s_nop 0
	s_nop 0
	v_pk_mul_f32 v[18:19], v[18:19], v[44:45]
	v_and_b32_e32 v45, 0xffff0000, v8
	v_pk_mul_f32 v[18:19], v[42:43], v[18:19]
	v_pk_mul_f32 v[42:43], v[60:61], v[46:47] op_sel_hi:[1,0]
	v_lshlrev_b32_e64 v44, 16, v8
	v_pk_mul_f32 v[12:13], v[12:13], v[42:43]
	v_mul_f32_e32 v8, 0xbfb8aa3b, v44
	v_pk_mul_f32 v[38:39], v[38:39], v[12:13]
	v_pk_mul_f32 v[12:13], v[56:57], v[46:47] op_sel_hi:[1,0]
	v_exp_f32_e64 v8, v8
	v_pk_mul_f32 v[12:13], v[14:15], v[12:13]
	v_cvt_pk_bf16_f32 v14, v38, v39
	v_pk_mul_f32 v[36:37], v[36:37], v[12:13]
	v_cvt_pk_bf16_f32 v12, v16, v17
	v_cvt_pk_bf16_f32 v13, v18, v19
	v_cvt_pk_bf16_f32 v15, v36, v37
	global_store_dwordx4 v[34:35], v[12:15], off offset:3072
	global_load_dwordx4 v[12:15], v28, s[26:27] offset:32
	s_nop 0
	s_nop 0
	global_load_dwordx4 v[16:19], v28, s[26:27] offset:48
	v_and_b32_e32 v37, 0xffff0000, v10
	v_mul_f32_e32 v35, 0xbfb8aa3b, v37
	v_exp_f32_e64 v38, v35
	v_lshlrev_b32_e64 v34, 16, v11
	v_and_b32_e32 v35, 0xffff0000, v11
	v_and_b32_e32 v39, 0xffff0000, v9
	v_add_f32_e64 v11, 1.0, v38
	v_lshlrev_b32_e64 v38, 16, v9
	v_mul_f32_e32 v9, 0xbfb8aa3b, v38
	v_exp_f32_e64 v9, v9
	v_mul_f32_e32 v42, 0xbfb8aa3b, v39
	v_exp_f32_e64 v43, v42
	v_lshlrev_b32_e64 v36, 16, v10
	v_add_f32_e64 v9, 1.0, v9
	v_rcp_f32_e64 v42, v9
	v_add_f32_e64 v9, 1.0, v43
	v_mul_f32_e32 v43, 0xbfb8aa3b, v45
	v_exp_f32_e64 v47, v43
	v_mul_f32_e32 v10, 0xbfb8aa3b, v36
	v_exp_f32_e64 v10, v10
	v_rcp_f32_e64 v43, v9
	v_add_f32_e64 v9, 1.0, v47
	v_mul_f32_e32 v47, 0xbfb8aa3b, v34
	v_exp_f32_e64 v47, v47
	v_mul_f32_e32 v48, 0xbfb8aa3b, v35
	v_add_f32_e64 v10, 1.0, v10
	v_exp_f32_e64 v49, v48
	v_rcp_f32_e64 v10, v10
	v_rcp_f32_e64 v11, v11
	v_add_f32_e64 v8, 1.0, v8
	v_rcp_f32_e64 v8, v8
	v_rcp_f32_e64 v9, v9
	v_add_f32_e64 v47, 1.0, v47
	v_rcp_f32_e64 v48, v47
	v_add_f32_e64 v47, 1.0, v49
	v_pk_mul_f32 v[10:11], v[10:11], v[36:37]
	v_pk_mul_f32 v[36:37], v[42:43], v[38:39]
	v_pk_mul_f32 v[38:39], v[66:67], v[46:47] op_sel_hi:[1,0]
	v_pk_mul_f32 v[8:9], v[8:9], v[44:45]
	v_rcp_f32_e64 v49, v47
	s_waitcnt vmcnt(1)
	s_nop 0
	v_pk_mul_f32 v[12:13], v[12:13], v[38:39]
	s_nop 0
	s_nop 0
	v_pk_mul_f32 v[8:9], v[8:9], v[12:13]
	v_pk_mul_f32 v[12:13], v[76:77], v[46:47] op_sel_hi:[1,0]
	v_pk_mul_f32 v[34:35], v[48:49], v[34:35]
	v_pk_mul_f32 v[12:13], v[14:15], v[12:13]
	v_pk_mul_f32 v[14:15], v[68:69], v[46:47] op_sel_hi:[1,0]
	v_pk_mul_f32 v[12:13], v[36:37], v[12:13]
	s_waitcnt vmcnt(0)
	s_nop 0
	v_pk_mul_f32 v[14:15], v[16:17], v[14:15]
	v_cvt_pk_bf16_f32 v8, v8, v9
	v_pk_mul_f32 v[10:11], v[10:11], v[14:15]
	v_pk_mul_f32 v[14:15], v[80:81], v[46:47] op_sel_hi:[1,0]
	v_cvt_pk_bf16_f32 v9, v12, v13
	v_pk_mul_f32 v[14:15], v[18:19], v[14:15]
	v_cvt_pk_bf16_f32 v10, v10, v11
	v_pk_mul_f32 v[14:15], v[34:35], v[14:15]
	v_and_b32_e32 v19, 0xffff0000, v6
	v_cvt_pk_bf16_f32 v11, v14, v15
	global_store_dwordx4 v[32:33], v[8:11], off offset:16
	global_load_dwordx4 v[8:11], v28, s[26:27] offset:64
	s_nop 0
	s_nop 0
	global_load_dwordx4 v[12:15], v28, s[26:27] offset:80
	v_mul_f32_e32 v17, 0xbfb8aa3b, v19
	v_exp_f32_e64 v34, v17
	v_lshlrev_b32_e64 v16, 16, v7
	v_and_b32_e32 v17, 0xffff0000, v7
	v_and_b32_e32 v35, 0xffff0000, v5
	v_add_f32_e64 v7, 1.0, v34
	v_lshlrev_b32_e64 v34, 16, v5
	v_mul_f32_e32 v5, 0xbfb8aa3b, v34
	v_exp_f32_e64 v5, v5
	v_mul_f32_e32 v36, 0xbfb8aa3b, v35
	v_exp_f32_e64 v37, v36
	v_lshlrev_b32_e64 v18, 16, v6
	v_mul_f32_e32 v6, 0xbfb8aa3b, v18
	v_add_f32_e64 v5, 1.0, v5
	v_lshlrev_b32_e64 v38, 16, v4
	v_and_b32_e32 v39, 0xffff0000, v4
	v_exp_f32_e64 v6, v6
	v_rcp_f32_e64 v36, v5
	v_add_f32_e64 v5, 1.0, v37
	v_mul_f32_e32 v4, 0xbfb8aa3b, v38
	v_mul_f32_e32 v37, 0xbfb8aa3b, v39
	v_exp_f32_e64 v4, v4
	v_exp_f32_e64 v42, v37
	v_add_f32_e64 v6, 1.0, v6
	v_rcp_f32_e64 v6, v6
	v_rcp_f32_e64 v7, v7
	v_rcp_f32_e64 v37, v5
	v_add_f32_e64 v4, 1.0, v4
	v_add_f32_e64 v5, 1.0, v42
	v_mul_f32_e32 v42, 0xbfb8aa3b, v16
	v_mul_f32_e32 v43, 0xbfb8aa3b, v17
	v_rcp_f32_e64 v4, v4
	v_exp_f32_e64 v42, v42
	v_exp_f32_e64 v43, v43
	v_rcp_f32_e64 v5, v5
	v_pk_mul_f32 v[6:7], v[6:7], v[18:19]
	v_pk_mul_f32 v[18:19], v[36:37], v[34:35]
	v_pk_mul_f32 v[34:35], v[98:99], v[46:47] op_sel_hi:[1,0]
	v_add_f32_e64 v42, 1.0, v42
	v_add_f32_e64 v43, 1.0, v43
	v_pk_mul_f32 v[4:5], v[4:5], v[38:39]
	v_rcp_f32_e64 v42, v42
	v_rcp_f32_e64 v43, v43
	s_waitcnt vmcnt(1)
	s_nop 0
	v_pk_mul_f32 v[8:9], v[8:9], v[34:35]
	s_nop 0
	s_nop 0
	v_pk_mul_f32 v[4:5], v[4:5], v[8:9]
	v_pk_mul_f32 v[8:9], v[26:27], v[46:47] op_sel_hi:[1,0]
	v_pk_mul_f32 v[16:17], v[42:43], v[16:17]
	v_pk_mul_f32 v[8:9], v[10:11], v[8:9]
	v_pk_mul_f32 v[10:11], v[104:105], v[46:47] op_sel_hi:[1,0]
	v_pk_mul_f32 v[8:9], v[18:19], v[8:9]
	s_waitcnt vmcnt(0)
	s_nop 0
	v_pk_mul_f32 v[10:11], v[12:13], v[10:11]
	v_cvt_pk_bf16_f32 v4, v4, v5
	v_pk_mul_f32 v[6:7], v[6:7], v[10:11]
	v_pk_mul_f32 v[10:11], v[74:75], v[46:47] op_sel_hi:[1,0]
	v_cvt_pk_bf16_f32 v5, v8, v9
	v_pk_mul_f32 v[10:11], v[14:15], v[10:11]
	v_cvt_pk_bf16_f32 v6, v6, v7
	v_pk_mul_f32 v[10:11], v[16:17], v[10:11]
	v_lshlrev_b32_e64 v12, 16, v0
	v_cvt_pk_bf16_f32 v7, v10, v11
	global_store_dwordx4 v[32:33], v[4:7], off offset:32
	global_load_dwordx4 v[4:7], v28, s[26:27] offset:96
	s_nop 0
	s_nop 0
	global_load_dwordx4 v[8:11], v28, s[26:27] offset:112
	v_and_b32_e32 v13, 0xffff0000, v0
	v_mul_f32_e32 v0, 0xbfb8aa3b, v12
	v_exp_f32_e64 v0, v0
	v_mul_f32_e32 v14, 0xbfb8aa3b, v13
	v_exp_f32_e64 v15, v14
	v_add_f32_e64 v0, 1.0, v0
	v_rcp_f32_e64 v14, v0
	v_add_f32_e64 v0, 1.0, v15
	v_rcp_f32_e64 v15, v0
	v_lshlrev_b32_e64 v0, 16, v1
	v_and_b32_e32 v1, 0xffff0000, v1
	v_pk_mul_f32 v[12:13], v[14:15], v[12:13]
	v_mul_f32_e32 v14, 0xbfb8aa3b, v0
	v_exp_f32_e64 v16, v14
	v_pk_mul_f32 v[14:15], v[40:41], v[46:47] op_sel_hi:[1,0]
	s_waitcnt vmcnt(1)
; #define LAS __attribute__((address_space(3)))
; __device__ __forceinline__ void ret_sample_unit(PR P, LAS float* lds, const int b, const int h, const int wv) {
;     const int tid = fresh_tid(wv), lane = tid & 63, wid = tid >> 6;
;     const bf16_t* PS = (const bf16_t*)(P.ws + WS_BIG); bf16_t* Y = (bf16_t*)(P.ws + WS_XN);
;     const float* rc = (const float*)(P.ws + WS_ROPE); const float* rs = rc + 2052 * 64;
;     LAS float* q = lds; LAS float* k = lds + 512; LAS float* v = lds + 1024; LAS float* Pm = lds + 1536; LAS float* y2p = lds + 1600; LAS float* red = lds + 1600 + 2048;
;     const float lg2 = log2f(1.0f - exp2f(-5.0f - (float)h));
;     const int row0 = MP + b * 4;
;     { const int t = (tid & 255) >> 6, f = tid & 63; const bf16_t* src = PS + (size_t)(row0 + t) * NCOLS + 1792 + h * 128;
;       if (tid < 256) { const float cs = rc[(2048 + t) * 64 + f], sn = rs[(2048 + t) * 64 + f];
;           const float q1 = bf2f(src[f]), q2 = bf2f(src[f + 64]); q[t * 128 + f] = q1 * cs - q2 * sn; q[t * 128 + f + 64] = q1 * sn + q2 * cs;
;           const float k1 = bf2f(src[512 + f]), k2 = bf2f(src[512 + f + 64]); k[t * 128 + f] = (k1 * cs - k2 * sn) * 0.08838834764831845f; k[t * 128 + f + 64] = (k1 * sn + k2 * cs) * 0.08838834764831845f; }
;       else { v[t * 128 + f] = bf2f(src[1024 + f]); v[t * 128 + f + 64] = bf2f(src[1024 + f + 64]); } }
;     __syncthreads();
;     if (wid == 0) { const int pi = lane >> 4, pj = (lane >> 2) & 3, part = lane & 3; float s = 0.f;
; __device__ __forceinline__ void ret_unit_c(PR P, LAS unsigned char* lds, const int bh, const int n, const int wv) {
;     ...
;       for (int x = 0; x < 4; ++x) { const u32x4 g4 = *(const u32x4*)(gp + x * 8); const float4 w0 = *(const float4*)(gw + x * 8), w1 = *(const float4*)(gw + x * 8 + 4);
;           const float gg[8] = {lo_bf(g4.x), hi_bf(g4.x), lo_bf(g4.y), hi_bf(g4.y), lo_bf(g4.z), hi_bf(g4.z), lo_bf(g4.w), hi_bf(g4.w)}; const float ww[8] = {w0.x, w0.y, w0.z, w0.w, w1.x, w1.y, w1.z, w1.w};
;           float o[8];
; #pragma unroll
;           for (int z = 0; z < 8; ++z) o[z] = yv[x * 8 + z] * rstd * ww[z] * (gg[z] * __builtin_amdgcn_rcpf(1.0f + __expf(-gg[z])));
;           u32x4 w; w.x = pg8::cvt_pk_bf16(o[0], o[1]); w.y = pg8::cvt_pk_bf16(o[2], o[3]); w.z = pg8::cvt_pk_bf16(o[4], o[5]); w.w = pg8::cvt_pk_bf16(o[6], o[7]);
;           *(u32x4*)(yo + x * 8) = w; } }
	s_nop 0
	v_pk_mul_f32 v[4:5], v[4:5], v[14:15]
	s_nop 0
	s_nop 0
	v_pk_mul_f32 v[4:5], v[12:13], v[4:5]
	v_mul_f32_e32 v13, 0xbfb8aa3b, v1
	v_exp_f32_e64 v13, v13
	v_add_f32_e64 v12, 1.0, v16
	v_rcp_f32_e64 v12, v12
	v_pk_mul_f32 v[14:15], v[24:25], v[46:47] op_sel_hi:[1,0]
	v_add_f32_e64 v13, 1.0, v13
	v_rcp_f32_e64 v13, v13
	v_pk_mul_f32 v[6:7], v[6:7], v[14:15]
	v_lshlrev_b32_e64 v14, 16, v2
	v_mul_f32_e32 v15, 0xbfb8aa3b, v14
	v_exp_f32_e64 v16, v15
	v_pk_mul_f32 v[0:1], v[12:13], v[0:1]
	v_and_b32_e32 v15, 0xffff0000, v2
	v_pk_mul_f32 v[6:7], v[0:1], v[6:7]
	v_mul_f32_e32 v1, 0xbfb8aa3b, v15
	v_exp_f32_e64 v1, v1
	v_pk_mul_f32 v[12:13], v[22:23], v[46:47] op_sel_hi:[1,0]
	v_lshlrev_b32_e64 v2, 16, v3
	v_and_b32_e32 v3, 0xffff0000, v3
	s_waitcnt vmcnt(0)
	s_nop 0
	v_pk_mul_f32 v[8:9], v[8:9], v[12:13]
	v_mul_f32_e32 v12, 0xbfb8aa3b, v2
	v_mul_f32_e32 v13, 0xbfb8aa3b, v3
	v_exp_f32_e64 v12, v12
	v_exp_f32_e64 v13, v13
	v_add_f32_e64 v0, 1.0, v16
	v_add_f32_e64 v1, 1.0, v1
	v_rcp_f32_e64 v0, v0
	v_rcp_f32_e64 v1, v1
	v_add_f32_e64 v12, 1.0, v12
	v_add_f32_e64 v13, 1.0, v13
	v_rcp_f32_e64 v12, v12
	v_rcp_f32_e64 v13, v13
	v_pk_mul_f32 v[0:1], v[0:1], v[14:15]
	v_pk_mul_f32 v[2:3], v[12:13], v[2:3]
	v_pk_mul_f32 v[8:9], v[0:1], v[8:9]
	v_pk_mul_f32 v[0:1], v[20:21], v[46:47] op_sel_hi:[1,0]
	s_nop 0
	s_nop 0
	v_pk_mul_f32 v[0:1], v[10:11], v[0:1]
	s_nop 0
	s_nop 0
	v_pk_mul_f32 v[10:11], v[2:3], v[0:1]
	v_cvt_pk_bf16_f32 v0, v4, v5
	v_cvt_pk_bf16_f32 v1, v6, v7
	v_cvt_pk_bf16_f32 v2, v8, v9
	v_cvt_pk_bf16_f32 v3, v10, v11
	global_store_dwordx4 v[32:33], v[0:3], off offset:48
	s_barrier
	s_cbranch_scc0 .LBB0_654
	s_cmpk_gt_i32 s2, 0xa7f
	s_cbranch_scc1 .LBB0_689
	s_add_u32 s18, s10, 0x3d44800
	s_addc_u32 s19, s11, 0
	s_nop 0
	s_add_u32 s6, s8, 0x5588000
	s_addc_u32 s7, s9, 0
	s_nop 0
	s_add_u32 s20, s10, 0xea84800
	s_addc_u32 s21, s11, 0
	s_nop 0
	s_add_u32 s22, s10, 0xda04800
	s_addc_u32 s23, s11, 0
	s_nop 0
	s_add_u32 s24, s10, 0xbae4800
	s_addc_u32 s25, s11, 0
	s_nop 0
	s_add_u32 s26, s8, 0x4588000
	s_addc_u32 s27, s9, 0
	s_and_b32 s44, s2, 3
	v_cvt_f32_ubyte0_e64 v0, s44
	v_sub_f32_e32 v0, 0xc0a00000, v0
	s_mov_b32 s45, 0xc2fc0000
	v_mov_b32_e32 v72, 0x42800000
	v_cmp_gt_f32_e64 vcc, s45, v0
	s_and_b64 s[8:9], vcc, exec
	s_nop 0
	s_cselect_b32 s8, 0xffffffc0, 0
	v_cndmask_b32_e64 v1, 0, v72, vcc
	v_add_f32_e64 v0, v0, v1
	v_exp_f32_e64 v0, v0
	s_mov_b32 s46, 0x800000
	v_mov_b32_e32 v1, 0x42000000
	s_mov_b32 s29, 0
	s_nop 0
	v_ldexp_f32 v0, v0, s8
	v_sub_f32_e64 v0, 1.0, v0
	v_cmp_gt_f32_e64 vcc, s46, v0
	s_and_b64 s[8:9], vcc, exec
	s_cselect_b32 s8, 32, 0
	v_ldexp_f32 v0, v0, s8
	v_log_f32_e64 v0, v0
	v_cndmask_b32_e64 v1, 0, v1, vcc
	s_lshl_b32 s47, s44, 7
	s_movk_i32 s57, 0xf00
	v_sub_f32_e64 v73, v0, v1
	v_add_f32_e64 v2, v73, v73
	v_cmp_gt_f32_e64 vcc, s45, v2
	v_mul_f32_e64 v0, 4.0, v73
	s_and_b64 s[8:9], vcc, exec
	s_nop 0
	v_cndmask_b32_e64 v2, 0, v72, vcc
	v_fmac_f32_e64 v2, 2.0, v73
	v_cmp_gt_f32_e64 vcc, s45, v0
	v_exp_f32_e64 v2, v2
	s_cselect_b32 s8, 0xffffffc0, 0
	v_cndmask_b32_e64 v0, 0, v72, vcc
	v_fmac_f32_e64 v0, 4.0, v73
	v_exp_f32_e64 v0, v0
	v_mul_f32_e32 v1, 0x40400000, v73
	v_ldexp_f32 v74, v2, s8
	s_and_b64 s[8:9], vcc, exec
	s_nop 0
	s_cselect_b32 s8, 0xffffffc0, 0
	v_cmp_gt_f32_e64 vcc, s45, v1
	v_ldexp_f32 v75, v0, s8
	s_and_b64 s[8:9], vcc, exec
	s_nop 0
	v_cndmask_b32_e64 v0, 0, v72, vcc
	v_fmac_f32_e32 v0, 0x40400000, v73
	v_cmp_gt_f32_e64 vcc, s45, v73
	v_exp_f32_e64 v0, v0
	s_cselect_b32 s8, 0xffffffc0, 0
	v_cndmask_b32_e64 v1, 0, v72, vcc
	v_add_f32_e64 v1, v73, v1
	v_exp_f32_e64 v1, v1
	v_ldexp_f32 v76, v0, s8
	s_and_b64 s[8:9], vcc, exec
	s_nop 0
	s_cselect_b32 s8, 0xffffffc0, 0
	v_ldexp_f32 v77, v1, s8
	s_lshl_b32 s8, s44, 8
	s_add_u32 s30, s4, s8
	s_addc_u32 s31, s5, 0
	s_add_u32 s34, s18, s8
	s_addc_u32 s35, s19, 0
	s_lshr_b32 s8, s49, 4
	s_add_i32 s4, s8, 0x4200
	s_lshl_b32 s5, s8, 9
	s_lshl_b32 s9, s2, 5
	s_lshl_b32 s8, s8, 2
	s_nop 0
	s_add_i32 s55, s9, 0xfffff000
	s_add_i32 s56, s8, 0x4010
	v_mov_b32_e64 v25, 0
	s_movk_i32 s60, 0xff
	s_nop 0
	s_mov_b64 s[36:37], 0xe00
	s_movk_i32 s61, 0xff90
	s_movk_i32 s62, 0x1e00
	s_movk_i32 s63, 0x1000
	s_nop 0
	v_mov_b32_e32 v78, 0x3727c5ac
	s_movk_i32 s64, 0x7fff
	s_movk_i32 s65, 0x600
	v_mov_b32_e32 v79, 0x80000
	v_not_b32_e64 v80, 63
	v_mov_b32_e32 v81, 0xffffe000
	s_branch .LBB0_659
	.p2alignl 3, 3212836864
.LBB0_657:
	s_or_b64 exec, exec, s[8:9]
	.p2alignl 3, 3212836864
.LBB0_658:
	s_add_i32 s8, s49, 0x80
	s_add_i32 s4, s4, 8
	s_addk_i32 s5, 0x1000
	s_addk_i32 s55, 0x1000
	s_add_i32 s56, s56, 32
	s_cmpk_lt_i32 s49, 0x980
	s_mov_b32 s49, s8
	s_cbranch_scc0 .LBB0_689
	.p2alignl 3, 3212836864
.LBB0_659:
	s_cmpk_gt_i32 s49, 0x7ff
	s_mov_b64 s[8:9], -1
	s_cbranch_scc0 .LBB0_672
	s_nop 0
	s_and_b32 s13, s49, 0x7ffffffc
	v_mbcnt_lo_u32_b32 v2, -1, 0
	v_mbcnt_hi_u32_b32 v2, -1, v2
	s_add_i32 s12, s13, 0x3800
	v_add_u32_e64 v83, s33, v2
	v_bfe_u32 v3, v83, 6, 2
	v_or_b32_e64 v0, s12, v3
	v_and_b32_e64 v82, 63, v2
	v_mul_lo_u32 v24, v0, s57
	v_lshl_add_u64 v[0:1], v[24:25], 1, s[34:35]
	v_cmp_lt_i32_e64 vcc, s60, v83
	v_lshlrev_b32_e64 v24, 1, v82
	s_waitcnt vmcnt(0)
	s_nop 0
	v_lshlrev_b32_e64 v4, 2, v82
	s_and_saveexec_b64 s[8:9], vcc
	s_xor_b64 s[8:9], exec, s[8:9]
	s_cbranch_execz .LBB0_662
	s_nop 0
	v_lshl_add_u64 v[0:1], v[0:1], 0, v[24:25]
	v_lshl_add_u64 v[0:1], v[0:1], 0, s[36:37]
	global_load_ushort v5, v[0:1], off offset:2048
	s_nop 0
	s_nop 0
	global_load_ushort v0, v[0:1], off offset:2176
	v_lshlrev_b32_e64 v1, 9, v3
	v_add3_u32 v1, 0, v1, v4
	s_waitcnt vmcnt(1)
	s_nop 0
	v_lshlrev_b32_e64 v3, 16, v5
	s_waitcnt vmcnt(0)
	s_nop 0
	v_lshlrev_b32_e64 v0, 16, v0
	ds_write2st64_b32 v1, v3, v0 offset0:16 offset1:17
	.p2alignl 3, 3212836864
; __device__ __forceinline__ float bf2f(unsigned b) { return __uint_as_float(b << 16); }
; __device__ __forceinline__ float quad_sum(float v) { v += dppf<0xB1>(v); v += dppf<0x4E>(v); return v; }
; __device__ __forceinline__ void ret_sample_unit(PR P, LAS float* lds, const int b, const int h, const int wv) {
;     ...
;     { const int t = (tid & 255) >> 6, f = tid & 63; const bf16_t* src = PS + (size_t)(row0 + t) * NCOLS + 1792 + h * 128;
;       if (tid < 256) { const float cs = rc[(2048 + t) * 64 + f], sn = rs[(2048 + t) * 64 + f];
;           const float q1 = bf2f(src[f]), q2 = bf2f(src[f + 64]); q[t * 128 + f] = q1 * cs - q2 * sn; q[t * 128 + f + 64] = q1 * sn + q2 * cs;
;           const float k1 = bf2f(src[512 + f]), k2 = bf2f(src[512 + f + 64]); k[t * 128 + f] = (k1 * cs - k2 * sn) * 0.08838834764831845f; k[t * 128 + f + 64] = (k1 * sn + k2 * cs) * 0.08838834764831845f; }
;       else { v[t * 128 + f] = bf2f(src[1024 + f]); v[t * 128 + f + 64] = bf2f(src[1024 + f + 64]); } }
;     __syncthreads();
;     if (wid == 0) { const int pi = lane >> 4, pj = (lane >> 2) & 3, part = lane & 3; float s = 0.f;
;         for (int d = part * 32; d < part * 32 + 32; ++d) s += q[pi * 128 + d] * k[pj * 128 + d];
;         s = quad_sum(s); if (part == 0) Pm[pi * 4 + pj] = pi >= pj ? s * exp2f(lg2 * (float)(pi - pj)) : 0.f; }
.LBB0_662:
	s_andn2_saveexec_b64 s[8:9], s[8:9]
	s_cbranch_execz .LBB0_664
	v_and_b32_e32 v5, 0xff, v83
	v_lshl_add_u64 v[0:1], v[0:1], 0, v[24:25]
	v_lshl_or_b32 v5, v5, 2, v79
	v_lshl_add_u64 v[6:7], v[0:1], 0, s[36:37]
	global_load_ushort v8, v[0:1], off offset:3584
	s_nop 0
	s_nop 0
	global_load_ushort v0, v[0:1], off offset:3712
	s_nop 0
	s_nop 0
	global_load_ushort v1, v[6:7], off offset:1024
	s_nop 0
	s_nop 0
	global_load_ushort v6, v[6:7], off offset:1152
	s_nop 0
	s_nop 0
	global_load_dword v7, v5, s[16:17]
	s_nop 0
	s_nop 0
	global_load_dword v5, v5, s[14:15]
	v_lshl_or_b32 v3, v3, 9, v4
	v_add_u32_e64 v3, 0, v3
	s_waitcnt vmcnt(5)
	s_nop 0
	v_lshlrev_b32_e64 v4, 16, v8
	s_waitcnt vmcnt(4)
	s_nop 0
	v_lshlrev_b32_e64 v0, 16, v0
	s_waitcnt vmcnt(3)
	s_nop 0
	v_lshlrev_b32_e64 v1, 16, v1
	s_waitcnt vmcnt(2)
	s_nop 0
	v_lshlrev_b32_e64 v6, 16, v6
	s_waitcnt vmcnt(1)
	s_nop 0
	v_mul_f32_e64 v8, v7, v0
	s_waitcnt vmcnt(0)
	s_nop 0
	v_mul_f32_e64 v0, v5, v0
	v_mul_f32_e64 v9, v7, v6
	v_mul_f32_e64 v6, v5, v6
	v_fma_f32 v8, v5, v4, -v8
	v_fmac_f32_e64 v0, v7, v4
	v_fma_f32 v4, v5, v1, -v9
	v_fmac_f32_e64 v6, v7, v1
	ds_write2st64_b32 v3, v8, v0 offset1:1
	v_mul_f32_e32 v0, 0x3db504f3, v4
	v_mul_f32_e32 v1, 0x3db504f3, v6
	ds_write2st64_b32 v3, v0, v1 offset0:8 offset1:9
	.p2alignl 3, 3212836864
.LBB0_664:
	s_or_b64 exec, exec, s[8:9]
	s_addk_i32 s13, 0xf800
	v_cmp_gt_u32_e64 vcc, 64, v83
	s_waitcnt lgkmcnt(0)
	s_barrier
	s_and_saveexec_b64 s[10:11], vcc
	s_cbranch_execz .LBB0_667
	v_lshrrev_b32_e64 v1, 4, v83
	v_and_b32_e64 v24, 3, v2
	v_lshlrev_b32_e64 v3, 9, v1
	v_lshlrev_b32_e64 v13, 7, v24
	v_add3_u32 v3, 0, v3, v13
	ds_read_b128 v[4:7], v3
	ds_read_b128 v[8:11], v3 offset:16
	v_bfe_u32 v0, v2, 2, 2
	v_lshlrev_b32_e64 v12, 9, v0
	v_add3_u32 v38, 0, v12, v13
	ds_read_b128 v[12:15], v38 offset:2048
	ds_read_b128 v[16:19], v3 offset:32
	ds_read_b128 v[20:23], v3 offset:48
	ds_read_b128 v[26:29], v38 offset:2064
	ds_read_b128 v[30:33], v38 offset:2080
	ds_read_b128 v[34:37], v38 offset:2096
	s_waitcnt lgkmcnt(5)
	s_nop 0
	v_fma_f32 v39, v4, v12, 0
	v_fmac_f32_e64 v39, v5, v13
	v_fmac_f32_e64 v39, v6, v14
	v_fmac_f32_e64 v39, v7, v15
	s_waitcnt lgkmcnt(2)
	s_nop 0
	v_fmac_f32_e64 v39, v8, v26
	v_fmac_f32_e64 v39, v9, v27
	v_fmac_f32_e64 v39, v10, v28
	v_fmac_f32_e64 v39, v11, v29
	s_waitcnt lgkmcnt(1)
	s_nop 0
	v_fmac_f32_e64 v39, v16, v30
	v_fmac_f32_e64 v39, v17, v31
	v_fmac_f32_e64 v39, v18, v32
	v_fmac_f32_e64 v39, v19, v33
	ds_read_b128 v[4:7], v3 offset:64
	ds_read_b128 v[8:11], v38 offset:2112
	s_waitcnt lgkmcnt(2)
	s_nop 0
	v_fmac_f32_e64 v39, v20, v34
	v_fmac_f32_e64 v39, v21, v35
	v_fmac_f32_e64 v39, v22, v36
	v_fmac_f32_e64 v39, v23, v37
	ds_read_b128 v[12:15], v3 offset:80
	ds_read_b128 v[16:19], v38 offset:2128
	s_waitcnt lgkmcnt(2)
	s_nop 0
	v_fmac_f32_e64 v39, v4, v8
	v_fmac_f32_e64 v39, v5, v9
	v_fmac_f32_e64 v39, v6, v10
	v_fmac_f32_e64 v39, v7, v11
	ds_read_b128 v[4:7], v3 offset:96
	ds_read_b128 v[8:11], v38 offset:2144
	s_waitcnt lgkmcnt(2)
	s_nop 0
	v_fmac_f32_e64 v39, v12, v16
	v_fmac_f32_e64 v39, v13, v17
	v_fmac_f32_e64 v39, v14, v18
	v_fmac_f32_e64 v39, v15, v19
	ds_read_b128 v[12:15], v3 offset:112
	ds_read_b128 v[16:19], v38 offset:2160
	s_waitcnt lgkmcnt(2)
	s_nop 0
	v_fmac_f32_e64 v39, v4, v8
	v_fmac_f32_e64 v39, v5, v9
	v_fmac_f32_e64 v39, v6, v10
	v_fmac_f32_e64 v39, v7, v11
	s_waitcnt lgkmcnt(0)
	s_nop 0
	v_fmac_f32_e64 v39, v12, v16
	v_fmac_f32_e64 v39, v13, v17
	v_fmac_f32_e64 v39, v14, v18
	v_fmac_f32_e64 v39, v15, v19
	v_mov_b32_e64 v4, v25
	v_cmp_eq_u32_e64 vcc, 0, v24
	v_add_f32_dpp v3, v39, v39 quad_perm:[1,0,3,2] row_mask:0xf bank_mask:0xf bound_ctrl:1
	s_nop 1
	s_nop 0
	v_mov_b32_dpp v4, v3 quad_perm:[2,3,0,1] row_mask:0xf bank_mask:0xf
	s_and_b64 exec, exec, vcc
	s_cbranch_execz .LBB0_667
	v_sub_co_u32_e64 v1, vcc, v1, v0
	v_cvt_f32_u32_e64 v1, v1
	v_add_f32_e64 v3, v3, v4
	v_and_b32_e64 v2, 48, v2
	v_lshlrev_b32_e64 v0, 2, v0
	v_mul_f32_e64 v4, v73, v1
	v_cmp_gt_f32_e64 s[8:9], s45, v4
	v_add3_u32 v0, 0, v2, v0
	s_nop 0
	s_nop 0
	v_cndmask_b32_e64 v4, 0, v72, s[8:9]
	v_fmac_f32_e64 v4, v73, v1
	v_exp_f32_e64 v1, v4
	v_cndmask_b32_e64 v4, 0, v80, s[8:9]
	v_ldexp_f32 v1, v1, v4
	v_mul_f32_e64 v1, v1, v3
	v_cndmask_b32_e64 v1, v1, 0, vcc
	ds_write_b32 v0, v1 offset:6144
	.p2alignl 3, 3212836864
; __device__ __forceinline__ void ret_sample_unit(PR P, LAS float* lds, const int b, const int h, const int wv) {
;     ...
;     { const int e = tid & 127, dg = tid >> 7; const float c4 = exp2f(lg2 * 4.0f), g3 = exp2f(lg2 * 3.0f), g2_ = exp2f(lg2 * 2.0f), g1 = exp2f(lg2);
;       const float v0 = v[e] * g3, v1 = v[128 + e] * g2_, v2 = v[256 + e] * g1, v3 = v[384 + e];
;       const float* S0 = P.state_ret + ((size_t)(b * 4 + h) * 128) * 128 + e; float* So = P.out + O_RTS + ((size_t)(b * 4 + h) * 128) * 128 + e;
;       float a0 = 0.f, a1 = 0.f, a2 = 0.f, a3 = 0.f;
;       float sv[32];
; #pragma unroll
;       for (int x = 0; x < 32; ++x) sv[x] = S0[(size_t)(dg * 32 + x) * 128];
.LBB0_667:
	s_or_b64 exec, exec, s[10:11]
	s_nop 0
	s_load_dwordx2 s[8:9], s[38:39], 0x20
	s_or_b32 s10, s13, s44
	s_lshl_b32 s28, s10, 14
	v_ashrrev_i32_e64 v85, 7, v83
	s_lshl_b64 s[10:11], s[28:29], 2
	s_nop 0
	v_and_b32_e32 v84, 0x7f, v83
	s_waitcnt lgkmcnt(0)
	s_add_u32 s8, s8, s10
	v_lshlrev_b32_e64 v4, 5, v85
	v_lshlrev_b32_e64 v24, 2, v84
	s_addc_u32 s9, s9, s11
	s_nop 0
	v_ashrrev_i32_e64 v5, 31, v4
	v_or_b32_e64 v10, 1, v4
	v_or_b32_e64 v12, 2, v4
	v_or_b32_e64 v14, 3, v4
	v_or_b32_e64 v16, 4, v4
	v_or_b32_e64 v18, 5, v4
	v_or_b32_e64 v20, 6, v4
	v_or_b32_e64 v22, 7, v4
	v_lshl_add_u64 v[8:9], s[8:9], 0, v[24:25]
	v_lshlrev_b64 v[70:71], 9, v[4:5]
	v_ashrrev_i32_e64 v11, 31, v10
	v_ashrrev_i32_e64 v13, 31, v12
	v_ashrrev_i32_e64 v15, 31, v14
	v_ashrrev_i32_e64 v17, 31, v16
	v_ashrrev_i32_e64 v19, 31, v18
	v_ashrrev_i32_e64 v21, 31, v20
	v_ashrrev_i32_e64 v23, 31, v22
	v_add_u32_e64 v87, 0, v24
	v_lshl_add_u64 v[6:7], v[8:9], 0, v[70:71]
	v_lshlrev_b64 v[68:69], 9, v[10:11]
	v_lshlrev_b64 v[66:67], 9, v[12:13]
	v_lshlrev_b64 v[64:65], 9, v[14:15]
	v_lshlrev_b64 v[62:63], 9, v[16:17]
	v_lshlrev_b64 v[60:61], 9, v[18:19]
	v_lshlrev_b64 v[58:59], 9, v[20:21]
	v_lshlrev_b64 v[56:57], 9, v[22:23]
	ds_read2st64_b32 v[2:3], v87 offset0:16 offset1:18
	ds_read2st64_b32 v[0:1], v87 offset0:20 offset1:22
	v_lshl_add_u64 v[10:11], v[8:9], 0, v[68:69]
	v_lshl_add_u64 v[12:13], v[8:9], 0, v[66:67]
	v_lshl_add_u64 v[14:15], v[8:9], 0, v[64:65]
	v_lshl_add_u64 v[16:17], v[8:9], 0, v[62:63]
	v_lshl_add_u64 v[18:19], v[8:9], 0, v[60:61]
	v_lshl_add_u64 v[20:21], v[8:9], 0, v[58:59]
	v_lshl_add_u64 v[22:23], v[8:9], 0, v[56:57]
	global_load_dword v113, v[6:7], off
	global_load_dword v178, v[10:11], off
	global_load_dword v179, v[12:13], off
	global_load_dword v180, v[14:15], off
	global_load_dword v181, v[16:17], off
	global_load_dword v182, v[18:19], off
	global_load_dword v183, v[20:21], off
	global_load_dword v184, v[22:23], off
	v_or_b32_e64 v6, 8, v4
	v_ashrrev_i32_e64 v7, 31, v6
	v_or_b32_e64 v10, 9, v4
	v_or_b32_e64 v12, 10, v4
	v_or_b32_e64 v14, 11, v4
	v_or_b32_e64 v16, 12, v4
	v_or_b32_e64 v18, 13, v4
	v_or_b32_e64 v20, 14, v4
	v_or_b32_e64 v22, 15, v4
	v_lshlrev_b64 v[54:55], 9, v[6:7]
	v_ashrrev_i32_e64 v11, 31, v10
	v_ashrrev_i32_e64 v13, 31, v12
	v_ashrrev_i32_e64 v15, 31, v14
	v_ashrrev_i32_e64 v17, 31, v16
	v_ashrrev_i32_e64 v19, 31, v18
	v_ashrrev_i32_e64 v21, 31, v20
	v_ashrrev_i32_e64 v23, 31, v22
	v_lshl_add_u64 v[6:7], v[8:9], 0, v[54:55]
	v_lshlrev_b64 v[52:53], 9, v[10:11]
	v_lshlrev_b64 v[50:51], 9, v[12:13]
	v_lshlrev_b64 v[48:49], 9, v[14:15]
	v_lshlrev_b64 v[46:47], 9, v[16:17]
	v_lshlrev_b64 v[44:45], 9, v[18:19]
	v_lshlrev_b64 v[42:43], 9, v[20:21]
	v_lshlrev_b64 v[40:41], 9, v[22:23]
	v_lshl_add_u64 v[10:11], v[8:9], 0, v[52:53]
	v_lshl_add_u64 v[12:13], v[8:9], 0, v[50:51]
	v_lshl_add_u64 v[14:15], v[8:9], 0, v[48:49]
	v_lshl_add_u64 v[16:17], v[8:9], 0, v[46:47]
	v_lshl_add_u64 v[18:19], v[8:9], 0, v[44:45]
	v_lshl_add_u64 v[20:21], v[8:9], 0, v[42:43]
	v_lshl_add_u64 v[22:23], v[8:9], 0, v[40:41]
	global_load_dword v185, v[6:7], off
	global_load_dword v186, v[10:11], off
	global_load_dword v187, v[12:13], off
	global_load_dword v112, v[14:15], off
	global_load_dword v111, v[16:17], off
	global_load_dword v110, v[18:19], off
	global_load_dword v109, v[20:21], off
	global_load_dword v108, v[22:23], off
	v_or_b32_e64 v6, 16, v4
	v_ashrrev_i32_e64 v7, 31, v6
	v_or_b32_e64 v10, 17, v4
	v_or_b32_e64 v12, 18, v4
	v_or_b32_e64 v14, 19, v4
	v_or_b32_e64 v16, 20, v4
	v_or_b32_e64 v18, 21, v4
	v_or_b32_e64 v20, 22, v4
	v_or_b32_e64 v22, 23, v4
	v_lshlrev_b64 v[38:39], 9, v[6:7]
	v_ashrrev_i32_e64 v11, 31, v10
	v_ashrrev_i32_e64 v13, 31, v12
	v_ashrrev_i32_e64 v15, 31, v14
	v_ashrrev_i32_e64 v17, 31, v16
	v_ashrrev_i32_e64 v19, 31, v18
	v_ashrrev_i32_e64 v21, 31, v20
	v_ashrrev_i32_e64 v23, 31, v22
	v_lshl_add_u64 v[6:7], v[8:9], 0, v[38:39]
	v_lshlrev_b64 v[36:37], 9, v[10:11]
	v_lshlrev_b64 v[34:35], 9, v[12:13]
	v_lshlrev_b64 v[32:33], 9, v[14:15]
	v_lshlrev_b64 v[30:31], 9, v[16:17]
	v_lshlrev_b64 v[28:29], 9, v[18:19]
	v_lshlrev_b64 v[26:27], 9, v[20:21]
	v_lshlrev_b64 v[22:23], 9, v[22:23]
	v_lshl_add_u64 v[10:11], v[8:9], 0, v[36:37]
	v_lshl_add_u64 v[12:13], v[8:9], 0, v[34:35]
	v_lshl_add_u64 v[14:15], v[8:9], 0, v[32:33]
	v_lshl_add_u64 v[16:17], v[8:9], 0, v[30:31]
	v_lshl_add_u64 v[18:19], v[8:9], 0, v[28:29]
	v_lshl_add_u64 v[20:21], v[8:9], 0, v[26:27]
	v_lshl_add_u64 v[88:89], v[8:9], 0, v[22:23]
	global_load_dword v107, v[6:7], off
	global_load_dword v106, v[10:11], off
	global_load_dword v105, v[12:13], off
	global_load_dword v104, v[14:15], off
	global_load_dword v103, v[16:17], off
	global_load_dword v102, v[18:19], off
	global_load_dword v101, v[20:21], off
	global_load_dword v100, v[88:89], off
	v_or_b32_e64 v6, 24, v4
	v_ashrrev_i32_e64 v7, 31, v6
	v_lshlrev_b64 v[20:21], 9, v[6:7]
	v_or_b32_e64 v6, 25, v4
	v_ashrrev_i32_e64 v7, 31, v6
	v_lshlrev_b64 v[18:19], 9, v[6:7]
	v_or_b32_e64 v6, 26, v4
	v_ashrrev_i32_e64 v7, 31, v6
	v_lshlrev_b64 v[16:17], 9, v[6:7]
	v_or_b32_e64 v6, 27, v4
	v_ashrrev_i32_e64 v7, 31, v6
	v_lshlrev_b64 v[14:15], 9, v[6:7]
	v_or_b32_e64 v6, 28, v4
	v_ashrrev_i32_e64 v7, 31, v6
	v_lshlrev_b64 v[12:13], 9, v[6:7]
	v_or_b32_e64 v6, 29, v4
	v_ashrrev_i32_e64 v7, 31, v6
	v_lshlrev_b64 v[10:11], 9, v[6:7]
	v_or_b32_e64 v6, 30, v4
	v_or_b32_e64 v4, 31, v4
	v_ashrrev_i32_e64 v7, 31, v6
	v_ashrrev_i32_e64 v5, 31, v4
	v_lshl_add_u64 v[88:89], v[8:9], 0, v[20:21]
	v_lshl_add_u64 v[90:91], v[8:9], 0, v[18:19]
	v_lshl_add_u64 v[92:93], v[8:9], 0, v[16:17]
	v_lshlrev_b64 v[6:7], 9, v[6:7]
	v_lshlrev_b64 v[4:5], 9, v[4:5]
	v_lshl_add_u64 v[96:97], v[8:9], 0, v[14:15]
	v_lshl_add_u64 v[114:115], v[8:9], 0, v[12:13]
	v_lshl_add_u64 v[116:117], v[8:9], 0, v[10:11]
	v_lshl_add_u64 v[118:119], v[8:9], 0, v[6:7]
	v_lshl_add_u64 v[8:9], v[8:9], 0, v[4:5]
	global_load_dword v99, v[88:89], off
	global_load_dword v95, v[90:91], off
	global_load_dword v94, v[92:93], off
	s_nop 0
	s_nop 0
	global_load_dword v93, v[96:97], off
	global_load_dword v92, v[114:115], off
	global_load_dword v91, v[116:117], off
	global_load_dword v90, v[118:119], off
	global_load_dword v88, v[8:9], off
	s_waitcnt lgkmcnt(1)
; __device__ __forceinline__ void ret_sample_unit(PR P, LAS float* lds, const int b, const int h, const int wv) {
;     ...
; #pragma unroll
;       for (int x = 0; x < 32; ++x) { const int d = dg * 32 + x; const float s = sv[x];
;           a0 = fmaf(q[d], s, a0); a1 = fmaf(q[128 + d], s, a1); a2 = fmaf(q[256 + d], s, a2); a3 = fmaf(q[384 + d], s, a3);
;           So[(size_t)d * 128] = s * c4 + k[d] * v0 + k[128 + d] * v1 + k[256 + d] * v2 + k[384 + d] * v3; }
	s_nop 0
	v_mul_f32_e64 v89, v76, v2
	v_and_b32_e32 v2, 0xffffff80, v83
	v_add_u32_e64 v2, 0, v2
	ds_read_b128 v[114:117], v2
	ds_read_b128 v[118:121], v2 offset:512
	ds_read_b128 v[122:125], v2 offset:16
	ds_read_b128 v[126:129], v2 offset:1024
	ds_read_b128 v[130:133], v2 offset:528
	ds_read_b128 v[134:137], v2 offset:1536
	ds_read_b128 v[138:141], v2 offset:2048
	ds_read_b128 v[142:145], v2 offset:1040
	ds_read_b128 v[154:157], v2 offset:2560
	s_add_u32 s8, s6, s10
	s_addc_u32 s9, s7, s11
	v_lshl_add_u64 v[8:9], s[8:9], 0, v[24:25]
	s_waitcnt vmcnt(31) lgkmcnt(8)
	s_nop 0
	v_fma_f32 v24, v114, v113, 0
	ds_read_b128 v[146:149], v2 offset:1552
	ds_read_b128 v[150:153], v2 offset:2064
	s_waitcnt lgkmcnt(4)
	s_nop 0
	v_mul_f32_e64 v114, v89, v138
	ds_read_b128 v[158:161], v2 offset:3072
	ds_read_b128 v[162:165], v2 offset:3584
	ds_read_b128 v[166:169], v2 offset:2576
	v_mul_f32_e64 v3, v74, v3
	v_fmac_f32_e64 v114, v75, v113
	v_mul_f32_e64 v0, v77, v0
	s_waitcnt lgkmcnt(5)
	s_nop 0
	v_fmac_f32_e64 v114, v3, v154
	s_waitcnt lgkmcnt(2)
	s_nop 0
	v_fmac_f32_e64 v114, v0, v158
	s_waitcnt lgkmcnt(1)
	s_nop 0
	v_fmac_f32_e64 v114, v1, v162
	v_lshl_add_u64 v[70:71], v[8:9], 0, v[70:71]
	global_store_dword v[70:71], v114, off
	v_mul_f32_e64 v70, v89, v139
	s_waitcnt vmcnt(31)
	s_nop 0
	v_fmac_f32_e64 v70, v75, v178
	v_fmac_f32_e64 v70, v3, v155
	v_fmac_f32_e64 v70, v0, v159
	v_fmac_f32_e64 v70, v1, v163
	v_lshl_add_u64 v[68:69], v[8:9], 0, v[68:69]
	global_store_dword v[68:69], v70, off
	v_mul_f32_e64 v68, v89, v140
	s_waitcnt vmcnt(31)
	s_nop 0
	v_fmac_f32_e64 v68, v75, v179
	v_fmac_f32_e64 v68, v3, v156
	v_fmac_f32_e64 v68, v0, v160
	v_fmac_f32_e64 v68, v1, v164
	v_lshl_add_u64 v[66:67], v[8:9], 0, v[66:67]
	ds_read_b128 v[170:173], v2 offset:3088
	global_store_dword v[66:67], v68, off
	v_mul_f32_e64 v66, v89, v141
	ds_read_b128 v[174:177], v2 offset:3600
	s_waitcnt vmcnt(31)
	s_nop 0
	v_fmac_f32_e64 v66, v75, v180
	v_fmac_f32_e64 v66, v3, v157
	v_mul_f32_e64 v68, v89, v150
	v_fmac_f32_e64 v66, v0, v161
	s_waitcnt vmcnt(30)
	s_nop 0
	v_fmac_f32_e64 v68, v75, v181
	v_fmac_f32_e64 v66, v1, v165
	v_lshl_add_u64 v[64:65], v[8:9], 0, v[64:65]
	s_waitcnt lgkmcnt(2)
	s_nop 0
	v_fmac_f32_e64 v68, v3, v166
	global_store_dword v[64:65], v66, off
	ds_read_b128 v[64:67], v2 offset:32
	s_waitcnt lgkmcnt(2)
	s_nop 0
	v_fmac_f32_e64 v68, v0, v170
	s_waitcnt lgkmcnt(1)
	s_nop 0
	v_fmac_f32_e64 v68, v1, v174
	v_lshl_add_u64 v[62:63], v[8:9], 0, v[62:63]
	global_store_dword v[62:63], v68, off
	v_mul_f32_e64 v62, v89, v151
	s_waitcnt vmcnt(31)
	s_nop 0
	v_fmac_f32_e64 v62, v75, v182
	v_fmac_f32_e64 v62, v3, v167
	v_fmac_f32_e64 v62, v0, v171
	v_fmac_f32_e64 v62, v1, v175
	v_lshl_add_u64 v[60:61], v[8:9], 0, v[60:61]
	global_store_dword v[60:61], v62, off
	v_mul_f32_e64 v60, v89, v152
	s_waitcnt vmcnt(31)
	s_nop 0
	v_fmac_f32_e64 v60, v75, v183
	v_fmac_f32_e64 v60, v3, v168
	v_fmac_f32_e64 v60, v0, v172
	v_fmac_f32_e64 v60, v1, v176
	v_lshl_add_u64 v[58:59], v[8:9], 0, v[58:59]
	v_fmac_f32_e64 v24, v115, v178
	global_store_dword v[58:59], v60, off
	v_mul_f32_e64 v58, v89, v153
	v_fmac_f32_e64 v24, v116, v179
	s_waitcnt vmcnt(31)
	s_nop 0
	v_fmac_f32_e64 v58, v75, v184
	v_fma_f32 v96, v118, v113, 0
	v_fmac_f32_e64 v24, v117, v180
	v_fmac_f32_e64 v58, v3, v169
	v_fma_f32 v97, v126, v113, 0
	v_fma_f32 v98, v134, v113, 0
	v_fmac_f32_e64 v96, v119, v178
	v_fmac_f32_e64 v24, v122, v181
	v_fmac_f32_e64 v58, v0, v173
	v_fmac_f32_e64 v97, v127, v178
	v_fmac_f32_e64 v98, v135, v178
	v_fmac_f32_e64 v96, v120, v179
	v_fmac_f32_e64 v24, v123, v182
	v_fmac_f32_e64 v58, v1, v177
	v_lshl_add_u64 v[56:57], v[8:9], 0, v[56:57]
	v_fmac_f32_e64 v97, v128, v179
	v_fmac_f32_e64 v98, v136, v179
	v_fmac_f32_e64 v96, v121, v180
	v_fmac_f32_e64 v24, v124, v183
	global_store_dword v[56:57], v58, off
	v_fmac_f32_e64 v97, v129, v180
	v_fmac_f32_e64 v98, v137, v180
	v_fmac_f32_e64 v96, v130, v181
	v_fmac_f32_e64 v24, v125, v184
	ds_read_b128 v[56:59], v2 offset:544
	ds_read_b128 v[60:63], v2 offset:48
	ds_read_b128 v[68:71], v2 offset:1056
	ds_read_b128 v[114:117], v2 offset:560
	ds_read_b128 v[118:121], v2 offset:1568
	ds_read_b128 v[122:125], v2 offset:2080
	ds_read_b128 v[126:129], v2 offset:1072
	v_fmac_f32_e64 v97, v142, v181
	v_fmac_f32_e64 v98, v146, v181
	v_fmac_f32_e64 v96, v131, v182
	ds_read_b128 v[138:141], v2 offset:2592
	v_fmac_f32_e64 v97, v143, v182
	v_fmac_f32_e64 v98, v147, v182
	v_fmac_f32_e64 v96, v132, v183
	v_fmac_f32_e64 v97, v144, v183
	v_fmac_f32_e64 v98, v148, v183
	v_fmac_f32_e64 v96, v133, v184
	v_fmac_f32_e64 v97, v145, v184
	v_fmac_f32_e64 v98, v149, v184
	s_waitcnt vmcnt(31) lgkmcnt(7)
	s_nop 0
	v_fmac_f32_e64 v96, v56, v185
	ds_read_b128 v[130:133], v2 offset:1584
	ds_read_b128 v[134:137], v2 offset:2096
	s_waitcnt lgkmcnt(4)
	s_nop 0
	v_mul_f32_e64 v56, v89, v122
	ds_read_b128 v[142:145], v2 offset:3104
	ds_read_b128 v[146:149], v2 offset:3616
	ds_read_b128 v[150:153], v2 offset:2608
	v_fmac_f32_e64 v56, v75, v185
	s_waitcnt lgkmcnt(5)
	s_nop 0
	v_fmac_f32_e64 v56, v3, v138
	s_waitcnt lgkmcnt(2)
	s_nop 0
	v_fmac_f32_e64 v56, v0, v142
	s_waitcnt lgkmcnt(1)
	s_nop 0
	v_fmac_f32_e64 v56, v1, v146
	v_lshl_add_u64 v[54:55], v[8:9], 0, v[54:55]
	global_store_dword v[54:55], v56, off
	v_mul_f32_e64 v54, v89, v123
	s_waitcnt vmcnt(31)
	s_nop 0
	v_fmac_f32_e64 v54, v75, v186
	v_fmac_f32_e64 v54, v3, v139
	v_fmac_f32_e64 v54, v0, v143
	v_fmac_f32_e64 v54, v1, v147
	v_lshl_add_u64 v[52:53], v[8:9], 0, v[52:53]
	global_store_dword v[52:53], v54, off
	v_mul_f32_e64 v52, v89, v124
	s_waitcnt vmcnt(31)
; __device__ __forceinline__ void ret_sample_unit(PR P, LAS float* lds, const int b, const int h, const int wv) {
;     ...
; #pragma unroll
;       for (int x = 0; x < 32; ++x) { const int d = dg * 32 + x; const float s = sv[x];
;           a0 = fmaf(q[d], s, a0); a1 = fmaf(q[128 + d], s, a1); a2 = fmaf(q[256 + d], s, a2); a3 = fmaf(q[384 + d], s, a3);
;           So[(size_t)d * 128] = s * c4 + k[d] * v0 + k[128 + d] * v1 + k[256 + d] * v2 + k[384 + d] * v3; }
	s_nop 0
	v_fmac_f32_e64 v52, v75, v187
	v_fmac_f32_e64 v52, v3, v140
	v_fmac_f32_e64 v52, v0, v144
	v_fmac_f32_e64 v52, v1, v148
	v_lshl_add_u64 v[50:51], v[8:9], 0, v[50:51]
	ds_read_b128 v[154:157], v2 offset:3120
	global_store_dword v[50:51], v52, off
	v_mul_f32_e64 v50, v89, v125
	ds_read_b128 v[158:161], v2 offset:3632
	s_waitcnt vmcnt(31)
	s_nop 0
	v_fmac_f32_e64 v50, v75, v112
	v_fmac_f32_e64 v50, v3, v141
	v_mul_f32_e64 v52, v89, v134
	v_fmac_f32_e64 v50, v0, v145
	s_waitcnt vmcnt(30)
	s_nop 0
	v_fmac_f32_e64 v52, v75, v111
	v_fmac_f32_e64 v50, v1, v149
	v_lshl_add_u64 v[48:49], v[8:9], 0, v[48:49]
	s_waitcnt lgkmcnt(2)
	s_nop 0
	v_fmac_f32_e64 v52, v3, v150
	global_store_dword v[48:49], v50, off
	ds_read_b128 v[48:51], v2 offset:64
	s_waitcnt lgkmcnt(2)
	s_nop 0
	v_fmac_f32_e64 v52, v0, v154
	s_waitcnt lgkmcnt(1)
	s_nop 0
	v_fmac_f32_e64 v52, v1, v158
	v_lshl_add_u64 v[46:47], v[8:9], 0, v[46:47]
	global_store_dword v[46:47], v52, off
	v_mul_f32_e64 v46, v89, v135
	s_waitcnt vmcnt(31)
	s_nop 0
	v_fmac_f32_e64 v46, v75, v110
	v_fmac_f32_e64 v46, v3, v151
	v_fmac_f32_e64 v46, v0, v155
	v_fmac_f32_e64 v46, v1, v159
	v_lshl_add_u64 v[44:45], v[8:9], 0, v[44:45]
	global_store_dword v[44:45], v46, off
	v_mul_f32_e64 v44, v89, v136
	s_waitcnt vmcnt(31)
	s_nop 0
	v_fmac_f32_e64 v44, v75, v109
	v_fmac_f32_e64 v44, v3, v152
	v_fmac_f32_e64 v44, v0, v156
	v_fmac_f32_e64 v24, v64, v185
	v_fmac_f32_e64 v44, v1, v160
	v_lshl_add_u64 v[42:43], v[8:9], 0, v[42:43]
	v_fmac_f32_e64 v24, v65, v186
	global_store_dword v[42:43], v44, off
	v_mul_f32_e64 v42, v89, v137
	v_fmac_f32_e64 v96, v57, v186
	v_fmac_f32_e64 v24, v66, v187
	s_waitcnt vmcnt(31)
	s_nop 0
	v_fmac_f32_e64 v42, v75, v108
	v_fmac_f32_e64 v96, v58, v187
	v_fmac_f32_e64 v24, v67, v112
	v_fmac_f32_e64 v42, v3, v153
	v_fmac_f32_e64 v97, v68, v185
	v_fmac_f32_e64 v98, v118, v185
	v_fmac_f32_e64 v96, v59, v112
	v_fmac_f32_e64 v24, v60, v111
	v_fmac_f32_e64 v42, v0, v157
	v_fmac_f32_e64 v97, v69, v186
	v_fmac_f32_e64 v98, v119, v186
	v_fmac_f32_e64 v96, v114, v111
	v_fmac_f32_e64 v24, v61, v110
	v_fmac_f32_e64 v42, v1, v161
	v_lshl_add_u64 v[40:41], v[8:9], 0, v[40:41]
	v_fmac_f32_e64 v97, v70, v187
	v_fmac_f32_e64 v98, v120, v187
	v_fmac_f32_e64 v96, v115, v110
	v_fmac_f32_e64 v24, v62, v109
	global_store_dword v[40:41], v42, off
	v_fmac_f32_e64 v97, v71, v112
	v_fmac_f32_e64 v98, v121, v112
	v_fmac_f32_e64 v96, v116, v109
	v_fmac_f32_e64 v24, v63, v108
	ds_read_b128 v[40:43], v2 offset:576
	ds_read_b128 v[44:47], v2 offset:80
	ds_read_b128 v[52:55], v2 offset:1088
	ds_read_b128 v[56:59], v2 offset:592
	ds_read_b128 v[60:63], v2 offset:1600
	ds_read_b128 v[64:67], v2 offset:2112
	ds_read_b128 v[68:71], v2 offset:1104
	v_fmac_f32_e64 v97, v126, v111
	v_fmac_f32_e64 v98, v130, v111
	v_fmac_f32_e64 v96, v117, v108
	ds_read_b128 v[116:119], v2 offset:2624
	v_fmac_f32_e64 v97, v127, v110
	v_fmac_f32_e64 v98, v131, v110
	v_fmac_f32_e64 v97, v128, v109
	v_fmac_f32_e64 v98, v132, v109
	v_fmac_f32_e64 v97, v129, v108
	v_fmac_f32_e64 v98, v133, v108
	s_waitcnt vmcnt(31) lgkmcnt(7)
	s_nop 0
	v_fmac_f32_e64 v96, v40, v107
	ds_read_b128 v[108:111], v2 offset:1616
	ds_read_b128 v[112:115], v2 offset:2128
	s_waitcnt lgkmcnt(4)
	s_nop 0
	v_mul_f32_e64 v40, v89, v64
	ds_read_b128 v[120:123], v2 offset:3136
	ds_read_b128 v[124:127], v2 offset:3648
	ds_read_b128 v[128:131], v2 offset:2640
	v_fmac_f32_e64 v40, v75, v107
	s_waitcnt lgkmcnt(5)
	s_nop 0
	v_fmac_f32_e64 v40, v3, v116
	s_waitcnt lgkmcnt(2)
	s_nop 0
	v_fmac_f32_e64 v40, v0, v120
	s_waitcnt lgkmcnt(1)
	s_nop 0
	v_fmac_f32_e64 v40, v1, v124
	v_lshl_add_u64 v[38:39], v[8:9], 0, v[38:39]
	global_store_dword v[38:39], v40, off
	v_mul_f32_e64 v38, v89, v65
	s_waitcnt vmcnt(31)
	s_nop 0
	v_fmac_f32_e64 v38, v75, v106
	v_fmac_f32_e64 v38, v3, v117
	v_fmac_f32_e64 v38, v0, v121
	v_fmac_f32_e64 v38, v1, v125
	v_lshl_add_u64 v[36:37], v[8:9], 0, v[36:37]
	global_store_dword v[36:37], v38, off
	v_mul_f32_e64 v36, v89, v66
	s_waitcnt vmcnt(31)
	s_nop 0
	v_fmac_f32_e64 v36, v75, v105
	v_fmac_f32_e64 v36, v3, v118
	v_fmac_f32_e64 v36, v0, v122
	v_fmac_f32_e64 v36, v1, v126
	v_lshl_add_u64 v[34:35], v[8:9], 0, v[34:35]
	global_store_dword v[34:35], v36, off
	v_mul_f32_e64 v34, v89, v67
	s_waitcnt vmcnt(31)
	s_nop 0
	v_fmac_f32_e64 v34, v75, v104
	v_fmac_f32_e64 v34, v3, v119
	ds_read_b128 v[132:135], v2 offset:3152
	ds_read_b128 v[136:139], v2 offset:3664
	v_fmac_f32_e64 v34, v0, v123
	v_fmac_f32_e64 v34, v1, v127
	v_lshl_add_u64 v[32:33], v[8:9], 0, v[32:33]
	global_store_dword v[32:33], v34, off
	v_mul_f32_e64 v32, v89, v112
	s_waitcnt vmcnt(31)
	s_nop 0
	v_fmac_f32_e64 v32, v75, v103
	s_waitcnt lgkmcnt(2)
	s_nop 0
	v_fmac_f32_e64 v32, v3, v128
	s_waitcnt lgkmcnt(1)
	s_nop 0
	v_fmac_f32_e64 v32, v0, v132
	s_waitcnt lgkmcnt(0)
	s_nop 0
	v_fmac_f32_e64 v32, v1, v136
	v_lshl_add_u64 v[30:31], v[8:9], 0, v[30:31]
	global_store_dword v[30:31], v32, off
	v_mul_f32_e64 v30, v89, v113
	s_waitcnt vmcnt(31)
	s_nop 0
	v_fmac_f32_e64 v30, v75, v102
	v_fmac_f32_e64 v30, v3, v129
	v_fmac_f32_e64 v30, v0, v133
	v_fmac_f32_e64 v24, v48, v107
	v_fmac_f32_e64 v30, v1, v137
	v_lshl_add_u64 v[28:29], v[8:9], 0, v[28:29]
	v_fmac_f32_e64 v24, v49, v106
	global_store_dword v[28:29], v30, off
	v_mul_f32_e64 v28, v89, v114
	v_mul_f32_e64 v30, v89, v115
	v_fmac_f32_e64 v24, v50, v105
	s_waitcnt vmcnt(31)
	s_nop 0
	v_fmac_f32_e64 v28, v75, v101
	s_waitcnt vmcnt(30)
; __device__ __forceinline__ void ret_sample_unit(PR P, LAS float* lds, const int b, const int h, const int wv) {
;     ...
; #pragma unroll
;       for (int x = 0; x < 32; ++x) { const int d = dg * 32 + x; const float s = sv[x];
;           a0 = fmaf(q[d], s, a0); a1 = fmaf(q[128 + d], s, a1); a2 = fmaf(q[256 + d], s, a2); a3 = fmaf(q[384 + d], s, a3);
;           So[(size_t)d * 128] = s * c4 + k[d] * v0 + k[128 + d] * v1 + k[256 + d] * v2 + k[384 + d] * v3; }
;       y2p[(dg * 4 + 0) * 128 + e] = a0; y2p[(dg * 4 + 1) * 128 + e] = a1; y2p[(dg * 4 + 2) * 128 + e] = a2; y2p[(dg * 4 + 3) * 128 + e] = a3; }
;     __syncthreads();
	s_nop 0
	v_fmac_f32_e64 v30, v75, v100
	v_fmac_f32_e64 v97, v52, v107
	v_fmac_f32_e64 v96, v41, v106
	v_fmac_f32_e64 v24, v51, v104
	v_fmac_f32_e64 v28, v3, v130
	v_fmac_f32_e64 v30, v3, v131
	v_fmac_f32_e64 v98, v60, v107
	v_fmac_f32_e64 v97, v53, v106
	v_fmac_f32_e64 v96, v42, v105
	v_fmac_f32_e64 v24, v44, v103
	v_fmac_f32_e64 v28, v0, v134
	v_fmac_f32_e64 v30, v0, v135
	v_fmac_f32_e64 v98, v61, v106
	v_fmac_f32_e64 v97, v54, v105
	v_fmac_f32_e64 v96, v43, v104
	v_fmac_f32_e64 v24, v45, v102
	v_fmac_f32_e64 v28, v1, v138
	v_lshl_add_u64 v[26:27], v[8:9], 0, v[26:27]
	v_fmac_f32_e64 v30, v1, v139
	v_lshl_add_u64 v[22:23], v[8:9], 0, v[22:23]
	v_fmac_f32_e64 v98, v62, v105
	v_fmac_f32_e64 v97, v55, v104
	v_fmac_f32_e64 v96, v56, v103
	v_fmac_f32_e64 v24, v46, v101
	global_store_dword v[26:27], v28, off
	global_store_dword v[22:23], v30, off
	v_fmac_f32_e64 v98, v63, v104
	v_fmac_f32_e64 v97, v68, v103
	v_fmac_f32_e64 v96, v57, v102
	v_fmac_f32_e64 v24, v47, v100
	ds_read_b128 v[26:29], v2 offset:96
	ds_read_b128 v[30:33], v2 offset:608
	ds_read_b128 v[34:37], v2 offset:112
	ds_read_b128 v[38:41], v2 offset:1120
	ds_read_b128 v[42:45], v2 offset:624
	ds_read_b128 v[46:49], v2 offset:1632
	ds_read_b128 v[50:53], v2 offset:2144
	ds_read_b128 v[54:57], v2 offset:1136
	v_fmac_f32_e64 v98, v108, v103
	v_fmac_f32_e64 v97, v69, v102
	ds_read_b128 v[66:69], v2 offset:2656
	v_fmac_f32_e64 v98, v109, v102
	v_fmac_f32_e64 v96, v58, v101
	v_fmac_f32_e64 v97, v70, v101
	v_fmac_f32_e64 v98, v110, v101
	v_fmac_f32_e64 v96, v59, v100
	v_fmac_f32_e64 v97, v71, v100
	v_fmac_f32_e64 v98, v111, v100
	ds_read_b128 v[58:61], v2 offset:1648
	ds_read_b128 v[62:65], v2 offset:2160
	s_waitcnt lgkmcnt(4)
	s_nop 0
	v_mul_f32_e64 v22, v89, v50
	ds_read_b128 v[100:103], v2 offset:3168
	ds_read_b128 v[104:107], v2 offset:3680
	ds_read_b128 v[108:111], v2 offset:2672
	s_waitcnt vmcnt(31)
	s_nop 0
	v_fmac_f32_e64 v22, v75, v99
	s_waitcnt lgkmcnt(5)
	s_nop 0
	v_fmac_f32_e64 v22, v3, v66
	s_waitcnt lgkmcnt(2)
	s_nop 0
	v_fmac_f32_e64 v22, v0, v100
	s_waitcnt lgkmcnt(1)
	s_nop 0
	v_fmac_f32_e64 v22, v1, v104
	v_lshl_add_u64 v[20:21], v[8:9], 0, v[20:21]
	global_store_dword v[20:21], v22, off
	v_mul_f32_e64 v20, v89, v51
	s_waitcnt vmcnt(31)
	s_nop 0
	v_fmac_f32_e64 v20, v75, v95
	v_fmac_f32_e64 v20, v3, v67
	v_fmac_f32_e64 v20, v0, v101
	v_fmac_f32_e64 v20, v1, v105
	v_lshl_add_u64 v[18:19], v[8:9], 0, v[18:19]
	global_store_dword v[18:19], v20, off
	v_mul_f32_e64 v18, v89, v52
	s_waitcnt vmcnt(31)
	s_nop 0
	v_fmac_f32_e64 v18, v75, v94
	v_fmac_f32_e64 v18, v3, v68
	v_fmac_f32_e64 v18, v0, v102
	v_fmac_f32_e64 v18, v1, v106
	v_lshl_add_u64 v[16:17], v[8:9], 0, v[16:17]
	global_store_dword v[16:17], v18, off
	v_mul_f32_e64 v16, v89, v53
	s_waitcnt vmcnt(31)
	s_nop 0
	v_fmac_f32_e64 v16, v75, v93
	v_fmac_f32_e64 v16, v3, v69
	ds_read_b128 v[112:115], v2 offset:3184
	ds_read_b128 v[116:119], v2 offset:3696
	v_fmac_f32_e64 v16, v0, v103
	v_fmac_f32_e64 v16, v1, v107
	v_lshl_add_u64 v[14:15], v[8:9], 0, v[14:15]
	global_store_dword v[14:15], v16, off
	v_mul_f32_e64 v14, v89, v62
	s_waitcnt vmcnt(31)
	s_nop 0
	v_fmac_f32_e64 v14, v75, v92
	s_waitcnt lgkmcnt(2)
	s_nop 0
	v_fmac_f32_e64 v14, v3, v108
	s_waitcnt lgkmcnt(1)
	s_nop 0
	v_fmac_f32_e64 v14, v0, v112
	s_waitcnt lgkmcnt(0)
	s_nop 0
	v_fmac_f32_e64 v14, v1, v116
	v_lshl_add_u64 v[12:13], v[8:9], 0, v[12:13]
	global_store_dword v[12:13], v14, off
	v_mul_f32_e64 v12, v89, v63
	s_waitcnt vmcnt(31)
	s_nop 0
	v_fmac_f32_e64 v12, v75, v91
	v_fmac_f32_e64 v12, v3, v109
	v_fmac_f32_e64 v12, v0, v113
	v_fmac_f32_e64 v12, v1, v117
	v_lshl_add_u64 v[10:11], v[8:9], 0, v[10:11]
	global_store_dword v[10:11], v12, off
	v_mul_f32_e64 v10, v89, v64
	s_waitcnt vmcnt(31)
	s_nop 0
	v_fmac_f32_e64 v10, v75, v90
	v_fmac_f32_e64 v10, v3, v110
	v_fmac_f32_e64 v24, v26, v99
	v_fmac_f32_e64 v96, v30, v99
	v_fmac_f32_e64 v10, v0, v114
	v_fmac_f32_e64 v97, v38, v99
	v_fmac_f32_e64 v98, v46, v99
	v_fmac_f32_e64 v24, v27, v95
	v_fmac_f32_e64 v96, v31, v95
	v_fmac_f32_e64 v10, v1, v118
	v_lshl_add_u64 v[6:7], v[8:9], 0, v[6:7]
	v_fmac_f32_e64 v97, v39, v95
	v_fmac_f32_e64 v98, v47, v95
	v_fmac_f32_e64 v24, v28, v94
	v_fmac_f32_e64 v96, v32, v94
	global_store_dword v[6:7], v10, off
	v_mul_f32_e64 v6, v89, v65
	v_fmac_f32_e64 v97, v40, v94
	v_fmac_f32_e64 v98, v48, v94
	v_fmac_f32_e64 v24, v29, v93
	v_fmac_f32_e64 v96, v33, v93
	s_waitcnt vmcnt(31)
	s_nop 0
	v_fmac_f32_e64 v6, v75, v88
	v_fmac_f32_e64 v97, v41, v93
	v_fmac_f32_e64 v98, v49, v93
	v_fmac_f32_e64 v24, v34, v92
	v_fmac_f32_e64 v96, v42, v92
	v_fmac_f32_e64 v6, v3, v111
	v_fmac_f32_e64 v97, v54, v92
	v_fmac_f32_e64 v98, v58, v92
	v_fmac_f32_e64 v24, v35, v91
	v_fmac_f32_e64 v96, v43, v91
	v_fmac_f32_e64 v6, v0, v115
	v_fmac_f32_e64 v97, v55, v91
	v_fmac_f32_e64 v98, v59, v91
	v_fmac_f32_e64 v24, v36, v90
	v_fmac_f32_e64 v96, v44, v90
	v_fmac_f32_e64 v6, v1, v119
	v_lshl_add_u64 v[0:1], v[8:9], 0, v[4:5]
	v_fmac_f32_e64 v97, v56, v90
	v_fmac_f32_e64 v98, v60, v90
	v_fmac_f32_e64 v24, v37, v88
	v_fmac_f32_e64 v96, v45, v88
	global_store_dword v[0:1], v6, off
	v_lshl_add_u32 v0, v85, 11, v87
	v_and_b32_e32 v1, 0x3fffff80, v83
	v_fmac_f32_e64 v97, v57, v88
	v_fmac_f32_e64 v98, v61, v88
	ds_write2st64_b32 v0, v24, v96 offset0:25 offset1:27
	ds_write2st64_b32 v0, v97, v98 offset0:29 offset1:31
	v_lshl_add_u32 v0, v83, 2, 0
	v_lshl_add_u32 v1, v1, 2, v87
	s_waitcnt lgkmcnt(0)
	s_barrier
; __device__ __forceinline__ float bf2f(unsigned b) { return __uint_as_float(b << 16); }
; template <bool SAMPLE>
; __device__ __forceinline__ void rwkv_unit(PR P, LAS float* lds, const int b, const int h, const int half, const int wv) {
;     ...
;     const int ltok = (tid - 256) >> 4, lcg = tid & 15; const bool lwave = tid >= 256; const int hch = h * 64 + lcg * 4;
;     const float4 mur = *(const float4*)(P.mu + hch), muk = *(const float4*)(P.mu + 512 + hch), muv = *(const float4*)(P.mu + 1024 + hch);
;     const float4 kk4 = *(const float4*)(P.k_k + hch), ka4 = *(const float4*)(P.k_a + hch);
;     typedef float f32x2 __attribute__((ext_vector_type(2)));
;     const int row0 = half * 32 + (wid & 3) * 8 + (lane >> 4) * 2, cgl = lane & 15, j0 = cgl * 4;
;     f32x2 S[4];
; #pragma unroll
;     for (int c = 0; c < 4; ++c) S[c] = (f32x2){0.f, 0.f};
;     float* sout = P.out + (SAMPLE ? O_WKS : O_WKP) + ((size_t)(b * 8 + h) * 64 + row0) * 64 + j0;
;     if (SAMPLE && wid < 4) { const float* sp = P.state_wkv + ((size_t)(b * 8 + h) * 64 + row0) * 64 + j0; const float4 s0 = *(const float4*)sp, s1 = *(const float4*)(sp + 64);
;         S[0] = (f32x2){s0.x, s1.x}; S[1] = (f32x2){s0.y, s1.y}; S[2] = (f32x2){s0.z, s1.z}; S[3] = (f32x2){s0.w, s1.w}; }
; __device__ __forceinline__ void ret_sample_unit(PR P, LAS float* lds, const int b, const int h, const int wv) {
;     ...
;     { const int i = tid >> 7, e = tid & 127;
;       float y = (y2p[(0 + i) * 128 + e] + y2p[(4 + i) * 128 + e] + y2p[(8 + i) * 128 + e] + y2p[(12 + i) * 128 + e]) * exp2f(lg2 * (float)(i + 1));
; #pragma unroll
;       for (int j = 0; j < 4; ++j) y = fmaf(Pm[i * 4 + j], v[j * 128 + e], y);
;       float s = wave_sum(y); if (lane == 0) red[wid] = s; __syncthreads();
;       const float mean = (red[i * 2] + red[i * 2 + 1]) * (1.0f / 128.0f); const float dlt = y - mean;
;       float s2 = wave_sum(dlt * dlt); if (lane == 0) red[8 + wid] = s2; __syncthreads();
;       const float var = (red[8 + i * 2] + red[8 + i * 2 + 1]) * (1.0f / 128.0f);
;       const float g = bf2f(PS[(size_t)(row0 + i) * NCOLS + 1792 + 1536 + h * 128 + e]);
;       const float o = dlt * rsqrtf(var + 1e-5f) * P.gn_w[h * 128 + e] * (g * __builtin_amdgcn_rcpf(1.0f + __expf(-g)));
;       Y[(size_t)(row0 + i) * 1024 + 512 + h * 128 + e] = f2bf(o); }
	ds_read2st64_b32 v[6:7], v1 offset0:33 offset1:41
	ds_read_b32 v8, v0 offset:6400
	ds_read_b32 v9, v1 offset:12544
	v_add_u32_e64 v0, 1, v85
	v_cvt_f32_i32_e64 v10, v0
	v_mad_u64_u32 v[0:1], s[8:9], v85, s61, v[2:3]
	s_waitcnt lgkmcnt(1)
	s_nop 0
	v_add_f32_e64 v1, v8, v6
	v_mul_f32_e64 v6, v73, v10
	v_cmp_gt_f32_e64 vcc, s45, v6
	ds_read_b128 v[2:5], v0 offset:6144
	v_add_f32_e64 v1, v1, v7
	v_cndmask_b32_e64 v6, 0, v72, vcc
	v_fmac_f32_e64 v6, v73, v10
	v_exp_f32_e64 v10, v6
	ds_read2st64_b32 v[6:7], v87 offset0:16 offset1:18
	s_waitcnt lgkmcnt(2)
	s_nop 0
	v_add_f32_e64 v1, v1, v9
	v_cndmask_b32_e64 v11, 0, v80, vcc
	ds_read2st64_b32 v[8:9], v87 offset0:20 offset1:22
	v_ldexp_f32 v10, v10, v11
	v_mul_f32_e64 v1, v10, v1
	s_waitcnt lgkmcnt(1)
	s_nop 0
	v_fmac_f32_e64 v1, v2, v6
	v_fmac_f32_e64 v1, v3, v7
	s_waitcnt lgkmcnt(0)
	s_nop 0
	v_fmac_f32_e64 v1, v4, v8
	v_fmac_f32_e64 v1, v5, v9
	v_ashrrev_i32_e64 v86, 6, v83
	v_cmp_eq_u32_e64 vcc, 0, v82
	v_add_f32_dpp v2, v1, v1 quad_perm:[1,0,3,2] row_mask:0xf bank_mask:0xf bound_ctrl:1
	v_lshl_add_u32 v3, v86, 2, 0
	s_nop 0
	s_nop 0
	v_add_f32_dpp v2, v2, v2 quad_perm:[2,3,0,1] row_mask:0xf bank_mask:0xf bound_ctrl:1
	s_nop 1
	s_nop 0
	v_add_f32_dpp v2, v2, v2 row_half_mirror row_mask:0xf bank_mask:0xf bound_ctrl:1
	s_nop 1
	s_nop 0
	v_add_f32_dpp v2, v2, v2 row_mirror row_mask:0xf bank_mask:0xf bound_ctrl:1
	s_nop 0
	s_nop 0
	v_readlane_b32 s10, v2, 0
	v_readlane_b32 s28, v2, 16
	v_readlane_b32 s11, v2, 32
	v_readlane_b32 s13, v2, 48
	s_and_saveexec_b64 s[8:9], vcc
	s_nop 0
	v_mov_b32_e64 v2, s28
	v_add_f32_e64 v2, s10, v2
	v_add_f32_e64 v2, s11, v2
	v_add_f32_e64 v2, s13, v2
	ds_write_b32 v3, v2 offset:14592
	s_or_b64 exec, exec, s[8:9]
	s_nop 0
	v_lshlrev_b32_e64 v2, 3, v85
	v_sub_u32_e64 v4, v0, v2
	s_waitcnt lgkmcnt(0)
	s_barrier
	ds_read_b64 v[4:5], v4 offset:14592
	v_mov_b32_e64 v6, v25
	s_waitcnt lgkmcnt(0)
	s_nop 0
	v_add_f32_e64 v4, v4, v5
	v_fmac_f32_e32 v1, 0xbc000000, v4
	v_mul_f32_e64 v4, v1, v1
	s_nop 1
	s_nop 0
	v_mov_b32_dpp v6, v4 quad_perm:[1,0,3,2] row_mask:0xf bank_mask:0xf
	v_fmac_f32_e64 v6, v1, v1
	s_nop 1
	s_nop 0
	v_add_f32_dpp v4, v6, v6 quad_perm:[2,3,0,1] row_mask:0xf bank_mask:0xf bound_ctrl:1
	s_nop 1
	s_nop 0
	v_add_f32_dpp v4, v4, v4 row_half_mirror row_mask:0xf bank_mask:0xf bound_ctrl:1
	s_nop 1
	s_nop 0
	v_add_f32_dpp v4, v4, v4 row_mirror row_mask:0xf bank_mask:0xf bound_ctrl:1
	s_nop 0
	s_nop 0
	v_readlane_b32 s10, v4, 0
	v_readlane_b32 s28, v4, 16
	v_readlane_b32 s11, v4, 32
	v_readlane_b32 s13, v4, 48
	s_and_saveexec_b64 s[8:9], vcc
	s_nop 0
	v_mov_b32_e64 v4, s28
	v_add_f32_e64 v4, s10, v4
	v_add_f32_e64 v4, s11, v4
	v_add_f32_e64 v4, s13, v4
	ds_write_b32 v3, v4 offset:14624
	s_or_b64 exec, exec, s[8:9]
	s_nop 0
	v_add_u32_e64 v4, s12, v85
	v_mov_b64_e64 v[6:7], s[18:19]
	v_mad_i64_i32 v[6:7], s[8:9], v4, s62, v[6:7]
	s_lshl_b32 s28, s47, 1
	s_nop 0
	v_lshl_add_u64 v[6:7], v[6:7], 0, s[28:29]
	v_lshlrev_b32_e64 v24, 1, v84
	v_lshl_add_u64 v[6:7], v[6:7], 0, v[24:25]
	v_add_co_u32_e64 v6, vcc, s63, v6
	s_waitcnt lgkmcnt(0)
	s_nop 0
	v_addc_co_u32_e64 v7, vcc, 0, v7, vcc
	s_barrier
	s_nop 0
	global_load_ushort v8, v[6:7], off offset:2560
	s_load_dwordx2 s[8:9], s[38:39], 0xa8
	v_or_b32_e64 v3, s47, v84
	v_lshlrev_b32_e64 v3, 2, v3
	v_sub_u32_e64 v2, 0, v2
	v_add_u32_e64 v0, v0, v2
	s_waitcnt lgkmcnt(0)
	s_nop 0
	global_load_dword v3, v3, s[8:9]
	ds_read_b64 v[6:7], v0 offset:14624
	v_ashrrev_i32_e64 v5, 31, v4
	v_lshlrev_b64 v[4:5], 11, v[4:5]
	v_lshl_add_u64 v[4:5], s[30:31], 0, v[4:5]
	v_lshl_add_u64 v[4:5], v[4:5], 0, v[24:25]
	s_waitcnt lgkmcnt(0)
	s_nop 0
	v_add_f32_e64 v0, v6, v7
	v_fmamk_f32 v2, v0, 0x3c000000, v78
	v_mul_f32_e32 v6, 0x4b800000, v2
	v_cmp_gt_f32_e64 vcc, s46, v2
	s_mov_b64 s[8:9], 0
	s_waitcnt vmcnt(1)
	v_lshlrev_b32_e64 v0, 16, v8
	v_mul_f32_e32 v7, 0xbfb8aa3b, v0
	v_exp_f32_e64 v7, v7
	v_cndmask_b32_e64 v2, v2, v6, vcc
	v_rsq_f32_e64 v6, v2
	v_add_f32_e64 v2, 1.0, v7
	v_rcp_f32_e64 v2, v2
	v_mul_f32_e32 v7, 0x45800000, v6
	v_cndmask_b32_e64 v6, v6, v7, vcc
	v_mul_f32_e64 v1, v1, v6
	s_waitcnt vmcnt(0)
	s_nop 0
	v_pk_mul_f32 v[0:1], v[2:3], v[0:1]
	s_nop 0
	s_nop 0
	v_pk_mul_f32 v[0:1], v[0:1], v[0:1] op_sel:[0,1] op_sel_hi:[1,0]
	s_nop 0
	s_nop 0
	v_bfe_u32 v1, v0, 16, 1
	v_add3_u32 v0, v0, v1, s64
	global_store_short_d16_hi v[4:5], v0, off
	s_barrier
	.p2alignl 3, 3212836864
.LBB0_672:
	s_and_b64 vcc, exec, s[8:9]
	s_cbranch_vccz .LBB0_658
	v_mbcnt_lo_u32_b32 v2, -1, 0
	v_mbcnt_hi_u32_b32 v2, -1, v2
	s_load_dwordx2 s[12:13], s[38:39], 0x50
	s_load_dwordx4 s[8:11], s[38:39], 0x80
	v_lshlrev_b32_e64 v0, 2, v2
	s_and_b32 s28, s55, 0x1c0
	v_and_b32_e64 v82, 60, v0
	s_waitcnt vmcnt(0)
	s_nop 0
	v_or_b32_e64 v32, s28, v82
	v_lshlrev_b32_e64 v24, 2, v32
	s_waitcnt lgkmcnt(0)
	s_nop 0
	v_lshl_add_u64 v[0:1], s[12:13], 0, v[24:25]
	v_add_co_u32_e64 v0, vcc, s63, v0
	v_add_u32_e64 v33, s33, v2
	s_nop 0
	s_nop 0
	v_addc_co_u32_e64 v1, vcc, 0, v1, vcc
	global_load_dwordx4 v[20:23], v24, s[12:13]
	global_load_dwordx4 v[16:19], v[0:1], off
	global_load_dwordx4 v[8:11], v24, s[8:9]
	global_load_dwordx4 v[12:15], v24, s[12:13] offset:2048
	global_load_dwordx4 v[4:7], v24, s[10:11]
	v_ashrrev_i32_e64 v0, 6, v33
	v_lshlrev_b32_e64 v1, 3, v0
	v_and_b32_e64 v69, 24, v1
	v_lshrrev_b32_e64 v1, 3, v2
	s_add_i32 s8, s5, s28
	s_and_b32 s42, s55, 32
	v_and_b32_e64 v71, 6, v1
	v_and_b32_e64 v68, 15, v2
	s_add_i32 s8, s8, s42
	s_nop 0
	v_lshlrev_b32_e64 v70, 2, v68
	v_or_b32_e64 v1, v69, v71
	v_add_lshl_u32 v24, v1, s8, 6
	v_cmp_gt_i32_e64 vcc, 4, v0
	v_mov_b32_e64 v28, 0
	v_lshlrev_b32_e64 v26, 2, v70
	v_mov_b32_e64 v29, 0
	v_mov_b32_e64 v0, 0
	v_mov_b32_e64 v1, 0
	v_mov_b32_e64 v30, 0
	v_mov_b32_e64 v31, 0
	v_mov_b32_e64 v2, 0
	v_mov_b32_e64 v3, 0
	s_and_saveexec_b64 s[8:9], vcc
	s_cbranch_execz .LBB0_675
	s_load_dwordx2 s[10:11], s[38:39], 0x18
	v_mov_b32_e64 v27, v25
	s_waitcnt lgkmcnt(0)
	s_nop 0
	v_lshl_add_u64 v[0:1], v[24:25], 2, s[10:11]
	v_lshl_add_u64 v[0:1], v[0:1], 0, v[26:27]
	global_load_dwordx4 v[34:37], v[0:1], off
	s_nop 0
	s_nop 0
	global_load_dwordx4 v[0:3], v[0:1], off offset:256
	s_waitcnt vmcnt(1)
	s_nop 0
	v_mov_b32_e64 v28, v34
	s_waitcnt vmcnt(0)
	s_nop 0
	v_mov_b32_e64 v29, v0
	v_mov_b32_e64 v0, v35
	v_mov_b32_e64 v30, v36
	v_mov_b32_e64 v31, v2
	v_mov_b32_e64 v2, v37
	.p2alignl 3, 3212836864
.LBB0_675:
	s_or_b64 exec, exec, s[8:9]
	s_nop 0
	v_add_u32_e32 v34, 0xffffff00, v33
	v_ashrrev_i32_e64 v27, 4, v34
	v_cmp_lt_i32_e64 s[8:9], s60, v33
	v_cmp_gt_i32_e64 s[10:11], 4, v27
	s_and_b64 s[12:13], s[8:9], s[10:11]
	s_nop 0
	v_add_u32_e64 v66, s56, v27
	v_lshlrev_b32_e64 v64, 1, v32
	s_and_saveexec_b64 s[40:41], s[12:13]
	s_cbranch_execz .LBB0_677
	v_subrev_u32_e64 v33, 17, v66
	v_mov_b32_e64 v35, s4
	v_cmp_gt_u32_e64 s[10:11], 16, v34
	v_add_u32_e64 v32, -16, v66
	v_mov_b32_e64 v65, v25
	v_cndmask_b32_e64 v38, v33, v35, s[10:11]
	v_mov_b64_e64 v[34:35], s[18:19]
	v_ashrrev_i32_e64 v33, 31, v32
	v_mad_i64_i32 v[36:37], s[10:11], v32, s62, v[34:35]
	v_lshl_add_u64 v[36:37], v[36:37], 0, v[64:65]
	v_mad_i64_i32 v[34:35], s[10:11], v38, s62, v[34:35]
	v_lshlrev_b64 v[32:33], 10, v[32:33]
	v_lshl_add_u64 v[34:35], v[34:35], 0, v[64:65]
	global_load_dwordx2 v[62:63], v[36:37], off
	global_load_dwordx2 v[42:43], v[36:37], off offset:1024
	global_load_dwordx2 v[56:57], v[36:37], off offset:2048
	global_load_dwordx2 v[60:61], v[34:35], off
	v_lshl_add_u64 v[36:37], s[22:23], 0, v[32:33]
	v_lshl_add_u64 v[32:33], s[20:21], 0, v[32:33]
	v_lshl_add_u64 v[36:37], v[36:37], 0, v[64:65]
	v_lshl_add_u64 v[32:33], v[32:33], 0, v[64:65]
	global_load_dwordx2 v[44:45], v[34:35], off offset:1024
	global_load_dwordx2 v[58:59], v[34:35], off offset:2048
	global_load_dwordx2 v[54:55], v[36:37], off
	global_load_dwordx2 v[38:39], v[32:33], off
	.p2alignl 3, 3212836864
.LBB0_677:
	s_or_b64 exec, exec, s[40:41]
	s_nop 0
	v_cmp_gt_i32_e64 s[10:11], -12, v27
	s_and_b64 s[10:11], s[8:9], s[10:11]
	s_and_saveexec_b64 s[40:41], s[10:11]
	s_cbranch_execz .LBB0_679
	s_nop 0
	v_add_u32_e64 v32, -1, v66
	v_mov_b32_e64 v33, s4
	v_cmp_eq_u32_e64 s[8:9], -16, v27
	v_mov_b32_e64 v65, v25
	v_ashrrev_i32_e64 v67, 31, v66
	v_cndmask_b32_e64 v40, v32, v33, s[8:9]
	v_mov_b64_e64 v[32:33], s[18:19]
	v_mad_i64_i32 v[34:35], s[8:9], v66, s62, v[32:33]
	v_lshl_add_u64 v[36:37], v[34:35], 0, v[64:65]
	v_mad_i64_i32 v[32:33], s[8:9], v40, s62, v[32:33]
	v_lshl_add_u64 v[32:33], v[32:33], 0, v[64:65]
	global_load_dwordx2 v[52:53], v[36:37], off
	global_load_dwordx2 v[34:35], v[36:37], off offset:1024
	global_load_dwordx2 v[46:47], v[36:37], off offset:2048
	global_load_dwordx2 v[50:51], v[32:33], off
	v_lshlrev_b64 v[36:37], 10, v[66:67]
	v_lshl_add_u64 v[40:41], s[22:23], 0, v[36:37]
	v_lshl_add_u64 v[40:41], v[40:41], 0, v[64:65]
	v_lshl_add_u64 v[36:37], s[20:21], 0, v[36:37]
	v_lshl_add_u64 v[64:65], v[36:37], 0, v[64:65]
	global_load_dwordx2 v[36:37], v[32:33], off offset:1024
	global_load_dwordx2 v[48:49], v[32:33], off offset:2048
	s_nop 0
	s_nop 0
	global_load_dwordx2 v[40:41], v[40:41], off
	s_nop 0
	s_nop 0
	global_load_dwordx2 v[32:33], v[64:65], off
	.p2alignl 3, 3212836864
.LBB0_679:
	s_or_b64 exec, exec, s[40:41]
	s_nop 0
	v_mul_lo_u32 v27, v27, s65
	v_lshlrev_b32_e64 v64, 2, v82
	v_add3_u32 v27, 0, v27, v64
	s_and_saveexec_b64 s[8:9], s[12:13]
	s_cbranch_execz .LBB0_681
	s_waitcnt vmcnt(7)
	s_nop 0
	v_lshlrev_b32_e64 v64, 16, v62
	v_and_b32_e32 v65, 0xffff0000, v62
	s_waitcnt vmcnt(4)
	s_nop 0
	v_lshlrev_b32_e64 v66, 16, v60
	v_and_b32_e32 v67, 0xffff0000, v60
	v_lshlrev_b32_e64 v62, 16, v63
	v_and_b32_e32 v63, 0xffff0000, v63
	v_lshlrev_b32_e64 v60, 16, v61
	v_and_b32_e32 v61, 0xffff0000, v61
	v_pk_add_f32 v[66:67], v[66:67], v[64:65] neg_lo:[0,1] neg_hi:[0,1]
	v_pk_add_f32 v[60:61], v[60:61], v[62:63] neg_lo:[0,1] neg_hi:[0,1]
	v_pk_fma_f32 v[64:65], v[20:21], v[66:67], v[64:65]
	v_pk_fma_f32 v[66:67], v[22:23], v[60:61], v[62:63]
	v_lshlrev_b32_e64 v60, 16, v56
	v_and_b32_e32 v61, 0xffff0000, v56
	s_waitcnt vmcnt(2)
	s_nop 0
	v_lshlrev_b32_e64 v62, 16, v58
	v_and_b32_e32 v63, 0xffff0000, v58
	v_lshlrev_b32_e64 v56, 16, v57
	v_and_b32_e32 v57, 0xffff0000, v57
	v_lshlrev_b32_e64 v58, 16, v59
	v_and_b32_e32 v59, 0xffff0000, v59
	v_pk_add_f32 v[62:63], v[62:63], v[60:61] neg_lo:[0,1] neg_hi:[0,1]
	v_pk_add_f32 v[58:59], v[58:59], v[56:57] neg_lo:[0,1] neg_hi:[0,1]
	v_pk_fma_f32 v[60:61], v[16:17], v[62:63], v[60:61]
	v_pk_fma_f32 v[62:63], v[18:19], v[58:59], v[56:57]
	s_waitcnt vmcnt(1)
	s_nop 0
	v_lshlrev_b32_e64 v56, 16, v54
	v_and_b32_e32 v57, 0xffff0000, v54
	v_lshlrev_b32_e64 v58, 16, v55
	v_and_b32_e32 v59, 0xffff0000, v55
	v_lshlrev_b32_e64 v54, 16, v42
	v_and_b32_e32 v55, 0xffff0000, v42
	v_lshlrev_b32_e64 v82, 16, v44
	v_and_b32_e32 v83, 0xffff0000, v44
	v_pk_add_f32 v[82:83], v[82:83], v[54:55] neg_lo:[0,1] neg_hi:[0,1]
	v_lshlrev_b32_e64 v42, 16, v43
	v_and_b32_e32 v43, 0xffff0000, v43
	v_lshlrev_b32_e64 v44, 16, v45
	v_and_b32_e32 v45, 0xffff0000, v45
	v_pk_fma_f32 v[54:55], v[12:13], v[82:83], v[54:55]
	v_pk_add_f32 v[44:45], v[44:45], v[42:43] neg_lo:[0,1] neg_hi:[0,1]
	v_pk_mul_f32 v[84:85], v[8:9], v[54:55]
	v_pk_fma_f32 v[42:43], v[14:15], v[44:45], v[42:43]
	v_pk_mul_f32 v[86:87], v[84:85], v[84:85]
	v_pk_mul_f32 v[88:89], v[10:11], v[42:43]
	v_add_f32_e64 v86, v86, v87
	v_pk_mul_f32 v[44:45], v[88:89], v[88:89]
	s_waitcnt vmcnt(0)
	s_nop 0
	v_lshlrev_b32_e64 v82, 16, v38
	v_add_f32_e64 v44, v44, v86
	v_add_f32_e64 v44, v45, v44
	v_and_b32_e32 v83, 0xffff0000, v38
	v_lshlrev_b32_e64 v38, 16, v39
	v_add_f32_dpp v44, v44, v44 quad_perm:[1,0,3,2] row_mask:0xf bank_mask:0xf bound_ctrl:1
	v_and_b32_e32 v39, 0xffff0000, v39
	v_pk_add_f32 v[86:87], v[82:83], -1.0 op_sel_hi:[1,0]
	v_add_f32_dpp v44, v44, v44 quad_perm:[2,3,0,1] row_mask:0xf bank_mask:0xf bound_ctrl:1
	v_pk_fma_f32 v[86:87], v[4:5], v[86:87], 1.0 op_sel_hi:[1,1,0]
	s_nop 0
	s_nop 0
	v_add_f32_dpp v44, v44, v44 row_half_mirror row_mask:0xf bank_mask:0xf bound_ctrl:1
	s_nop 1
	s_nop 0
	v_add_f32_dpp v44, v44, v44 row_mirror row_mask:0xf bank_mask:0xf bound_ctrl:1
	v_sqrt_f32_e64 v90, v44
	v_pk_add_f32 v[44:45], v[38:39], -1.0 op_sel_hi:[1,0]
	s_nop 0
	s_nop 0
	v_pk_fma_f32 v[44:45], v[6:7], v[44:45], 1.0 op_sel_hi:[1,1,0]
	s_nop 0
	s_nop 0
	v_pk_mul_f32 v[44:45], v[44:45], v[42:43]
	v_pk_mul_f32 v[42:43], v[86:87], v[54:55]
	v_xor_b32_e32 v54, 0x80000000, v90
	v_min_f32_e32 v54, 0xab8cbccc, v54
	v_rcp_f32_e64 v54, v54
	ds_write_b128 v27, v[64:67]
	ds_write_b128 v27, v[56:59] offset:256
	ds_write_b128 v27, v[42:45] offset:512
	v_pk_mul_f32 v[44:45], v[88:89], v[54:55] op_sel_hi:[1,0]
	v_pk_mul_f32 v[42:43], v[84:85], v[54:55] op_sel_hi:[1,0]
	ds_write_b128 v27, v[42:45] offset:768
	v_pk_mul_f32 v[44:45], v[44:45], v[38:39] neg_lo:[1,0] neg_hi:[1,0]
	v_pk_mul_f32 v[42:43], v[42:43], v[82:83] neg_lo:[1,0] neg_hi:[1,0]
	ds_write_b128 v27, v[42:45] offset:1024
	ds_write_b128 v27, v[60:63] offset:1280
	.p2alignl 3, 3212836864
; #define LAS __attribute__((address_space(3)))
; #define ROW16_SUM4(x, y, z, w) do { DPP4(x, y, z, w, "quad_perm:[1,0,3,2]", "s_nop 1"); DPP4(x, y, z, w, "quad_perm:[2,3,0,1]", ""); DPP4(x, y, z, w, "row_half_mirror", ""); DPP4(x, y, z, w, "row_mirror", ""); } while (0)
; template <bool SAMPLE>
; __device__ __forceinline__ void rwkv_unit(PR P, LAS float* lds, const int b, const int h, const int half, const int wv) {
;     ...
;         if (wid < 4) {
;             constexpr int GS = SAMPLE ? 4 : 16;
;             for (int g = 0; g < TC / GS; ++g) {
;                 float yk0 = 0.f, yk1 = 0.f;
;                 const LAS float* q0 = cur + (g * GS) * 384;
;                 f32x4 r4 = *(const LAS f32x4*)(q0 + j0), o4 = *(const LAS f32x4*)(q0 + 64 + j0), k4 = *(const LAS f32x4*)(q0 + 128 + j0), a4 = *(const LAS f32x4*)(q0 + 192 + j0), b4 = *(const LAS f32x4*)(q0 + 256 + j0);
;                 f32x2 v2 = *(const LAS f32x2*)(q0 + 320 + row0);
;                 float py0 = 0.f, py1 = 0.f;
; #pragma unroll
;                 for (int tt = 0; tt < GS; ++tt) {
;                     const LAS float* qn = q0 + (tt + 1 < GS ? tt + 1 : tt) * 384;
;                     const f32x4 nr4 = *(const LAS f32x4*)(qn + j0), no4 = *(const LAS f32x4*)(qn + 64 + j0), nk4 = *(const LAS f32x4*)(qn + 128 + j0), na4 = *(const LAS f32x4*)(qn + 192 + j0), nb4 = *(const LAS f32x4*)(qn + 256 + j0);
;                     const f32x2 nv2 = *(const LAS f32x2*)(qn + 320 + row0);
;                     f32x2 sa = (S[0] * a4[0] + S[1] * a4[1]) + (S[2] * a4[2] + S[3] * a4[3]);
;                     float sx = sa.x, sy = sa.y; ROW16_SUM4(sx, sy, py0, py1); sa = (f32x2){sx, sy};
.LBB0_681:
	s_or_b64 exec, exec, s[8:9]
	s_and_saveexec_b64 s[8:9], s[10:11]
	s_cbranch_execz .LBB0_683
	s_waitcnt vmcnt(0)
	v_lshlrev_b32_e64 v38, 16, v52
	v_and_b32_e32 v39, 0xffff0000, v52
	v_lshlrev_b32_e64 v42, 16, v50
	v_and_b32_e32 v43, 0xffff0000, v50
	v_pk_add_f32 v[42:43], v[42:43], v[38:39] neg_lo:[0,1] neg_hi:[0,1]
	v_lshlrev_b32_e64 v44, 16, v36
	v_pk_fma_f32 v[20:21], v[20:21], v[42:43], v[38:39]
	v_lshlrev_b32_e64 v38, 16, v53
	v_and_b32_e32 v39, 0xffff0000, v53
	v_lshlrev_b32_e64 v42, 16, v51
	v_and_b32_e32 v43, 0xffff0000, v51
	v_pk_add_f32 v[42:43], v[42:43], v[38:39] neg_lo:[0,1] neg_hi:[0,1]
	v_and_b32_e32 v45, 0xffff0000, v36
	v_pk_fma_f32 v[22:23], v[22:23], v[42:43], v[38:39]
	v_lshlrev_b32_e64 v38, 16, v46
	v_and_b32_e32 v39, 0xffff0000, v46
	v_lshlrev_b32_e64 v42, 16, v48
	v_and_b32_e32 v43, 0xffff0000, v48
	v_pk_add_f32 v[42:43], v[42:43], v[38:39] neg_lo:[0,1] neg_hi:[0,1]
	v_lshlrev_b32_e64 v36, 16, v37
	v_pk_fma_f32 v[16:17], v[16:17], v[42:43], v[38:39]
	v_lshlrev_b32_e64 v38, 16, v47
	v_and_b32_e32 v39, 0xffff0000, v47
	v_lshlrev_b32_e64 v42, 16, v49
	v_and_b32_e32 v43, 0xffff0000, v49
	v_pk_add_f32 v[42:43], v[42:43], v[38:39] neg_lo:[0,1] neg_hi:[0,1]
	v_and_b32_e32 v37, 0xffff0000, v37
	v_pk_fma_f32 v[18:19], v[18:19], v[42:43], v[38:39]
	v_lshlrev_b32_e64 v42, 16, v34
	v_and_b32_e32 v43, 0xffff0000, v34
	v_pk_add_f32 v[44:45], v[44:45], v[42:43] neg_lo:[0,1] neg_hi:[0,1]
	v_lshlrev_b32_e64 v34, 16, v35
	v_and_b32_e32 v35, 0xffff0000, v35
	v_pk_fma_f32 v[12:13], v[12:13], v[44:45], v[42:43]
	v_pk_add_f32 v[36:37], v[36:37], v[34:35] neg_lo:[0,1] neg_hi:[0,1]
	v_pk_mul_f32 v[8:9], v[8:9], v[12:13]
	v_pk_fma_f32 v[14:15], v[14:15], v[36:37], v[34:35]
	v_pk_mul_f32 v[44:45], v[8:9], v[8:9]
	v_pk_mul_f32 v[10:11], v[10:11], v[14:15]
	v_add_f32_e64 v36, v44, v45
	v_pk_mul_f32 v[34:35], v[10:11], v[10:11]
	v_lshlrev_b32_e64 v42, 16, v32
	v_add_f32_e64 v34, v34, v36
	v_add_f32_e64 v34, v35, v34
	v_and_b32_e32 v43, 0xffff0000, v32
	v_pk_add_f32 v[36:37], v[42:43], -1.0 op_sel_hi:[1,0]
	v_add_f32_dpp v34, v34, v34 quad_perm:[1,0,3,2] row_mask:0xf bank_mask:0xf bound_ctrl:1
	v_pk_fma_f32 v[4:5], v[4:5], v[36:37], 1.0 op_sel_hi:[1,1,0]
	v_lshlrev_b32_e64 v32, 16, v33
	v_add_f32_dpp v34, v34, v34 quad_perm:[2,3,0,1] row_mask:0xf bank_mask:0xf bound_ctrl:1
	v_pk_mul_f32 v[4:5], v[4:5], v[12:13]
	v_and_b32_e32 v33, 0xffff0000, v33
	v_add_f32_dpp v34, v34, v34 row_half_mirror row_mask:0xf bank_mask:0xf bound_ctrl:1
	v_lshlrev_b32_e64 v38, 16, v40
	v_and_b32_e32 v39, 0xffff0000, v40
	v_add_f32_dpp v34, v34, v34 row_mirror row_mask:0xf bank_mask:0xf bound_ctrl:1
	v_sqrt_f32_e64 v44, v34
	v_pk_add_f32 v[34:35], v[32:33], -1.0 op_sel_hi:[1,0]
	v_lshlrev_b32_e64 v40, 16, v41
	v_pk_fma_f32 v[6:7], v[6:7], v[34:35], 1.0 op_sel_hi:[1,1,0]
	v_xor_b32_e32 v12, 0x80000000, v44
	v_min_f32_e32 v12, 0xab8cbccc, v12
	v_rcp_f32_e64 v12, v12
	v_pk_mul_f32 v[6:7], v[6:7], v[14:15]
	v_and_b32_e32 v41, 0xffff0000, v41
	ds_write_b128 v27, v[20:23] offset:24576
	ds_write_b128 v27, v[38:41] offset:24832
	ds_write_b128 v27, v[4:7] offset:25088
	v_pk_mul_f32 v[6:7], v[10:11], v[12:13] op_sel_hi:[1,0]
	v_pk_mul_f32 v[4:5], v[8:9], v[12:13] op_sel_hi:[1,0]
	ds_write_b128 v27, v[4:7] offset:25344
	v_pk_mul_f32 v[6:7], v[6:7], v[32:33] neg_lo:[1,0] neg_hi:[1,0]
	v_pk_mul_f32 v[4:5], v[4:5], v[42:43] neg_lo:[1,0] neg_hi:[1,0]
	ds_write_b128 v27, v[4:7] offset:25600
	ds_write_b128 v27, v[16:19] offset:25856
	.p2alignl 3, 3212836864
.LBB0_683:
	s_or_b64 exec, exec, s[8:9]
	s_waitcnt lgkmcnt(0)
	s_barrier
	s_and_saveexec_b64 s[40:41], vcc
	s_cbranch_execz .LBB0_687
	s_nop 0
	v_lshl_add_u32 v27, v70, 2, 0
	s_waitcnt vmcnt(0)
	s_nop 0
	ds_read_b128 v[4:7], v27
	ds_read_b128 v[8:11], v27 offset:256
	ds_read_b128 v[14:17], v27 offset:512
	ds_read_b128 v[18:21], v27 offset:768
	v_or3_b32 v12, v71, s42, v69
	v_lshl_add_u32 v13, v12, 2, 0
	v_add_u32_e32 v22, 0x100, v13
	ds_read2st64_b64 v[32:35], v22 offset0:2 offset1:5
	ds_read_b128 v[36:39], v27 offset:1024
	ds_read_b128 v[40:43], v27 offset:1536
	ds_read_b128 v[44:47], v27 offset:1792
	ds_read_b128 v[48:51], v27 offset:2048
	ds_read_b128 v[52:55], v27 offset:2304
	ds_read_b128 v[56:59], v27 offset:2560
	s_waitcnt lgkmcnt(7)
	s_nop 0
	v_pk_mul_f32 v[22:23], v[0:1], v[18:19] op_sel:[0,1]
	v_pk_fma_f32 v[0:1], v[0:1], v[8:9], v[0:1] op_sel:[0,1,0] neg_lo:[1,0,0] neg_hi:[1,0,0]
	v_pk_fma_f32 v[18:19], v[28:29], v[18:19], v[22:23] op_sel_hi:[1,0,1]
	v_mov_b32_e64 v22, v21
	v_pk_mul_f32 v[22:23], v[2:3], v[22:23] op_sel_hi:[1,0]
	v_cmp_gt_u32_e64 s[8:9], 4, v68
	v_pk_fma_f32 v[20:21], v[30:31], v[20:21], v[22:23] op_sel_hi:[1,0,1]
	s_nop 0
	s_nop 0
	v_pk_add_f32 v[18:19], v[18:19], v[20:21]
	v_mov_b32_e64 v20, v25
	v_mov_b32_e64 v21, v25
	s_nop 1
	s_nop 0
	v_add_f32_dpp v18, v18, v18 quad_perm:[1,0,3,2] row_mask:0xf bank_mask:0xf bound_ctrl:1
	v_add_f32_dpp v19, v19, v19 quad_perm:[1,0,3,2] row_mask:0xf bank_mask:0xf bound_ctrl:1
	v_add_f32_dpp v20, v20, v20 quad_perm:[1,0,3,2] row_mask:0xf bank_mask:0xf bound_ctrl:1
	v_add_f32_dpp v21, v21, v21 quad_perm:[1,0,3,2] row_mask:0xf bank_mask:0xf bound_ctrl:1
	s_nop 0

; #define ROW16_SUM4(x, y, z, w) do { DPP4(x, y, z, w, "quad_perm:[1,0,3,2]", "s_nop 1"); DPP4(x, y, z, w, "quad_perm:[2,3,0,1]", ""); DPP4(x, y, z, w, "row_half_mirror", ""); DPP4(x, y, z, w, "row_mirror", ""); } while (0)
; template <bool SAMPLE>
; __device__ __forceinline__ void rwkv_unit(PR P, LAS float* lds, const int b, const int h, const int half, const int wv) {
;     ...
;                     float sx = sa.x, sy = sa.y; ROW16_SUM4(sx, sy, py0, py1); sa = (f32x2){sx, sy};
	s_nop 0
	v_add_f32_dpp v18, v18, v18 quad_perm:[2,3,0,1] row_mask:0xf bank_mask:0xf bound_ctrl:1
	v_add_f32_dpp v19, v19, v19 quad_perm:[2,3,0,1] row_mask:0xf bank_mask:0xf bound_ctrl:1
	v_add_f32_dpp v20, v20, v20 quad_perm:[2,3,0,1] row_mask:0xf bank_mask:0xf bound_ctrl:1
	v_add_f32_dpp v21, v21, v21 quad_perm:[2,3,0,1] row_mask:0xf bank_mask:0xf bound_ctrl:1
	s_nop 0

; #define ROW16_SUM4(x, y, z, w) do { DPP4(x, y, z, w, "quad_perm:[1,0,3,2]", "s_nop 1"); DPP4(x, y, z, w, "quad_perm:[2,3,0,1]", ""); DPP4(x, y, z, w, "row_half_mirror", ""); DPP4(x, y, z, w, "row_mirror", ""); } while (0)
; template <bool SAMPLE>
; __device__ __forceinline__ void rwkv_unit(PR P, LAS float* lds, const int b, const int h, const int half, const int wv) {
;     ...
;                     float sx = sa.x, sy = sa.y; ROW16_SUM4(sx, sy, py0, py1); sa = (f32x2){sx, sy};
	s_nop 0
	v_add_f32_dpp v18, v18, v18 row_half_mirror row_mask:0xf bank_mask:0xf bound_ctrl:1
	v_add_f32_dpp v19, v19, v19 row_half_mirror row_mask:0xf bank_mask:0xf bound_ctrl:1
	v_add_f32_dpp v20, v20, v20 row_half_mirror row_mask:0xf bank_mask:0xf bound_ctrl:1
	v_add_f32_dpp v21, v21, v21 row_half_mirror row_mask:0xf bank_mask:0xf bound_ctrl:1
	s_nop 0

; #define ROW16_SUM4(x, y, z, w) do { DPP4(x, y, z, w, "quad_perm:[1,0,3,2]", "s_nop 1"); DPP4(x, y, z, w, "quad_perm:[2,3,0,1]", ""); DPP4(x, y, z, w, "row_half_mirror", ""); DPP4(x, y, z, w, "row_mirror", ""); } while (0)
; template <bool SAMPLE>
; __device__ __forceinline__ void rwkv_unit(PR P, LAS float* lds, const int b, const int h, const int half, const int wv) {
;     ...
;                     float sx = sa.x, sy = sa.y; ROW16_SUM4(sx, sy, py0, py1); sa = (f32x2){sx, sy};
;                     if (tt > 0) { yk0 = cgl == tt - 1 ? py0 : yk0; yk1 = cgl == tt - 1 ? py1 : yk1; }
; #pragma unroll
;                     for (int c = 0; c < 4; ++c) { f32x2 t = S[c] - S[c] * o4[c]; t = t + sa * b4[c]; S[c] = t + v2 * k4[c]; }
;                     const f32x2 y = (S[0] * r4[0] + S[1] * r4[1]) + (S[2] * r4[2] + S[3] * r4[3]);
;                     py0 = y.x; py1 = y.y;
;                     r4 = nr4; o4 = no4; k4 = nk4; a4 = na4; b4 = nb4; v2 = nv2;
	s_nop 0
	v_add_f32_dpp v18, v18, v18 row_mirror row_mask:0xf bank_mask:0xf bound_ctrl:1
	v_add_f32_dpp v19, v19, v19 row_mirror row_mask:0xf bank_mask:0xf bound_ctrl:1
	v_add_f32_dpp v20, v20, v20 row_mirror row_mask:0xf bank_mask:0xf bound_ctrl:1
	v_add_f32_dpp v21, v21, v21 row_mirror row_mask:0xf bank_mask:0xf bound_ctrl:1
	s_nop 0
	s_nop 0
	v_pk_fma_f32 v[20:21], v[28:29], v[8:9], v[28:29] op_sel_hi:[1,0,1] neg_lo:[1,0,0] neg_hi:[1,0,0]
	s_waitcnt lgkmcnt(5)
	s_nop 0
	v_pk_fma_f32 v[0:1], v[36:37], v[18:19], v[0:1] op_sel:[1,0,0]
	v_pk_fma_f32 v[20:21], v[36:37], v[18:19], v[20:21] op_sel_hi:[0,1,1]
	v_pk_fma_f32 v[36:37], v[14:15], v[32:33], v[0:1] op_sel:[1,0,0]
	v_pk_fma_f32 v[0:1], v[30:31], v[10:11], v[30:31] op_sel_hi:[1,0,1] neg_lo:[1,0,0] neg_hi:[1,0,0]
	v_pk_fma_f32 v[22:23], v[14:15], v[32:33], v[20:21] op_sel_hi:[0,1,1]
	v_pk_fma_f32 v[0:1], v[38:39], v[18:19], v[0:1] op_sel_hi:[0,1,1]
	v_pk_fma_f32 v[60:61], v[16:17], v[32:33], v[0:1] op_sel_hi:[0,1,1]
	v_mov_b32_e64 v0, v11
	v_pk_fma_f32 v[0:1], v[2:3], v[0:1], v[2:3] op_sel_hi:[1,0,1] neg_lo:[1,0,0] neg_hi:[1,0,0]
	v_mov_b32_e64 v2, v39
	v_pk_fma_f32 v[0:1], v[2:3], v[18:19], v[0:1] op_sel_hi:[0,1,1]
	v_mov_b32_e64 v2, v17
	v_pk_fma_f32 v[32:33], v[2:3], v[32:33], v[0:1] op_sel_hi:[0,1,1]
	v_mov_b32_e64 v2, v7
	v_pk_mul_f32 v[2:3], v[2:3], v[32:33] op_sel_hi:[0,1]
	s_waitcnt lgkmcnt(1)
	s_nop 0
	v_mov_b32_e64 v38, v55
	v_pk_mul_f32 v[0:1], v[4:5], v[36:37] op_sel:[1,0]
	v_pk_fma_f32 v[2:3], v[6:7], v[60:61], v[2:3] op_sel_hi:[0,1,1]
	v_pk_mul_f32 v[6:7], v[52:53], v[36:37] op_sel:[1,0]
	v_pk_mul_f32 v[38:39], v[38:39], v[32:33] op_sel_hi:[0,1]
	v_pk_fma_f32 v[0:1], v[4:5], v[22:23], v[0:1] op_sel_hi:[0,1,1]
	v_pk_fma_f32 v[6:7], v[52:53], v[22:23], v[6:7] op_sel_hi:[0,1,1]
	v_pk_fma_f32 v[38:39], v[54:55], v[60:61], v[38:39] op_sel_hi:[0,1,1]
	v_pk_add_f32 v[4:5], v[0:1], v[2:3]
	v_pk_add_f32 v[6:7], v[6:7], v[38:39]
	ds_read_b128 v[0:3], v27 offset:3328
	ds_read_b128 v[8:11], v27 offset:3584
	ds_read_b128 v[14:17], v27 offset:3840
	ds_read_b128 v[18:21], v27 offset:4096
	ds_read_b128 v[28:31], v27 offset:3072
	ds_read_b64 v[62:63], v13 offset:4352
	s_nop 1
	s_nop 0
	v_add_f32_dpp v6, v6, v6 quad_perm:[1,0,3,2] row_mask:0xf bank_mask:0xf bound_ctrl:1
	v_add_f32_dpp v7, v7, v7 quad_perm:[1,0,3,2] row_mask:0xf bank_mask:0xf bound_ctrl:1
	v_add_f32_dpp v4, v4, v4 quad_perm:[1,0,3,2] row_mask:0xf bank_mask:0xf bound_ctrl:1
	v_add_f32_dpp v5, v5, v5 quad_perm:[1,0,3,2] row_mask:0xf bank_mask:0xf bound_ctrl:1
	v_pk_fma_f32 v[36:37], v[44:45], v[36:37], v[36:37] op_sel:[1,0,0] neg_lo:[1,0,0] neg_hi:[1,0,0]

; #define ROW16_SUM4(x, y, z, w) do { DPP4(x, y, z, w, "quad_perm:[1,0,3,2]", "s_nop 1"); DPP4(x, y, z, w, "quad_perm:[2,3,0,1]", ""); DPP4(x, y, z, w, "row_half_mirror", ""); DPP4(x, y, z, w, "row_mirror", ""); } while (0)
; template <bool SAMPLE>
; __device__ __forceinline__ void rwkv_unit(PR P, LAS float* lds, const int b, const int h, const int half, const int wv) {
;     ...
;                     float sx = sa.x, sy = sa.y; ROW16_SUM4(sx, sy, py0, py1); sa = (f32x2){sx, sy};
	v_add_f32_dpp v6, v6, v6 quad_perm:[2,3,0,1] row_mask:0xf bank_mask:0xf bound_ctrl:1
	v_add_f32_dpp v7, v7, v7 quad_perm:[2,3,0,1] row_mask:0xf bank_mask:0xf bound_ctrl:1
	v_add_f32_dpp v4, v4, v4 quad_perm:[2,3,0,1] row_mask:0xf bank_mask:0xf bound_ctrl:1
	v_add_f32_dpp v5, v5, v5 quad_perm:[2,3,0,1] row_mask:0xf bank_mask:0xf bound_ctrl:1
	v_pk_fma_f32 v[22:23], v[44:45], v[22:23], v[22:23] op_sel_hi:[0,1,1] neg_lo:[1,0,0] neg_hi:[1,0,0]

; #define ROW16_SUM4(x, y, z, w) do { DPP4(x, y, z, w, "quad_perm:[1,0,3,2]", "s_nop 1"); DPP4(x, y, z, w, "quad_perm:[2,3,0,1]", ""); DPP4(x, y, z, w, "row_half_mirror", ""); DPP4(x, y, z, w, "row_mirror", ""); } while (0)
; template <bool SAMPLE>
; __device__ __forceinline__ void rwkv_unit(PR P, LAS float* lds, const int b, const int h, const int half, const int wv) {
;     ...
;                     float sx = sa.x, sy = sa.y; ROW16_SUM4(sx, sy, py0, py1); sa = (f32x2){sx, sy};
	v_add_f32_dpp v6, v6, v6 row_half_mirror row_mask:0xf bank_mask:0xf bound_ctrl:1
	v_add_f32_dpp v7, v7, v7 row_half_mirror row_mask:0xf bank_mask:0xf bound_ctrl:1
	v_add_f32_dpp v4, v4, v4 row_half_mirror row_mask:0xf bank_mask:0xf bound_ctrl:1
	v_add_f32_dpp v5, v5, v5 row_half_mirror row_mask:0xf bank_mask:0xf bound_ctrl:1
	s_nop 0

; #define ROW16_SUM4(x, y, z, w) do { DPP4(x, y, z, w, "quad_perm:[1,0,3,2]", "s_nop 1"); DPP4(x, y, z, w, "quad_perm:[2,3,0,1]", ""); DPP4(x, y, z, w, "row_half_mirror", ""); DPP4(x, y, z, w, "row_mirror", ""); } while (0)
; template <bool SAMPLE>
; __device__ __forceinline__ void rwkv_unit(PR P, LAS float* lds, const int b, const int h, const int half, const int wv) {
;     ...
;                     float sx = sa.x, sy = sa.y; ROW16_SUM4(sx, sy, py0, py1); sa = (f32x2){sx, sy};
;                     if (tt > 0) { yk0 = cgl == tt - 1 ? py0 : yk0; yk1 = cgl == tt - 1 ? py1 : yk1; }
; #pragma unroll
;                     for (int c = 0; c < 4; ++c) { f32x2 t = S[c] - S[c] * o4[c]; t = t + sa * b4[c]; S[c] = t + v2 * k4[c]; }
;                     const f32x2 y = (S[0] * r4[0] + S[1] * r4[1]) + (S[2] * r4[2] + S[3] * r4[3]);
;                     py0 = y.x; py1 = y.y;
;                     r4 = nr4; o4 = no4; k4 = nk4; a4 = na4; b4 = nb4; v2 = nv2;
	s_nop 0
	v_add_f32_dpp v6, v6, v6 row_mirror row_mask:0xf bank_mask:0xf bound_ctrl:1
	v_add_f32_dpp v7, v7, v7 row_mirror row_mask:0xf bank_mask:0xf bound_ctrl:1
	v_add_f32_dpp v4, v4, v4 row_mirror row_mask:0xf bank_mask:0xf bound_ctrl:1
	v_add_f32_dpp v5, v5, v5 row_mirror row_mask:0xf bank_mask:0xf bound_ctrl:1
	s_waitcnt lgkmcnt(6)
	s_nop 0
	v_pk_fma_f32 v[36:37], v[56:57], v[6:7], v[36:37] op_sel:[1,0,0]
	v_pk_fma_f32 v[22:23], v[56:57], v[6:7], v[22:23] op_sel_hi:[0,1,1]
	v_pk_fma_f32 v[52:53], v[48:49], v[34:35], v[36:37] op_sel:[1,0,0]
	v_pk_fma_f32 v[36:37], v[46:47], v[60:61], v[60:61] op_sel_hi:[0,1,1] neg_lo:[1,0,0] neg_hi:[1,0,0]
	v_pk_fma_f32 v[36:37], v[58:59], v[6:7], v[36:37] op_sel_hi:[0,1,1]
	v_pk_fma_f32 v[54:55], v[50:51], v[34:35], v[36:37] op_sel_hi:[0,1,1]
	v_mov_b32_e64 v36, v47
	v_pk_fma_f32 v[32:33], v[36:37], v[32:33], v[32:33] op_sel_hi:[0,1,1] neg_lo:[1,0,0] neg_hi:[1,0,0]
	v_mov_b32_e64 v36, v59
	v_pk_fma_f32 v[22:23], v[48:49], v[34:35], v[22:23] op_sel_hi:[0,1,1]
	v_pk_fma_f32 v[6:7], v[36:37], v[6:7], v[32:33] op_sel_hi:[0,1,1]
	v_mov_b32_e64 v32, v51
	s_waitcnt lgkmcnt(3)
	s_nop 0
	v_pk_mul_f32 v[60:61], v[14:15], v[52:53] op_sel:[1,0]
	v_pk_fma_f32 v[56:57], v[32:33], v[34:35], v[6:7] op_sel_hi:[0,1,1]
	v_mov_b32_e64 v32, v43
	v_pk_fma_f32 v[14:15], v[14:15], v[22:23], v[60:61] op_sel_hi:[0,1,1]
	v_mov_b32_e64 v60, v17
	v_pk_mul_f32 v[6:7], v[40:41], v[52:53] op_sel:[1,0]
	v_pk_mul_f32 v[32:33], v[32:33], v[56:57] op_sel_hi:[0,1]
	v_pk_mul_f32 v[60:61], v[60:61], v[56:57] op_sel_hi:[0,1]
	v_pk_fma_f32 v[6:7], v[40:41], v[22:23], v[6:7] op_sel_hi:[0,1,1]
	v_pk_fma_f32 v[32:33], v[42:43], v[54:55], v[32:33] op_sel_hi:[0,1,1]
	v_pk_fma_f32 v[16:17], v[16:17], v[54:55], v[60:61] op_sel_hi:[0,1,1]
	v_pk_add_f32 v[6:7], v[6:7], v[32:33]
	v_pk_add_f32 v[14:15], v[14:15], v[16:17]
	ds_read_b128 v[32:35], v27 offset:4864
	ds_read_b128 v[36:39], v27 offset:5120
	ds_read_b128 v[40:43], v27 offset:5376
	ds_read_b128 v[44:47], v27 offset:5632
	ds_read_b128 v[48:51], v27 offset:4608
	ds_read_b64 v[58:59], v13 offset:5888
	s_nop 1
	s_nop 0
	v_add_f32_dpp v14, v14, v14 quad_perm:[1,0,3,2] row_mask:0xf bank_mask:0xf bound_ctrl:1
	v_add_f32_dpp v15, v15, v15 quad_perm:[1,0,3,2] row_mask:0xf bank_mask:0xf bound_ctrl:1
	v_add_f32_dpp v6, v6, v6 quad_perm:[1,0,3,2] row_mask:0xf bank_mask:0xf bound_ctrl:1
	v_add_f32_dpp v7, v7, v7 quad_perm:[1,0,3,2] row_mask:0xf bank_mask:0xf bound_ctrl:1
	v_pk_fma_f32 v[16:17], v[0:1], v[22:23], v[22:23] op_sel_hi:[0,1,1] neg_lo:[1,0,0] neg_hi:[1,0,0]

; #define ROW16_SUM4(x, y, z, w) do { DPP4(x, y, z, w, "quad_perm:[1,0,3,2]", "s_nop 1"); DPP4(x, y, z, w, "quad_perm:[2,3,0,1]", ""); DPP4(x, y, z, w, "row_half_mirror", ""); DPP4(x, y, z, w, "row_mirror", ""); } while (0)
; template <bool SAMPLE>
; __device__ __forceinline__ void rwkv_unit(PR P, LAS float* lds, const int b, const int h, const int half, const int wv) {
;     ...
;                     float sx = sa.x, sy = sa.y; ROW16_SUM4(sx, sy, py0, py1); sa = (f32x2){sx, sy};
	v_add_f32_dpp v14, v14, v14 quad_perm:[2,3,0,1] row_mask:0xf bank_mask:0xf bound_ctrl:1
	v_add_f32_dpp v15, v15, v15 quad_perm:[2,3,0,1] row_mask:0xf bank_mask:0xf bound_ctrl:1
	v_add_f32_dpp v6, v6, v6 quad_perm:[2,3,0,1] row_mask:0xf bank_mask:0xf bound_ctrl:1
	v_add_f32_dpp v7, v7, v7 quad_perm:[2,3,0,1] row_mask:0xf bank_mask:0xf bound_ctrl:1
	v_pk_fma_f32 v[0:1], v[0:1], v[52:53], v[52:53] op_sel:[1,0,0] neg_lo:[1,0,0] neg_hi:[1,0,0]

; #define ROW16_SUM4(x, y, z, w) do { DPP4(x, y, z, w, "quad_perm:[1,0,3,2]", "s_nop 1"); DPP4(x, y, z, w, "quad_perm:[2,3,0,1]", ""); DPP4(x, y, z, w, "row_half_mirror", ""); DPP4(x, y, z, w, "row_mirror", ""); } while (0)
; template <bool SAMPLE>
; __device__ __forceinline__ void rwkv_unit(PR P, LAS float* lds, const int b, const int h, const int half, const int wv) {
;     ...
;                     float sx = sa.x, sy = sa.y; ROW16_SUM4(sx, sy, py0, py1); sa = (f32x2){sx, sy};
	v_add_f32_dpp v14, v14, v14 row_half_mirror row_mask:0xf bank_mask:0xf bound_ctrl:1
	v_add_f32_dpp v15, v15, v15 row_half_mirror row_mask:0xf bank_mask:0xf bound_ctrl:1
	v_add_f32_dpp v6, v6, v6 row_half_mirror row_mask:0xf bank_mask:0xf bound_ctrl:1
	v_add_f32_dpp v7, v7, v7 row_half_mirror row_mask:0xf bank_mask:0xf bound_ctrl:1
	s_nop 0

; #define ROW16_SUM4(x, y, z, w) do { DPP4(x, y, z, w, "quad_perm:[1,0,3,2]", "s_nop 1"); DPP4(x, y, z, w, "quad_perm:[2,3,0,1]", ""); DPP4(x, y, z, w, "row_half_mirror", ""); DPP4(x, y, z, w, "row_mirror", ""); } while (0)
; template <bool SAMPLE>
; __device__ __forceinline__ void rwkv_unit(PR P, LAS float* lds, const int b, const int h, const int half, const int wv) {
;     ...
;                     float sx = sa.x, sy = sa.y; ROW16_SUM4(sx, sy, py0, py1); sa = (f32x2){sx, sy};
;                     if (tt > 0) { yk0 = cgl == tt - 1 ? py0 : yk0; yk1 = cgl == tt - 1 ? py1 : yk1; }
; #pragma unroll
;                     for (int c = 0; c < 4; ++c) { f32x2 t = S[c] - S[c] * o4[c]; t = t + sa * b4[c]; S[c] = t + v2 * k4[c]; }
;                     const f32x2 y = (S[0] * r4[0] + S[1] * r4[1]) + (S[2] * r4[2] + S[3] * r4[3]);
;                     py0 = y.x; py1 = y.y;
;                     r4 = nr4; o4 = no4; k4 = nk4; a4 = na4; b4 = nb4; v2 = nv2;
	s_nop 0
	v_add_f32_dpp v14, v14, v14 row_mirror row_mask:0xf bank_mask:0xf bound_ctrl:1
	v_add_f32_dpp v15, v15, v15 row_mirror row_mask:0xf bank_mask:0xf bound_ctrl:1
	v_add_f32_dpp v6, v6, v6 row_mirror row_mask:0xf bank_mask:0xf bound_ctrl:1
	v_add_f32_dpp v7, v7, v7 row_mirror row_mask:0xf bank_mask:0xf bound_ctrl:1
	s_waitcnt lgkmcnt(8)
	s_nop 0
	v_pk_fma_f32 v[16:17], v[18:19], v[14:15], v[16:17] op_sel_hi:[0,1,1]
	v_pk_fma_f32 v[0:1], v[18:19], v[14:15], v[0:1] op_sel:[1,0,0]
	s_waitcnt lgkmcnt(6)
	s_nop 0
	v_pk_fma_f32 v[16:17], v[8:9], v[62:63], v[16:17] op_sel_hi:[0,1,1]
	v_pk_fma_f32 v[0:1], v[8:9], v[62:63], v[0:1] op_sel:[1,0,0]
	v_pk_fma_f32 v[8:9], v[2:3], v[54:55], v[54:55] op_sel_hi:[0,1,1] neg_lo:[1,0,0] neg_hi:[1,0,0]
	v_pk_fma_f32 v[8:9], v[20:21], v[14:15], v[8:9] op_sel_hi:[0,1,1]
	v_mov_b32_e64 v2, v3
	v_pk_fma_f32 v[18:19], v[10:11], v[62:63], v[8:9] op_sel_hi:[0,1,1]
	v_pk_fma_f32 v[2:3], v[2:3], v[56:57], v[56:57] op_sel_hi:[0,1,1] neg_lo:[1,0,0] neg_hi:[1,0,0]
	v_mov_b32_e64 v8, v21
	v_pk_fma_f32 v[2:3], v[8:9], v[14:15], v[2:3] op_sel_hi:[0,1,1]
	v_mov_b32_e64 v8, v11
	v_pk_fma_f32 v[2:3], v[8:9], v[62:63], v[2:3] op_sel_hi:[0,1,1]
	v_mov_b32_e64 v10, v31
	v_pk_mul_f32 v[8:9], v[28:29], v[0:1] op_sel:[1,0]
	v_pk_mul_f32 v[10:11], v[10:11], v[2:3] op_sel_hi:[0,1]
	v_pk_fma_f32 v[8:9], v[28:29], v[16:17], v[8:9] op_sel_hi:[0,1,1]
	v_pk_fma_f32 v[10:11], v[30:31], v[18:19], v[10:11] op_sel_hi:[0,1,1]
	s_waitcnt lgkmcnt(3)
	s_nop 0
	v_mov_b32_e64 v14, v43
	v_pk_add_f32 v[8:9], v[8:9], v[10:11]
	v_pk_mul_f32 v[10:11], v[40:41], v[0:1] op_sel:[1,0]
	v_pk_mul_f32 v[14:15], v[14:15], v[2:3] op_sel_hi:[0,1]
	v_pk_fma_f32 v[10:11], v[40:41], v[16:17], v[10:11] op_sel_hi:[0,1,1]
	v_pk_fma_f32 v[14:15], v[42:43], v[18:19], v[14:15] op_sel_hi:[0,1,1]
	v_pk_add_f32 v[10:11], v[10:11], v[14:15]
	v_pk_fma_f32 v[14:15], v[32:33], v[16:17], v[16:17] op_sel_hi:[0,1,1] neg_lo:[1,0,0] neg_hi:[1,0,0]
	s_nop 1
	s_nop 0
	v_add_f32_dpp v10, v10, v10 quad_perm:[1,0,3,2] row_mask:0xf bank_mask:0xf bound_ctrl:1
	v_add_f32_dpp v11, v11, v11 quad_perm:[1,0,3,2] row_mask:0xf bank_mask:0xf bound_ctrl:1
	v_add_f32_dpp v8, v8, v8 quad_perm:[1,0,3,2] row_mask:0xf bank_mask:0xf bound_ctrl:1
	v_add_f32_dpp v9, v9, v9 quad_perm:[1,0,3,2] row_mask:0xf bank_mask:0xf bound_ctrl:1
	v_pk_fma_f32 v[0:1], v[32:33], v[0:1], v[0:1] op_sel:[1,0,0] neg_lo:[1,0,0] neg_hi:[1,0,0]

; #define ROW16_SUM4(x, y, z, w) do { DPP4(x, y, z, w, "quad_perm:[1,0,3,2]", "s_nop 1"); DPP4(x, y, z, w, "quad_perm:[2,3,0,1]", ""); DPP4(x, y, z, w, "row_half_mirror", ""); DPP4(x, y, z, w, "row_mirror", ""); } while (0)
; template <bool SAMPLE>
; __device__ __forceinline__ void rwkv_unit(PR P, LAS float* lds, const int b, const int h, const int half, const int wv) {
;     ...
;                     float sx = sa.x, sy = sa.y; ROW16_SUM4(sx, sy, py0, py1); sa = (f32x2){sx, sy};
	v_add_f32_dpp v10, v10, v10 quad_perm:[2,3,0,1] row_mask:0xf bank_mask:0xf bound_ctrl:1
	v_add_f32_dpp v11, v11, v11 quad_perm:[2,3,0,1] row_mask:0xf bank_mask:0xf bound_ctrl:1
	v_add_f32_dpp v8, v8, v8 quad_perm:[2,3,0,1] row_mask:0xf bank_mask:0xf bound_ctrl:1
	v_add_f32_dpp v9, v9, v9 quad_perm:[2,3,0,1] row_mask:0xf bank_mask:0xf bound_ctrl:1
	s_nop 0

; #define ROW16_SUM4(x, y, z, w) do { DPP4(x, y, z, w, "quad_perm:[1,0,3,2]", "s_nop 1"); DPP4(x, y, z, w, "quad_perm:[2,3,0,1]", ""); DPP4(x, y, z, w, "row_half_mirror", ""); DPP4(x, y, z, w, "row_mirror", ""); } while (0)
; template <bool SAMPLE>
; __device__ __forceinline__ void rwkv_unit(PR P, LAS float* lds, const int b, const int h, const int half, const int wv) {
;     ...
;                     float sx = sa.x, sy = sa.y; ROW16_SUM4(sx, sy, py0, py1); sa = (f32x2){sx, sy};
	s_nop 0
	v_add_f32_dpp v10, v10, v10 row_half_mirror row_mask:0xf bank_mask:0xf bound_ctrl:1
	v_add_f32_dpp v11, v11, v11 row_half_mirror row_mask:0xf bank_mask:0xf bound_ctrl:1
	v_add_f32_dpp v8, v8, v8 row_half_mirror row_mask:0xf bank_mask:0xf bound_ctrl:1
	v_add_f32_dpp v9, v9, v9 row_half_mirror row_mask:0xf bank_mask:0xf bound_ctrl:1
	s_nop 0

; __device__ __forceinline__ unsigned cvt_pk_bf16(float lo, float hi) { const f32x2_t v = {lo, hi}; const bf16x2_t b = __builtin_convertvector(v, bf16x2_t); return __builtin_bit_cast(unsigned, b); }
; #define ROW16_SUM4(x, y, z, w) do { DPP4(x, y, z, w, "quad_perm:[1,0,3,2]", "s_nop 1"); DPP4(x, y, z, w, "quad_perm:[2,3,0,1]", ""); DPP4(x, y, z, w, "row_half_mirror", ""); DPP4(x, y, z, w, "row_mirror", ""); } while (0)
; #define ROW16_SUM2(x, y) do { DPP2(x, y, "quad_perm:[1,0,3,2]", "s_nop 1"); DPP2(x, y, "quad_perm:[2,3,0,1]", "s_nop 0"); DPP2(x, y, "row_half_mirror", "s_nop 0"); DPP2(x, y, "row_mirror", "s_nop 0"); } while (0)
; template <bool SAMPLE>
; __device__ __forceinline__ void rwkv_unit(PR P, LAS float* lds, const int b, const int h, const int half, const int wv) {
;     ...
;                     f32x2 sa = (S[0] * a4[0] + S[1] * a4[1]) + (S[2] * a4[2] + S[3] * a4[3]);
;                     float sx = sa.x, sy = sa.y; ROW16_SUM4(sx, sy, py0, py1); sa = (f32x2){sx, sy};
;                     if (tt > 0) { yk0 = cgl == tt - 1 ? py0 : yk0; yk1 = cgl == tt - 1 ? py1 : yk1; }
; #pragma unroll
;                     for (int c = 0; c < 4; ++c) { f32x2 t = S[c] - S[c] * o4[c]; t = t + sa * b4[c]; S[c] = t + v2 * k4[c]; }
;                     const f32x2 y = (S[0] * r4[0] + S[1] * r4[1]) + (S[2] * r4[2] + S[3] * r4[3]);
;                     py0 = y.x; py1 = y.y;
;                     r4 = nr4; o4 = no4; k4 = nk4; a4 = na4; b4 = nb4; v2 = nv2;
;                 }
;                 ROW16_SUM2(py0, py1); yk0 = cgl == GS - 1 ? py0 : yk0; yk1 = cgl == GS - 1 ? py1 : yk1;
;                 if (cgl < GS) *(unsigned*)(YS + (size_t)(row_base + c * TC + g * GS + cgl) * 512 + h * 64 + row0) = pg8::cvt_pk_bf16(yk0, yk1);
;     ...
;         __syncthreads();
;     }
;     if (wid < 4) { *(float4*)sout = make_float4(S[0].x, S[1].x, S[2].x, S[3].x); *(float4*)(sout + 64) = make_float4(S[0].y, S[1].y, S[2].y, S[3].y); }
	s_nop 0
	v_add_f32_dpp v10, v10, v10 row_mirror row_mask:0xf bank_mask:0xf bound_ctrl:1
	v_add_f32_dpp v11, v11, v11 row_mirror row_mask:0xf bank_mask:0xf bound_ctrl:1
	v_add_f32_dpp v8, v8, v8 row_mirror row_mask:0xf bank_mask:0xf bound_ctrl:1
	v_add_f32_dpp v9, v9, v9 row_mirror row_mask:0xf bank_mask:0xf bound_ctrl:1
	s_waitcnt lgkmcnt(2)
	s_nop 0
	v_pk_fma_f32 v[14:15], v[44:45], v[10:11], v[14:15] op_sel_hi:[0,1,1]
	s_waitcnt lgkmcnt(0)
	s_nop 0
	v_pk_fma_f32 v[28:29], v[36:37], v[58:59], v[14:15] op_sel_hi:[0,1,1]
	v_pk_fma_f32 v[14:15], v[34:35], v[18:19], v[18:19] op_sel_hi:[0,1,1] neg_lo:[1,0,0] neg_hi:[1,0,0]
	v_pk_fma_f32 v[14:15], v[46:47], v[10:11], v[14:15] op_sel_hi:[0,1,1]
	v_pk_fma_f32 v[30:31], v[38:39], v[58:59], v[14:15] op_sel_hi:[0,1,1]
	v_mov_b32_e64 v14, v35
	v_pk_fma_f32 v[2:3], v[14:15], v[2:3], v[2:3] op_sel_hi:[0,1,1] neg_lo:[1,0,0] neg_hi:[1,0,0]
	v_mov_b32_e64 v14, v47
	v_pk_fma_f32 v[0:1], v[44:45], v[10:11], v[0:1] op_sel:[1,0,0]
	v_pk_fma_f32 v[2:3], v[14:15], v[10:11], v[2:3] op_sel_hi:[0,1,1]
	v_mov_b32_e64 v10, v39
	v_pk_fma_f32 v[0:1], v[36:37], v[58:59], v[0:1] op_sel:[1,0,0]
	v_pk_fma_f32 v[2:3], v[10:11], v[58:59], v[2:3] op_sel_hi:[0,1,1]
	v_mov_b32_e64 v14, v51
	v_pk_mul_f32 v[10:11], v[48:49], v[0:1] op_sel:[1,0]
	v_pk_mul_f32 v[14:15], v[14:15], v[2:3] op_sel_hi:[0,1]
	v_pk_fma_f32 v[10:11], v[48:49], v[28:29], v[10:11] op_sel_hi:[0,1,1]
	v_pk_fma_f32 v[14:15], v[50:51], v[30:31], v[14:15] op_sel_hi:[0,1,1]
	v_pk_add_f32 v[10:11], v[10:11], v[14:15]
	s_nop 0
	s_nop 1
	v_add_f32_dpp v10, v10, v10 quad_perm:[1,0,3,2] row_mask:0xf bank_mask:0xf bound_ctrl:1
	v_add_f32_dpp v11, v11, v11 quad_perm:[1,0,3,2] row_mask:0xf bank_mask:0xf bound_ctrl:1
	s_nop 0
	s_nop 0
	v_add_f32_dpp v10, v10, v10 quad_perm:[2,3,0,1] row_mask:0xf bank_mask:0xf bound_ctrl:1
	v_add_f32_dpp v11, v11, v11 quad_perm:[2,3,0,1] row_mask:0xf bank_mask:0xf bound_ctrl:1
	s_nop 0
	s_nop 0
	v_add_f32_dpp v10, v10, v10 row_half_mirror row_mask:0xf bank_mask:0xf bound_ctrl:1
	v_add_f32_dpp v11, v11, v11 row_half_mirror row_mask:0xf bank_mask:0xf bound_ctrl:1
	s_nop 0
	s_nop 0
	v_add_f32_dpp v10, v10, v10 row_mirror row_mask:0xf bank_mask:0xf bound_ctrl:1
	v_add_f32_dpp v11, v11, v11 row_mirror row_mask:0xf bank_mask:0xf bound_ctrl:1
	s_and_saveexec_b64 s[42:43], s[8:9]
	s_cbranch_execz .LBB0_686
	v_cmp_eq_u32_e64 s[8:9], 0, v68
	v_add_u32_e64 v13, s56, v68
	v_cmp_eq_u32_e64 s[10:11], 1, v68
	v_cndmask_b32_e64 v5, 0, v5, s[8:9]
	v_cndmask_b32_e64 v4, 0, v4, s[8:9]
	v_lshl_add_u32 v14, v13, 9, v81
	v_mov_b32_e64 v15, v25
	v_cndmask_b32_e64 v5, v5, v7, s[10:11]
	v_cmp_eq_u32_e64 s[12:13], 2, v68
	v_cndmask_b32_e64 v4, v4, v6, s[10:11]
	v_lshl_add_u64 v[14:15], v[14:15], 1, s[24:25]
	s_lshl_b32 s28, s28, 1
	s_nop 0
	v_cndmask_b32_e64 v5, v5, v9, s[12:13]
	v_cndmask_b32_e64 v4, v4, v8, s[12:13]
	v_cmp_eq_u32_e64 s[8:9], 3, v68
	v_lshl_add_u64 v[14:15], v[14:15], 0, s[28:29]
	v_lshlrev_b32_e64 v12, 1, v12
	v_mov_b32_e64 v13, v25
	v_cndmask_b32_e64 v5, v5, v11, s[8:9]
	v_cndmask_b32_e64 v4, v4, v10, s[8:9]
	v_lshl_add_u64 v[12:13], v[14:15], 0, v[12:13]
	v_cvt_pk_bf16_f32 v4, v4, v5
	global_store_dword v[12:13], v4, off
	.p2alignl 3, 3212836864
.LBB0_686:
	s_or_b64 exec, exec, s[42:43]
	.p2alignl 3, 3212836864
.LBB0_687:
	s_or_b64 exec, exec, s[40:41]
	s_barrier
	s_and_saveexec_b64 s[8:9], vcc
	s_cbranch_execz .LBB0_657
	s_waitcnt vmcnt(0)
	s_nop 0
	v_lshl_add_u64 v[4:5], v[24:25], 2, s[26:27]
	v_mov_b32_e64 v27, v25
	v_lshl_add_u64 v[8:9], v[4:5], 0, v[26:27]
	v_mov_b32_e64 v4, v28
	v_mov_b32_e64 v5, v0
	v_mov_b32_e64 v6, v30
	v_mov_b32_e64 v7, v2
	v_mov_b32_e64 v0, v29
	v_mov_b32_e64 v2, v31
	global_store_dwordx4 v[8:9], v[4:7], off
	global_store_dwordx4 v[8:9], v[0:3], off offset:256
	s_branch .LBB0_657
